# lru pass1/pass2 item heads: three masked conv-history loads issued back-to-back and overlapped with the main loads (single counted wait)
# speedup vs baseline: 1.1783x; 1.0023x over previous
; DI float bf2f(u16 v) { return (float)__builtin_bit_cast(_Float16, v); }
; DI u16 f2bf(float x) { return (u16)(pk2(x, 0.f) & 0xffffu); }
; DI int TID() { int t = threadIdx.x; asm volatile("" : "+v"(t)); return t; }
;   const int n = item & 7, chunk = (item >> 3) & 63, b = item >> 9;
;   u16* X = (u16*)lds;
;   u16* Wa = X + 64 * 72;
;   u16* Wx = Wa + 64 * 72;
;   float* preA = (float*)(lds + 3 * 64 * 72 * 2);
;   float* preX = preA + 64 * 64;
;   float* segP = preX + 64 * 64;
;   float* segH = segP + 256;
;   float* carA = segH + 256;
;   float* carB = carA + 256;
;   const int tid = TID(), ch = tid & 63, tq = tid >> 6;
;   const int chg = n * 64 + ch;
;   const int t0 = chunk * 64 + tq * 16;
;   const u16* zb = p.z + (size_t)b * S_ * ZS + XB + chg;
;   const float* cw = p.conv_w + l * 4 * 512;
;   const float w0 = cw[chg], w1 = cw[512 + chg], w2 = cw[1024 + chg], w3 = cw[1536 + chg];
;   const float cb = p.conv_b[l * 512 + chg];
;   float xm3 = (t0 >= 3) ? bf2f(zb[(size_t)(t0 - 3) * ZS]) : 0.f;
;   float xm2 = (t0 >= 2) ? bf2f(zb[(size_t)(t0 - 2) * ZS]) : 0.f;
;   float xm1 = (t0 >= 1) ? bf2f(zb[(size_t)(t0 - 1) * ZS]) : 0.f;
;   float xc[16];
; #pragma unroll
;   for (int i = 0; i < 16; ++i) {
;     const float cur = bf2f(zb[(size_t)(t0 + i) * ZS]);
;     xc[i] = cb + w0 * xm3 + w1 * xm2 + w2 * xm1 + w3 * cur;
;     xm3 = xm2; xm2 = xm1; xm1 = cur;
;     X[(tq * 16 + i) * 72 + ch] = f2bf(xc[i]);
;   }
.LBB0_340:
	s_sub_i32 s0, s12, 32
	s_lshr_b32 s9, s0, 9
	v_mov_b32_e32 v34, v209
	v_readlane_b32 s80, v253, 12
	s_and_b32 s10, s12, 7
	s_bfe_u32 s8, s0, 0x60003
	s_mul_i32 s0, s9, 0x3300000
	v_and_b32_e32 v71, 63, v34
	v_readlane_b32 s86, v253, 18
	s_waitcnt vmcnt(31)
	v_lshl_or_b32 v36, s10, 6, v71
	s_mul_hi_u32 s1, s9, 0x3300000
	v_readlane_b32 s87, v253, 19
	s_add_u32 s0, s86, s0
	s_addc_u32 s1, s87, s1
	v_lshlrev_b32_e32 v0, 1, v36
	v_lshl_add_u64 v[2:3], s[0:1], 0, v[0:1]
	v_readlane_b32 s0, v254, 11
	v_lshlrev_b32_e32 v0, 2, v36
	v_readlane_b32 s1, v254, 12
	s_nop 4
	global_load_dword v6, v0, s[0:1]
	global_load_dword v7, v0, s[0:1] offset:2048
	v_lshl_add_u64 v[4:5], s[0:1], 0, v[0:1]
	v_add_co_u32_e32 v4, vcc, 0x1000, v4
	v_readlane_b32 s0, v254, 9
	v_readlane_b32 s36, v251, 2
	v_addc_co_u32_e32 v5, vcc, 0, v5, vcc
	v_or_b32_e32 v0, s0, v36
	v_readlane_b32 s50, v251, 16
	v_readlane_b32 s51, v251, 17
	global_load_dword v8, v[4:5], off
	global_load_dword v38, v[4:5], off offset:2048
	v_lshl_add_u64 v[4:5], v[0:1], 2, s[50:51]
	global_load_dword v9, v[4:5], off
	v_ashrrev_i32_e32 v37, 6, v34
	v_lshlrev_b32_e32 v72, 4, v37
	v_lshl_add_u32 v10, s8, 6, v72
	v_readlane_b32 s1, v254, 10
	v_lshl_add_u64 v[2:3], v[2:3], 0, s[34:35]
	v_cmp_lt_i32_e32 vcc, 2, v10
	v_mov_b32_e32 v4, 0
	v_mov_b32_e32 v5, 0
	v_readlane_b32 s81, v253, 13
	v_readlane_b32 s82, v253, 14
	v_readlane_b32 s83, v253, 15
	v_readlane_b32 s84, v253, 16
	v_readlane_b32 s85, v253, 17
	v_readlane_b32 s88, v253, 20
	v_readlane_b32 s89, v253, 21
	v_readlane_b32 s90, v253, 22
	v_readlane_b32 s91, v253, 23
	v_readlane_b32 s92, v253, 24
	v_readlane_b32 s93, v253, 25
	v_readlane_b32 s94, v253, 26
	v_readlane_b32 s95, v253, 27
	v_readlane_b32 s37, v251, 3
	v_readlane_b32 s38, v251, 4
	v_readlane_b32 s39, v251, 5
	v_readlane_b32 s40, v251, 6
	v_readlane_b32 s41, v251, 7
	v_readlane_b32 s42, v251, 8
	v_readlane_b32 s43, v251, 9
	v_readlane_b32 s44, v251, 10
	v_readlane_b32 s45, v251, 11
	v_readlane_b32 s46, v251, 12
	v_readlane_b32 s47, v251, 13
	v_readlane_b32 s48, v251, 14
	v_readlane_b32 s49, v251, 15
	s_and_saveexec_b64 s[0:1], vcc
	s_cbranch_execz .LBB0_342
	v_add_u32_e32 v5, -3, v10
	v_mad_u64_u32 v[12:13], s[14:15], v5, s75, v[2:3]
	global_load_ushort v5, v[12:13], off
.LBB0_342:
	s_or_b64 exec, exec, s[0:1]
	v_cmp_lt_i32_e32 vcc, 1, v10
	s_and_saveexec_b64 s[0:1], vcc
	s_cbranch_execz .LBB0_344
	v_add_u32_e32 v4, -2, v10
	v_mad_u64_u32 v[12:13], s[14:15], v4, s75, v[2:3]
	global_load_ushort v4, v[12:13], off
.LBB0_344:
	s_or_b64 exec, exec, s[0:1]
	v_cmp_lt_i32_e32 vcc, 0, v10
	v_mov_b32_e32 v11, 0
	s_and_saveexec_b64 s[0:1], vcc
	s_cbranch_execz .LBB0_346
	v_add_u32_e32 v11, -1, v10
	v_mad_u64_u32 v[12:13], s[14:15], v11, s75, v[2:3]
	global_load_ushort v11, v[12:13], off
.LBB0_346:
	s_or_b64 exec, exec, s[0:1]
	v_mad_i64_i32 v[12:13], s[0:1], v10, s75, v[2:3]
	global_load_ushort v39, v[12:13], off
	v_or_b32_e32 v12, 1, v10
	v_mad_i64_i32 v[12:13], s[0:1], v12, s75, v[2:3]
	global_load_ushort v40, v[12:13], off
	v_or_b32_e32 v12, 2, v10
	v_mad_i64_i32 v[12:13], s[0:1], v12, s75, v[2:3]
	global_load_ushort v41, v[12:13], off
	v_or_b32_e32 v12, 3, v10
	v_mad_i64_i32 v[12:13], s[0:1], v12, s75, v[2:3]
	global_load_ushort v42, v[12:13], off
	v_or_b32_e32 v12, 4, v10
	v_mad_i64_i32 v[12:13], s[0:1], v12, s75, v[2:3]
	global_load_ushort v43, v[12:13], off
	s_movk_i32 s0, 0x900
	v_lshlrev_b32_e32 v12, 1, v71
	s_waitcnt vmcnt(5)
	v_cvt_f32_f16_e32 v5, v5
	v_cvt_f32_f16_e32 v4, v4
	v_cvt_f32_f16_e32 v11, v11
	v_fma_f32 v44, v6, v5, v9
	v_mul_lo_u32 v5, v37, s0
	v_or_b32_e32 v13, 5, v10
	v_fma_f32 v24, v6, v4, v9
	v_fmac_f32_e32 v44, v7, v4
	v_or_b32_e32 v27, v12, v5
	v_mad_i64_i32 v[4:5], s[0:1], v13, s75, v[2:3]
	global_load_ushort v45, v[4:5], off
	v_or_b32_e32 v74, 1, v72
	v_or_b32_e32 v14, 6, v10
	v_mad_u64_u32 v[4:5], s[0:1], v74, s76, v[12:13]
	v_mad_i64_i32 v[12:13], s[0:1], v14, s75, v[2:3]
	global_load_ushort v49, v[12:13], off
	v_or_b32_e32 v15, 7, v10
	v_or_b32_e32 v16, 8, v10
	v_or_b32_e32 v17, 9, v10
	v_or_b32_e32 v18, 10, v10
	v_or_b32_e32 v20, 11, v10
	v_or_b32_e32 v22, 12, v10
	v_mad_i64_i32 v[12:13], s[0:1], v15, s75, v[2:3]
	v_mad_i64_i32 v[14:15], s[0:1], v16, s75, v[2:3]
	v_mad_i64_i32 v[16:17], s[0:1], v17, s75, v[2:3]
	v_mad_i64_i32 v[18:19], s[0:1], v18, s75, v[2:3]
	v_mad_i64_i32 v[20:21], s[0:1], v20, s75, v[2:3]
	v_mad_i64_i32 v[22:23], s[0:1], v22, s75, v[2:3]
	global_load_ushort v50, v[12:13], off
	global_load_ushort v51, v[14:15], off
	global_load_ushort v52, v[16:17], off
	global_load_ushort v46, v[18:19], off
	global_load_ushort v47, v[20:21], off
	global_load_ushort v48, v[22:23], off
	v_fma_f32 v25, v6, v11, v9
	v_fmac_f32_e32 v24, v7, v11
	v_fmac_f32_e32 v44, v8, v11
	v_or_b32_e32 v26, 13, v10
	v_ashrrev_i32_e32 v35, 31, v34
	v_ashrrev_i32_e32 v75, 2, v34
	v_lshrrev_b32_e32 v73, 5, v71
	s_movk_i32 s96, 0x2000
	s_movk_i32 s97, 0x3000
	s_waitcnt vmcnt(12)
	v_fma_mixlo_f16 v5, v38, v39, v44 op_sel_hi:[0,1,0]
	v_fma_mix_f32 v53, v8, v39, v24 op_sel_hi:[0,1,0]
	v_fma_mix_f32 v11, v7, v39, v25 op_sel_hi:[0,1,0]
	v_fma_mix_f32 v12, v6, v39, v9 op_sel_hi:[0,1,0]
	ds_write_b16 v27, v5
	s_waitcnt vmcnt(11)
	v_fma_mixlo_f16 v5, v38, v40, v53 op_sel_hi:[0,1,0]
	v_fma_mix_f32 v54, v8, v40, v11 op_sel_hi:[0,1,0]
	v_fma_mix_f32 v11, v7, v40, v12 op_sel_hi:[0,1,0]
	v_fma_mix_f32 v12, v6, v40, v9 op_sel_hi:[0,1,0]
	ds_write_b16 v4, v5
	s_waitcnt vmcnt(10)
	v_fma_mixlo_f16 v5, v38, v41, v54 op_sel_hi:[0,1,0]
	v_fma_mix_f32 v55, v8, v41, v11 op_sel_hi:[0,1,0]
	v_fma_mix_f32 v11, v7, v41, v12 op_sel_hi:[0,1,0]
	v_fma_mix_f32 v13, v6, v41, v9 op_sel_hi:[0,1,0]
	ds_write_b16 v4, v5 offset:144
	s_waitcnt vmcnt(9)
; DI unsigned pk2(float a, float b) { f2_t v = {a, b}; bf2_t r = __builtin_convertvector(v, bf2_t); return __builtin_bit_cast(unsigned, r); }
; DI float bf2f(u16 v) { return (float)__builtin_bit_cast(_Float16, v); }
; DI u16 f2bf(float x) { return (u16)(pk2(x, 0.f) & 0xffffu); }
;     ...
;   float xm3 = (t0 >= 3) ? bf2f(zb[(size_t)(t0 - 3) * ZS]) : 0.f;
;   float xm2 = (t0 >= 2) ? bf2f(zb[(size_t)(t0 - 2) * ZS]) : 0.f;
;   float xm1 = (t0 >= 1) ? bf2f(zb[(size_t)(t0 - 1) * ZS]) : 0.f;
;   float xc[16];
; #pragma unroll
;   for (int i = 0; i < 16; ++i) {
;     const float cur = bf2f(zb[(size_t)(t0 + i) * ZS]);
;     xc[i] = cb + w0 * xm3 + w1 * xm2 + w2 * xm1 + w3 * cur;
;     xm3 = xm2; xm2 = xm1; xm1 = cur;
;     X[(tq * 16 + i) * 72 + ch] = f2bf(xc[i]);
;   }
;   {
;     const float4* ga = (const float4*)(p.w_rg_a + ((size_t)(l * 8 + n) * 64) * 64);
;     const float4* gx = (const float4*)(p.w_rg_x + ((size_t)(l * 8 + n) * 64) * 64);
; #pragma unroll
;     for (int i = 0; i < 4; ++i) {
;       const int idx = tid + 256 * i, d = idx >> 4, e = (idx & 15) * 4;
;       const float4 va = ga[idx], vx = gx[idx];
;       uint2 oa, ox;
;       oa.x = pk2(va.x, va.y); oa.y = pk2(va.z, va.w);
;       ox.x = pk2(vx.x, vx.y); ox.y = pk2(vx.z, vx.w);
;       *(uint2*)(Wa + d * 72 + e) = oa;
;       *(uint2*)(Wx + d * 72 + e) = ox;
;     }
;   }
;   __syncthreads();
	v_fma_mixlo_f16 v5, v38, v42, v55 op_sel_hi:[0,1,0]
	v_fma_mix_f32 v56, v8, v42, v11 op_sel_hi:[0,1,0]
	v_fma_mix_f32 v12, v7, v42, v13 op_sel_hi:[0,1,0]
	ds_write_b16 v4, v5 offset:288
	s_waitcnt vmcnt(8)
	v_fma_mixlo_f16 v5, v38, v43, v56 op_sel_hi:[0,1,0]
	v_fma_mix_f32 v57, v8, v43, v12 op_sel_hi:[0,1,0]
	ds_write_b16 v4, v5 offset:432
	v_mad_i64_i32 v[12:13], s[0:1], v26, s75, v[2:3]
	v_or_b32_e32 v5, 14, v10
	global_load_ushort v58, v[12:13], off
	v_mad_i64_i32 v[12:13], s[0:1], v5, s75, v[2:3]
	v_or_b32_e32 v5, 15, v10
	v_mad_i64_i32 v[2:3], s[0:1], v5, s75, v[2:3]
	s_lshl_b32 s0, s10, 12
	v_readlane_b32 s10, v254, 13
	s_mov_b32 s1, s25
	s_or_b32 s0, s0, s10
	global_load_ushort v59, v[12:13], off
	global_load_ushort v60, v[2:3], off
	s_lshl_b64 s[0:1], s[0:1], 2
	s_add_u32 s10, s60, s0
	s_addc_u32 s11, s61, s1
	s_add_u32 s0, s64, s0
	s_addc_u32 s1, s65, s1
	v_lshlrev_b64 v[2:3], 4, v[34:35]
	v_lshl_add_u64 v[62:63], s[10:11], 0, v[2:3]
	v_lshl_add_u64 v[2:3], s[0:1], 0, v[2:3]
	s_movk_i32 s0, 0x2000
	v_add_co_u32_e32 v26, vcc, s0, v62
	global_load_dwordx4 v[10:13], v[62:63], off
	s_nop 0
	v_addc_co_u32_e32 v27, vcc, 0, v63, vcc
	global_load_dwordx4 v[14:17], v[2:3], off
	v_add_co_u32_e32 v30, vcc, s0, v2
	s_movk_i32 s0, 0x3000
	s_nop 0
	v_addc_co_u32_e32 v31, vcc, 0, v3, vcc
	global_load_dwordx4 v[18:21], v[26:27], off offset:-4096
	global_load_dwordx4 v[22:25], v[30:31], off offset:-4096
	v_add_co_u32_e32 v62, vcc, s0, v62
	s_waitcnt vmcnt(14)
	v_fma_mixlo_f16 v5, v38, v45, v57 op_sel_hi:[0,1,0]
	v_addc_co_u32_e32 v63, vcc, 0, v63, vcc
	ds_write_b16 v4, v5 offset:576
	v_add_co_u32_e32 v2, vcc, s0, v2
	global_load_dwordx4 v[26:29], v[26:27], off
	s_nop 0
	global_load_dwordx4 v[30:33], v[30:31], off
	v_addc_co_u32_e32 v3, vcc, 0, v3, vcc
	global_load_dwordx4 v[76:79], v[62:63], off
	global_load_dwordx4 v[80:83], v[2:3], off
	v_fma_mix_f32 v2, v6, v43, v9 op_sel_hi:[0,1,0]
	v_fma_mix_f32 v2, v7, v45, v2 op_sel_hi:[0,1,0]
	s_waitcnt vmcnt(17)
	v_fma_mix_f32 v62, v8, v49, v2 op_sel_hi:[0,1,0]
	s_waitcnt vmcnt(16)
	v_fma_mixlo_f16 v2, v38, v50, v62 op_sel_hi:[0,1,0]
	ds_write_b16 v4, v2 offset:864
	v_fma_mix_f32 v2, v6, v45, v9 op_sel_hi:[0,1,0]
	v_fma_mix_f32 v2, v7, v49, v2 op_sel_hi:[0,1,0]
	v_fma_mix_f32 v64, v8, v50, v2 op_sel_hi:[0,1,0]
	s_waitcnt vmcnt(15)
	v_fma_mixlo_f16 v2, v38, v51, v64 op_sel_hi:[0,1,0]
	ds_write_b16 v4, v2 offset:1008
	v_fma_mix_f32 v2, v6, v49, v9 op_sel_hi:[0,1,0]
	v_fma_mix_f32 v2, v7, v50, v2 op_sel_hi:[0,1,0]
	v_fma_mix_f32 v66, v8, v51, v2 op_sel_hi:[0,1,0]
	s_waitcnt vmcnt(14)
	v_fma_mixlo_f16 v2, v38, v52, v66 op_sel_hi:[0,1,0]
	ds_write_b16 v4, v2 offset:1152
	v_fma_mix_f32 v2, v6, v50, v9 op_sel_hi:[0,1,0]
	v_fma_mix_f32 v2, v7, v51, v2 op_sel_hi:[0,1,0]
	v_fma_mix_f32 v63, v8, v52, v2 op_sel_hi:[0,1,0]
	s_waitcnt vmcnt(13)
	v_fma_mixlo_f16 v2, v38, v46, v63 op_sel_hi:[0,1,0]
	ds_write_b16 v4, v2 offset:1296
	v_fma_mix_f32 v2, v6, v51, v9 op_sel_hi:[0,1,0]
	v_fma_mix_f32 v2, v7, v52, v2 op_sel_hi:[0,1,0]
	v_fma_mix_f32 v65, v8, v46, v2 op_sel_hi:[0,1,0]
	s_waitcnt vmcnt(12)
	v_fma_mixlo_f16 v2, v38, v47, v65 op_sel_hi:[0,1,0]
	ds_write_b16 v4, v2 offset:1440
	v_fma_mix_f32 v2, v6, v52, v9 op_sel_hi:[0,1,0]
	v_fma_mix_f32 v2, v7, v46, v2 op_sel_hi:[0,1,0]
	v_fma_mix_f32 v67, v8, v47, v2 op_sel_hi:[0,1,0]
	s_waitcnt vmcnt(11)
	v_fma_mixlo_f16 v2, v38, v48, v67 op_sel_hi:[0,1,0]
	ds_write_b16 v4, v2 offset:1584
	v_fma_mix_f32 v2, v6, v46, v9 op_sel_hi:[0,1,0]
	v_fma_mix_f32 v2, v7, v47, v2 op_sel_hi:[0,1,0]
	v_fma_mix_f32 v68, v8, v48, v2 op_sel_hi:[0,1,0]
	s_waitcnt vmcnt(10)
	v_fma_mixlo_f16 v2, v38, v58, v68 op_sel_hi:[0,1,0]
	ds_write_b16 v4, v2 offset:1728
	v_fma_mix_f32 v2, v6, v47, v9 op_sel_hi:[0,1,0]
	v_fma_mix_f32 v2, v7, v48, v2 op_sel_hi:[0,1,0]
	v_fma_mix_f32 v69, v8, v58, v2 op_sel_hi:[0,1,0]
	v_fma_mix_f32 v5, v6, v42, v9 op_sel_hi:[0,1,0]
	v_fma_mix_f32 v5, v7, v43, v5 op_sel_hi:[0,1,0]
	v_fma_mix_f32 v61, v8, v45, v5 op_sel_hi:[0,1,0]
	v_lshrrev_b32_e32 v3, 4, v34
	v_fma_mixlo_f16 v5, v38, v49, v61 op_sel_hi:[0,1,0]
	s_waitcnt vmcnt(9)
	v_fma_mixlo_f16 v2, v38, v59, v69 op_sel_hi:[0,1,0]
	ds_write_b16 v4, v2 offset:1872
	v_fma_mix_f32 v2, v6, v48, v9 op_sel_hi:[0,1,0]
	v_fma_mix_f32 v2, v7, v58, v2 op_sel_hi:[0,1,0]
	v_fma_mix_f32 v70, v8, v59, v2 op_sel_hi:[0,1,0]
	s_waitcnt vmcnt(8)
	v_fma_mixlo_f16 v2, v38, v60, v70 op_sel_hi:[0,1,0]
	ds_write_b16 v4, v2 offset:2016
	v_lshlrev_b32_e32 v2, 3, v34
	v_and_b32_e32 v2, 0x78, v2
	v_mad_u64_u32 v[8:9], s[0:1], v3, s76, v[2:3]
	v_add_u32_e32 v3, 0x100, v34
	ds_write_b16 v4, v5 offset:720
	s_waitcnt vmcnt(7)
	v_cvt_pk_f16_f32 v4, v10, v11
	v_cvt_pk_f16_f32 v5, v12, v13
	v_lshrrev_b32_e32 v3, 4, v3
	s_waitcnt vmcnt(6)
	v_cvt_pk_f16_f32 v6, v14, v15
	v_cvt_pk_f16_f32 v7, v16, v17
	ds_write2st64_b64 v8, v[4:5], v[6:7] offset0:18 offset1:36
	v_mad_u64_u32 v[8:9], s[0:1], v3, s76, v[2:3]
	v_add_u32_e32 v3, 0x200, v34
	s_waitcnt vmcnt(5)
	v_cvt_pk_f16_f32 v4, v18, v19
	v_cvt_pk_f16_f32 v5, v20, v21
	s_waitcnt vmcnt(4)
	v_cvt_pk_f16_f32 v6, v22, v23
	v_cvt_pk_f16_f32 v7, v24, v25
	v_lshrrev_b32_e32 v3, 4, v3
	ds_write2st64_b64 v8, v[4:5], v[6:7] offset0:18 offset1:36
	v_mad_u64_u32 v[8:9], s[0:1], v3, s76, v[2:3]
	v_add_u32_e32 v3, 0x300, v34
	v_lshrrev_b32_e32 v3, 4, v3
	s_waitcnt vmcnt(3)
	v_cvt_pk_f16_f32 v4, v26, v27
	v_cvt_pk_f16_f32 v5, v28, v29
	s_waitcnt vmcnt(2)
	v_cvt_pk_f16_f32 v6, v30, v31
	v_cvt_pk_f16_f32 v7, v32, v33
	v_mad_u64_u32 v[2:3], s[0:1], v3, s76, v[2:3]
	ds_write2st64_b64 v8, v[4:5], v[6:7] offset0:18 offset1:36
	s_waitcnt vmcnt(1)
	v_cvt_pk_f16_f32 v4, v76, v77
	v_cvt_pk_f16_f32 v5, v78, v79
	s_waitcnt vmcnt(0)
	v_cvt_pk_f16_f32 v6, v80, v81
	v_cvt_pk_f16_f32 v7, v82, v83
	s_movk_i32 s0, 0xffe0
	ds_write2st64_b64 v2, v[4:5], v[6:7] offset0:18 offset1:36
	v_bfi_b32 v4, s0, v75, v34
	v_mul_lo_u32 v4, v4, s76
	v_lshl_add_u32 v84, v73, 4, v4
	v_lshlrev_b32_e32 v35, 2, v34
	s_waitcnt lgkmcnt(0)
	s_barrier
; #define MFMA(a, b, c) __builtin_amdgcn_mfma_f32_32x32x16_f16(__builtin_bit_cast(h16x8, (a)), __builtin_bit_cast(h16x8, (b)), (c), 0, 0, 0)
;     ...
;   {
;     const int lane = tid & 63, r = lane & 31, h = lane >> 5, mt = tq >> 1, nt = tq & 1;
;     const int q4 = (lane & 15) >> 2, p4 = lane & 3, blk = (lane >> 4) & 1;
;     f32x16 accA, accX;
; #pragma unroll
;     for (int i = 0; i < 16; ++i) { accA[i] = 0.f; accX[i] = 0.f; }
; #pragma unroll
;     for (int ks = 0; ks < 4; ++ks) {
;       const bf16x8 af = *(const bf16x8*)(X + (mt * 32 + r) * 72 + ks * 16 + 8 * h);
;       const int woff = (ks * 16 + 8 * h + q4) * 72 + nt * 32 + 16 * blk + 4 * p4;
;       const s16x4 alo = __builtin_amdgcn_ds_read_tr16_b64_v4i16((__attribute__((address_space(3))) s16x4*)(Wa + woff));
;       const s16x4 ahi = __builtin_amdgcn_ds_read_tr16_b64_v4i16((__attribute__((address_space(3))) s16x4*)(Wa + woff + 4 * 72));
;       const s16x4 xlo = __builtin_amdgcn_ds_read_tr16_b64_v4i16((__attribute__((address_space(3))) s16x4*)(Wx + woff));
;       const s16x4 xhi = __builtin_amdgcn_ds_read_tr16_b64_v4i16((__attribute__((address_space(3))) s16x4*)(Wx + woff + 4 * 72));
;       const bf16x8 ba_ = __builtin_shufflevector(alo, ahi, 0, 1, 2, 3, 4, 5, 6, 7);
;       const bf16x8 bx_ = __builtin_shufflevector(xlo, xhi, 0, 1, 2, 3, 4, 5, 6, 7);
;       accA = MFMA(af, ba_, accA);
;       accX = MFMA(af, bx_, accX);
;     }
; #pragma unroll
;     for (int i = 0; i < 16; ++i) {
;       const int t = mt * 32 + (i & 3) + 8 * (i >> 2) + 4 * h;
;       preA[t * 64 + nt * 32 + r] = accA[i];
;       preX[t * 64 + nt * 32 + r] = accX[i];
;     }
;   }
;   __syncthreads();
;   float aA[16], aX[16];
; #pragma unroll
;   for (int i = 0; i < 16; ++i) { aA[i] = preA[(tq * 16 + i) * 64 + ch]; aX[i] = preX[(tq * 16 + i) * 64 + ch]; }
;   const float ba = p.b_rg_a[l * 512 + chg], bx = p.b_rg_x[l * 512 + chg], lam = p.lru_lambda[l * 512 + chg];
;   const float sp = fmaxf(-lam, 0.f) + __logf(1.f + __expf(-fabsf(lam)));
;   float P = 1.f, H = 0.f;
; #pragma unroll
;   for (int i = 0; i < 16; ++i) {
;     const float rr = sigmoidf_(aA[i] + ba), ig = sigmoidf_(aX[i] + bx);
;     const float la = -8.f * rr * sp;
;     const float a = __expf(la);
;     const float x2 = 2.f * la;
;     const float em = (x2 > -0.1f) ? -x2 * (1.f + x2 * (0.5f + x2 * (0.16666667f + x2 * 0.041666667f))) : 1.f - __expf(x2);
	v_bfe_u32 v2, v34, 2, 2
	v_lshlrev_b32_e32 v4, 5, v37
	ds_read_b128 v[18:21], v84
	v_and_b32_e32 v3, 16, v34
	v_lshl_or_b32 v2, v73, 3, v2
	v_and_b32_e32 v85, 32, v4
	v_and_b32_e32 v4, 12, v35
	v_or3_b32 v3, v4, v3, v85
	v_mul_u32_u24_e32 v2, 0x48, v2
	v_add_lshl_u32 v86, v2, v3, 1
	ds_read_b64_tr_b16 v[2:3], v86 offset:9216
	ds_read_b64_tr_b16 v[4:5], v86 offset:9792
	s_waitcnt lgkmcnt(0)
	v_mfma_f32_32x32x16_f16 v[2:17], v[18:21], v[2:5], 0
	ds_read_b64_tr_b16 v[22:23], v86 offset:18432
	ds_read_b64_tr_b16 v[24:25], v86 offset:19008
	ds_read_b128 v[76:79], v84 offset:32
	ds_read_b64_tr_b16 v[80:81], v86 offset:11520
	ds_read_b64_tr_b16 v[82:83], v86 offset:12096
	v_and_b32_e32 v75, 0xffffffe0, v75
	v_lshlrev_b32_e32 v75, 6, v75
	v_and_b32_e32 v34, 31, v34
	v_lshl_or_b32 v73, v73, 8, v75
	v_or3_b32 v34, v73, v85, v34
	s_waitcnt lgkmcnt(3)
	v_mfma_f32_32x32x16_f16 v[18:33], v[18:21], v[22:25], 0
	v_lshlrev_b32_e32 v34, 2, v34
	s_mov_b32 s0, 0xbfb8aa3b
	s_waitcnt lgkmcnt(0)
	v_mfma_f32_32x32x16_f16 v[2:17], v[76:79], v[80:83], v[2:17]
	ds_read_b64_tr_b16 v[80:81], v86 offset:20736
	ds_read_b64_tr_b16 v[82:83], v86 offset:21312
	s_waitcnt lgkmcnt(0)
	v_mfma_f32_32x32x16_f16 v[18:33], v[76:79], v[80:83], v[18:33]
	ds_read_b128 v[76:79], v84 offset:64
	ds_read_b64_tr_b16 v[80:81], v86 offset:13824
	ds_read_b64_tr_b16 v[82:83], v86 offset:14400
	s_waitcnt lgkmcnt(0)
	v_mfma_f32_32x32x16_f16 v[2:17], v[76:79], v[80:83], v[2:17]
	ds_read_b64_tr_b16 v[80:81], v86 offset:23040
	ds_read_b64_tr_b16 v[82:83], v86 offset:23616
	s_waitcnt lgkmcnt(0)
	v_mfma_f32_32x32x16_f16 v[18:33], v[76:79], v[80:83], v[18:33]
	ds_read_b128 v[76:79], v84 offset:96
	ds_read_b64_tr_b16 v[80:81], v86 offset:16128
	ds_read_b64_tr_b16 v[82:83], v86 offset:16704
	s_waitcnt lgkmcnt(0)
	v_mfma_f32_32x32x16_f16 v[2:17], v[76:79], v[80:83], v[2:17]
	ds_read_b64_tr_b16 v[80:81], v86 offset:25344
	ds_read_b64_tr_b16 v[82:83], v86 offset:25920
	s_waitcnt lgkmcnt(0)
	v_mfma_f32_32x32x16_f16 v[18:33], v[76:79], v[80:83], v[18:33]
	s_nop 7
	ds_write2st64_b32 v34, v2, v3 offset0:108 offset1:109
	s_nop 2
	ds_write2st64_b32 v34, v18, v19 offset0:172 offset1:173
	ds_write2st64_b32 v34, v4, v5 offset0:110 offset1:111
	ds_write2st64_b32 v34, v20, v21 offset0:174 offset1:175
	ds_write2st64_b32 v34, v6, v7 offset0:116 offset1:117
	ds_write2st64_b32 v34, v22, v23 offset0:180 offset1:181
	ds_write2st64_b32 v34, v8, v9 offset0:118 offset1:119
	ds_write2st64_b32 v34, v24, v25 offset0:182 offset1:183
	ds_write2st64_b32 v34, v10, v11 offset0:124 offset1:125
	ds_write2st64_b32 v34, v26, v27 offset0:188 offset1:189
	ds_write2st64_b32 v34, v12, v13 offset0:126 offset1:127
	ds_write2st64_b32 v34, v28, v29 offset0:190 offset1:191
	ds_write2st64_b32 v34, v14, v15 offset0:132 offset1:133
	ds_write2st64_b32 v34, v30, v31 offset0:196 offset1:197
	ds_write2st64_b32 v34, v16, v17 offset0:134 offset1:135
	ds_write2st64_b32 v34, v32, v33 offset0:198 offset1:199
	v_lshlrev_b64 v[2:3], 2, v[0:1]
	v_lshl_add_u64 v[4:5], s[68:69], 0, v[2:3]
	s_waitcnt lgkmcnt(0)
	s_barrier
	global_load_dword v75, v[4:5], off
	v_lshl_add_u64 v[4:5], s[62:63], 0, v[2:3]
	global_load_dword v73, v[4:5], off
	v_lshl_add_u64 v[2:3], s[66:67], 0, v[2:3]
	global_load_dword v34, v[2:3], off
	v_lshlrev_b32_e32 v0, 2, v71
	v_lshl_or_b32 v2, v37, 12, v0
	ds_read2st64_b32 v[32:33], v2 offset0:108 offset1:172
	v_lshl_or_b32 v2, v74, 8, v0
	ds_read2st64_b32 v[30:31], v2 offset0:108 offset1:172
	v_lshl_or_b32 v2, v72, 8, v0
	v_or_b32_e32 v3, 0x200, v2
	ds_read2st64_b32 v[28:29], v3 offset0:108 offset1:172
	v_or_b32_e32 v3, 0x300, v2
	ds_read2st64_b32 v[26:27], v3 offset0:108 offset1:172
	v_or_b32_e32 v3, 0x400, v2
	ds_read2st64_b32 v[24:25], v3 offset0:108 offset1:172
	v_or_b32_e32 v3, 0x500, v2
	ds_read2st64_b32 v[22:23], v3 offset0:108 offset1:172
	v_or_b32_e32 v3, 0x600, v2
	ds_read2st64_b32 v[20:21], v3 offset0:108 offset1:172
	v_or_b32_e32 v3, 0x700, v2
	ds_read2st64_b32 v[18:19], v3 offset0:108 offset1:172
	v_or_b32_e32 v3, 0x800, v2
	ds_read2st64_b32 v[16:17], v3 offset0:108 offset1:172
	v_or_b32_e32 v3, 0x900, v2
	ds_read2st64_b32 v[14:15], v3 offset0:108 offset1:172
	v_or_b32_e32 v3, 0xa00, v2
	ds_read2st64_b32 v[12:13], v3 offset0:108 offset1:172
	v_or_b32_e32 v3, 0xb00, v2
	ds_read2st64_b32 v[10:11], v3 offset0:108 offset1:172
	v_or_b32_e32 v3, 0xc00, v2
	ds_read2st64_b32 v[8:9], v3 offset0:108 offset1:172
	v_or_b32_e32 v3, 0xd00, v2
	ds_read2st64_b32 v[6:7], v3 offset0:108 offset1:172
	v_mov_b32_e32 v76, 0x41b17218
	v_or_b32_e32 v4, 0xe00, v2
	v_or_b32_e32 v2, 0xf00, v2
	ds_read2st64_b32 v[4:5], v4 offset0:108 offset1:172
	s_waitcnt vmcnt(2)
	v_mul_f32_e64 v3, |v75|, s0
	v_exp_f32_e32 v3, v3
	s_waitcnt vmcnt(1) lgkmcnt(14)
	v_add_f32_e32 v32, v32, v73
	v_mul_f32_e32 v32, 0xbfb8aa3b, v32
	v_exp_f32_e32 v32, v32
	v_add_f32_e32 v3, 1.0, v3
	v_cmp_gt_f32_e32 vcc, s56, v3
	s_mov_b32 s0, 0x3f317217
	v_add_f32_e32 v32, 1.0, v32
	v_cndmask_b32_e64 v71, 0, 32, vcc
	v_ldexp_f32 v3, v3, v71
	v_log_f32_e32 v71, v3
	v_max_f32_e64 v72, -v75, -v75
	v_cndmask_b32_e32 v76, 0, v76, vcc
	v_max_f32_e32 v72, 0, v72
	v_mul_f32_e32 v74, 0x3f317217, v71
	v_fma_f32 v74, v71, s0, -v74
	v_fmac_f32_e32 v74, 0x3377d1cf, v71
	s_mov_b32 s0, 0x7f800000
	v_fmac_f32_e32 v74, 0x3f317217, v71
	v_cmp_lt_f32_e64 s[0:1], |v71|, s0
	ds_read2st64_b32 v[2:3], v2 offset0:108 offset1:172
	s_nop 0
	v_cndmask_b32_e64 v71, v71, v74, s[0:1]
	v_div_scale_f32 v74, s[0:1], v32, v32, 1.0
	v_rcp_f32_e32 v75, v74
	v_sub_f32_e32 v71, v71, v76
	v_add_f32_e32 v84, v72, v71
	s_mov_b32 s0, 0xbdcccccd
	v_fma_f32 v71, -v74, v75, 1.0
	v_fmac_f32_e32 v75, v71, v75
	v_div_scale_f32 v71, vcc, 1.0, v32, 1.0
	v_mul_f32_e32 v72, v71, v75
	v_fma_f32 v76, -v74, v72, v71
	v_fmac_f32_e32 v72, v76, v75
	v_fma_f32 v71, -v74, v72, v71
	v_div_fmas_f32 v71, v71, v75, v72
	v_div_fixup_f32 v32, v71, v32, 1.0
	v_mul_f32_e32 v32, 0xc1000000, v32
	v_mul_f32_e32 v32, v32, v84
	v_add_f32_e32 v72, v32, v32
	v_cmp_nlt_f32_e32 vcc, s0, v72
	s_and_saveexec_b64 s[0:1], vcc
	s_xor_b64 s[0:1], exec, s[0:1]
	v_mul_f32_e32 v71, 0x3fb8aa3b, v72
	v_exp_f32_e32 v71, v71
	s_nop 0
	v_sub_f32_e32 v71, 1.0, v71
	s_andn2_saveexec_b64 s[0:1], s[0:1]
	v_fmamk_f32 v71, v72, 0x3d2aaaab, v223
	v_fma_f32 v71, v72, v71, 0.5
	v_fma_f32 v71, v72, v71, 1.0
	v_mul_f32_e64 v71, v71, -v72
	s_or_b64 exec, exec, s[0:1]
	s_waitcnt lgkmcnt(14)
; DI float sigmoidf_(float x) { return 1.f / (1.f + __expf(-x)); }
;     ...
;   for (int i = 0; i < 16; ++i) {
;     const float rr = sigmoidf_(aA[i] + ba), ig = sigmoidf_(aX[i] + bx);
;     const float la = -8.f * rr * sp;
;     const float a = __expf(la);
;     const float x2 = 2.f * la;
;     const float em = (x2 > -0.1f) ? -x2 * (1.f + x2 * (0.5f + x2 * (0.16666667f + x2 * 0.041666667f))) : 1.f - __expf(x2);
;     const float bb = sqrtf(fmaxf(em, 0.f)) * ig * xc[i];
	v_add_f32_e32 v30, v30, v73
	v_mul_f32_e32 v30, 0xbfb8aa3b, v30
	v_exp_f32_e32 v30, v30
	s_nop 0
	v_add_f32_e32 v30, 1.0, v30
	v_div_scale_f32 v72, s[0:1], v30, v30, 1.0
	v_rcp_f32_e32 v74, v72
	v_div_scale_f32 v75, vcc, 1.0, v30, 1.0
	s_mov_b32 s0, 0xbdcccccd
	v_fma_f32 v76, -v72, v74, 1.0
	v_fmac_f32_e32 v74, v76, v74
	v_mul_f32_e32 v76, v75, v74
	v_fma_f32 v77, -v72, v76, v75
	v_fmac_f32_e32 v76, v77, v74
	v_fma_f32 v72, -v72, v76, v75
	v_div_fmas_f32 v72, v72, v74, v76
	v_div_fixup_f32 v30, v72, v30, 1.0
	v_mul_f32_e32 v30, 0xc1000000, v30
	v_mul_f32_e32 v30, v30, v84
	v_add_f32_e32 v74, v30, v30
	v_cmp_nlt_f32_e32 vcc, s0, v74
	s_and_saveexec_b64 s[0:1], vcc
	s_xor_b64 s[0:1], exec, s[0:1]
	v_mul_f32_e32 v72, 0x3fb8aa3b, v74
	v_exp_f32_e32 v72, v72
	s_nop 0
	v_sub_f32_e32 v72, 1.0, v72
	s_andn2_saveexec_b64 s[0:1], s[0:1]
	v_fmamk_f32 v72, v74, 0x3d2aaaab, v223
	v_fma_f32 v72, v74, v72, 0.5
	v_fma_f32 v72, v74, v72, 1.0
	v_mul_f32_e64 v72, v72, -v74
	s_or_b64 exec, exec, s[0:1]
	s_waitcnt lgkmcnt(13)
	v_add_f32_e32 v28, v28, v73
	v_mul_f32_e32 v28, 0xbfb8aa3b, v28
	v_exp_f32_e32 v28, v28
	s_nop 0
	v_add_f32_e32 v28, 1.0, v28
	v_div_scale_f32 v74, s[0:1], v28, v28, 1.0
	v_rcp_f32_e32 v75, v74
	v_div_scale_f32 v76, vcc, 1.0, v28, 1.0
	s_mov_b32 s0, 0xbdcccccd
	v_fma_f32 v77, -v74, v75, 1.0
	v_fmac_f32_e32 v75, v77, v75
	v_mul_f32_e32 v77, v76, v75
	v_fma_f32 v78, -v74, v77, v76
	v_fmac_f32_e32 v77, v78, v75
	v_fma_f32 v74, -v74, v77, v76
	v_div_fmas_f32 v74, v74, v75, v77
	v_div_fixup_f32 v28, v74, v28, 1.0
	v_mul_f32_e32 v28, 0xc1000000, v28
	v_mul_f32_e32 v28, v28, v84
	v_add_f32_e32 v75, v28, v28
	v_cmp_nlt_f32_e32 vcc, s0, v75
	s_and_saveexec_b64 s[0:1], vcc
	s_xor_b64 s[0:1], exec, s[0:1]
	v_mul_f32_e32 v74, 0x3fb8aa3b, v75
	v_exp_f32_e32 v74, v74
	s_nop 0
	v_sub_f32_e32 v74, 1.0, v74
	s_andn2_saveexec_b64 s[0:1], s[0:1]
	v_fmamk_f32 v74, v75, 0x3d2aaaab, v223
	v_fma_f32 v74, v75, v74, 0.5
	v_fma_f32 v74, v75, v74, 1.0
	v_mul_f32_e64 v74, v74, -v75
	s_or_b64 exec, exec, s[0:1]
	s_waitcnt lgkmcnt(12)
	v_add_f32_e32 v26, v26, v73
	v_mul_f32_e32 v26, 0xbfb8aa3b, v26
	v_exp_f32_e32 v26, v26
	s_nop 0
	v_add_f32_e32 v26, 1.0, v26
	v_div_scale_f32 v75, s[0:1], v26, v26, 1.0
	v_rcp_f32_e32 v76, v75
	v_div_scale_f32 v77, vcc, 1.0, v26, 1.0
	s_mov_b32 s0, 0xbdcccccd
	v_fma_f32 v78, -v75, v76, 1.0
	v_fmac_f32_e32 v76, v78, v76
	v_mul_f32_e32 v78, v77, v76
	v_fma_f32 v79, -v75, v78, v77
	v_fmac_f32_e32 v78, v79, v76
	v_fma_f32 v75, -v75, v78, v77
	v_div_fmas_f32 v75, v75, v76, v78
	v_div_fixup_f32 v26, v75, v26, 1.0
	v_mul_f32_e32 v26, 0xc1000000, v26
	v_mul_f32_e32 v26, v26, v84
	v_add_f32_e32 v76, v26, v26
	v_cmp_nlt_f32_e32 vcc, s0, v76
	s_and_saveexec_b64 s[0:1], vcc
	s_xor_b64 s[0:1], exec, s[0:1]
	v_mul_f32_e32 v75, 0x3fb8aa3b, v76
	v_exp_f32_e32 v75, v75
	s_nop 0
	v_sub_f32_e32 v75, 1.0, v75
	s_andn2_saveexec_b64 s[0:1], s[0:1]
	v_fmamk_f32 v75, v76, 0x3d2aaaab, v223
	v_fma_f32 v75, v76, v75, 0.5
	v_fma_f32 v75, v76, v75, 1.0
	v_mul_f32_e64 v75, v75, -v76
	s_or_b64 exec, exec, s[0:1]
	s_waitcnt lgkmcnt(11)
	v_add_f32_e32 v24, v24, v73
	v_mul_f32_e32 v24, 0xbfb8aa3b, v24
	v_exp_f32_e32 v24, v24
	s_nop 0
	v_add_f32_e32 v24, 1.0, v24
	v_div_scale_f32 v76, s[0:1], v24, v24, 1.0
	v_rcp_f32_e32 v77, v76
	v_div_scale_f32 v78, vcc, 1.0, v24, 1.0
	s_mov_b32 s0, 0xbdcccccd
	v_fma_f32 v79, -v76, v77, 1.0
	v_fmac_f32_e32 v77, v79, v77
	v_mul_f32_e32 v79, v78, v77
	v_fma_f32 v80, -v76, v79, v78
	v_fmac_f32_e32 v79, v80, v77
	v_fma_f32 v76, -v76, v79, v78
	v_div_fmas_f32 v76, v76, v77, v79
	v_div_fixup_f32 v24, v76, v24, 1.0
	v_mul_f32_e32 v24, 0xc1000000, v24
	v_mul_f32_e32 v24, v24, v84
	v_add_f32_e32 v77, v24, v24
	v_cmp_nlt_f32_e32 vcc, s0, v77
	s_and_saveexec_b64 s[0:1], vcc
	s_xor_b64 s[0:1], exec, s[0:1]
	v_mul_f32_e32 v76, 0x3fb8aa3b, v77
	v_exp_f32_e32 v76, v76
	s_nop 0
	v_sub_f32_e32 v76, 1.0, v76
	s_andn2_saveexec_b64 s[0:1], s[0:1]
	v_fmamk_f32 v76, v77, 0x3d2aaaab, v223
	v_fma_f32 v76, v77, v76, 0.5
	v_fma_f32 v76, v77, v76, 1.0
	v_mul_f32_e64 v76, v76, -v77
	s_or_b64 exec, exec, s[0:1]
	s_waitcnt lgkmcnt(10)
	v_add_f32_e32 v22, v22, v73
	v_mul_f32_e32 v22, 0xbfb8aa3b, v22
	v_exp_f32_e32 v22, v22
	s_nop 0
	v_add_f32_e32 v22, 1.0, v22
	v_div_scale_f32 v77, s[0:1], v22, v22, 1.0
	v_rcp_f32_e32 v78, v77
	v_div_scale_f32 v79, vcc, 1.0, v22, 1.0
	s_mov_b32 s0, 0xbdcccccd
	v_fma_f32 v80, -v77, v78, 1.0
	v_fmac_f32_e32 v78, v80, v78
	v_mul_f32_e32 v80, v79, v78
	v_fma_f32 v81, -v77, v80, v79
	v_fmac_f32_e32 v80, v81, v78
	v_fma_f32 v77, -v77, v80, v79
	v_div_fmas_f32 v77, v77, v78, v80
	v_div_fixup_f32 v22, v77, v22, 1.0
	v_mul_f32_e32 v22, 0xc1000000, v22
	v_mul_f32_e32 v22, v22, v84
	v_add_f32_e32 v78, v22, v22
	v_cmp_nlt_f32_e32 vcc, s0, v78
	s_and_saveexec_b64 s[0:1], vcc
	s_xor_b64 s[0:1], exec, s[0:1]
	v_mul_f32_e32 v77, 0x3fb8aa3b, v78
	v_exp_f32_e32 v77, v77
	s_nop 0
	v_sub_f32_e32 v77, 1.0, v77
	s_andn2_saveexec_b64 s[0:1], s[0:1]
	v_fmamk_f32 v77, v78, 0x3d2aaaab, v223
	v_fma_f32 v77, v78, v77, 0.5
	v_fma_f32 v77, v78, v77, 1.0
	v_mul_f32_e64 v77, v77, -v78
	s_or_b64 exec, exec, s[0:1]
	s_waitcnt lgkmcnt(9)
	v_add_f32_e32 v20, v20, v73
	v_mul_f32_e32 v20, 0xbfb8aa3b, v20
	v_exp_f32_e32 v20, v20
	s_nop 0
	v_add_f32_e32 v20, 1.0, v20
	v_div_scale_f32 v78, s[0:1], v20, v20, 1.0
	v_rcp_f32_e32 v79, v78
	v_div_scale_f32 v80, vcc, 1.0, v20, 1.0
	s_mov_b32 s0, 0xbdcccccd
	v_fma_f32 v81, -v78, v79, 1.0
	v_fmac_f32_e32 v79, v81, v79
	v_mul_f32_e32 v81, v80, v79
	v_fma_f32 v82, -v78, v81, v80
	v_fmac_f32_e32 v81, v82, v79
	v_fma_f32 v78, -v78, v81, v80
	v_div_fmas_f32 v78, v78, v79, v81
	v_div_fixup_f32 v20, v78, v20, 1.0
	v_mul_f32_e32 v20, 0xc1000000, v20
	v_mul_f32_e32 v20, v20, v84
	v_add_f32_e32 v79, v20, v20
	v_cmp_nlt_f32_e32 vcc, s0, v79
	s_and_saveexec_b64 s[0:1], vcc
	s_xor_b64 s[0:1], exec, s[0:1]
	v_mul_f32_e32 v78, 0x3fb8aa3b, v79
	v_exp_f32_e32 v78, v78
	s_nop 0
	v_sub_f32_e32 v78, 1.0, v78
	s_andn2_saveexec_b64 s[0:1], s[0:1]
	v_fmamk_f32 v78, v79, 0x3d2aaaab, v223
	v_fma_f32 v78, v79, v78, 0.5
	v_fma_f32 v78, v79, v78, 1.0
	v_mul_f32_e64 v78, v78, -v79
	s_or_b64 exec, exec, s[0:1]
	s_waitcnt lgkmcnt(8)
; DI float sigmoidf_(float x) { return 1.f / (1.f + __expf(-x)); }
;     ...
;   for (int i = 0; i < 16; ++i) {
;     const float rr = sigmoidf_(aA[i] + ba), ig = sigmoidf_(aX[i] + bx);
;     const float la = -8.f * rr * sp;
;     const float a = __expf(la);
;     const float x2 = 2.f * la;
;     const float em = (x2 > -0.1f) ? -x2 * (1.f + x2 * (0.5f + x2 * (0.16666667f + x2 * 0.041666667f))) : 1.f - __expf(x2);
	v_add_f32_e32 v18, v18, v73
	v_mul_f32_e32 v18, 0xbfb8aa3b, v18
	v_exp_f32_e32 v18, v18
	s_nop 0
	v_add_f32_e32 v18, 1.0, v18
	v_div_scale_f32 v79, s[0:1], v18, v18, 1.0
	v_rcp_f32_e32 v80, v79
	v_div_scale_f32 v81, vcc, 1.0, v18, 1.0
	s_mov_b32 s0, 0xbdcccccd
	v_fma_f32 v82, -v79, v80, 1.0
	v_fmac_f32_e32 v80, v82, v80
	v_mul_f32_e32 v82, v81, v80
	v_fma_f32 v83, -v79, v82, v81
	v_fmac_f32_e32 v82, v83, v80
	v_fma_f32 v79, -v79, v82, v81
	v_div_fmas_f32 v79, v79, v80, v82
	v_div_fixup_f32 v18, v79, v18, 1.0
	v_mul_f32_e32 v18, 0xc1000000, v18
	v_mul_f32_e32 v18, v18, v84
	v_add_f32_e32 v80, v18, v18
	v_cmp_nlt_f32_e32 vcc, s0, v80
	s_and_saveexec_b64 s[0:1], vcc
	s_xor_b64 s[0:1], exec, s[0:1]
	v_mul_f32_e32 v79, 0x3fb8aa3b, v80
	v_exp_f32_e32 v79, v79
	s_nop 0
	v_sub_f32_e32 v79, 1.0, v79
	s_andn2_saveexec_b64 s[0:1], s[0:1]
	v_fmamk_f32 v79, v80, 0x3d2aaaab, v223
	v_fma_f32 v79, v80, v79, 0.5
	v_fma_f32 v79, v80, v79, 1.0
	v_mul_f32_e64 v79, v79, -v80
	s_or_b64 exec, exec, s[0:1]
	s_waitcnt lgkmcnt(7)
	v_add_f32_e32 v16, v16, v73
	v_mul_f32_e32 v16, 0xbfb8aa3b, v16
	v_exp_f32_e32 v16, v16
	s_nop 0
	v_add_f32_e32 v16, 1.0, v16
	v_div_scale_f32 v80, s[0:1], v16, v16, 1.0
	v_rcp_f32_e32 v81, v80
	v_div_scale_f32 v82, vcc, 1.0, v16, 1.0
	s_mov_b32 s0, 0xbdcccccd
	v_fma_f32 v83, -v80, v81, 1.0
	v_fmac_f32_e32 v81, v83, v81
	v_mul_f32_e32 v83, v82, v81
	v_fma_f32 v85, -v80, v83, v82
	v_fmac_f32_e32 v83, v85, v81
	v_fma_f32 v80, -v80, v83, v82
	v_div_fmas_f32 v80, v80, v81, v83
	v_div_fixup_f32 v16, v80, v16, 1.0
	v_mul_f32_e32 v16, 0xc1000000, v16
	v_mul_f32_e32 v16, v16, v84
	v_add_f32_e32 v81, v16, v16
	v_cmp_nlt_f32_e32 vcc, s0, v81
	s_and_saveexec_b64 s[0:1], vcc
	s_xor_b64 s[0:1], exec, s[0:1]
	v_mul_f32_e32 v80, 0x3fb8aa3b, v81
	v_exp_f32_e32 v80, v80
	s_nop 0
	v_sub_f32_e32 v80, 1.0, v80
	s_andn2_saveexec_b64 s[0:1], s[0:1]
	v_fmamk_f32 v80, v81, 0x3d2aaaab, v223
	v_fma_f32 v80, v81, v80, 0.5
	v_fma_f32 v80, v81, v80, 1.0
	v_mul_f32_e64 v80, v80, -v81
	s_or_b64 exec, exec, s[0:1]
	s_waitcnt lgkmcnt(6)
	v_add_f32_e32 v14, v14, v73
	v_mul_f32_e32 v14, 0xbfb8aa3b, v14
	v_exp_f32_e32 v14, v14
	s_nop 0
	v_add_f32_e32 v14, 1.0, v14
	v_div_scale_f32 v81, s[0:1], v14, v14, 1.0
	v_rcp_f32_e32 v82, v81
	v_div_scale_f32 v83, vcc, 1.0, v14, 1.0
	s_mov_b32 s0, 0xbdcccccd
	v_fma_f32 v85, -v81, v82, 1.0
	v_fmac_f32_e32 v82, v85, v82
	v_mul_f32_e32 v85, v83, v82
	v_fma_f32 v86, -v81, v85, v83
	v_fmac_f32_e32 v85, v86, v82
	v_fma_f32 v81, -v81, v85, v83
	v_div_fmas_f32 v81, v81, v82, v85
	v_div_fixup_f32 v14, v81, v14, 1.0
	v_mul_f32_e32 v14, 0xc1000000, v14
	v_mul_f32_e32 v14, v14, v84
	v_add_f32_e32 v82, v14, v14
	v_cmp_nlt_f32_e32 vcc, s0, v82
	s_and_saveexec_b64 s[0:1], vcc
	s_xor_b64 s[0:1], exec, s[0:1]
	v_mul_f32_e32 v81, 0x3fb8aa3b, v82
	v_exp_f32_e32 v81, v81
	s_nop 0
	v_sub_f32_e32 v81, 1.0, v81
	s_andn2_saveexec_b64 s[0:1], s[0:1]
	v_fmamk_f32 v81, v82, 0x3d2aaaab, v223
	v_fma_f32 v81, v82, v81, 0.5
	v_fma_f32 v81, v82, v81, 1.0
	v_mul_f32_e64 v81, v81, -v82
	s_or_b64 exec, exec, s[0:1]
	s_waitcnt lgkmcnt(5)
	v_add_f32_e32 v12, v12, v73
	v_mul_f32_e32 v12, 0xbfb8aa3b, v12
	v_exp_f32_e32 v12, v12
	s_nop 0
	v_add_f32_e32 v12, 1.0, v12
	v_div_scale_f32 v82, s[0:1], v12, v12, 1.0
	v_rcp_f32_e32 v83, v82
	v_div_scale_f32 v85, vcc, 1.0, v12, 1.0
	s_mov_b32 s0, 0xbdcccccd
	v_fma_f32 v86, -v82, v83, 1.0
	v_fmac_f32_e32 v83, v86, v83
	v_mul_f32_e32 v86, v85, v83
	v_fma_f32 v87, -v82, v86, v85
	v_fmac_f32_e32 v86, v87, v83
	v_fma_f32 v82, -v82, v86, v85
	v_div_fmas_f32 v82, v82, v83, v86
	v_div_fixup_f32 v12, v82, v12, 1.0
	v_mul_f32_e32 v12, 0xc1000000, v12
	v_mul_f32_e32 v12, v12, v84
	v_add_f32_e32 v83, v12, v12
	v_cmp_nlt_f32_e32 vcc, s0, v83
	s_and_saveexec_b64 s[0:1], vcc
	s_xor_b64 s[0:1], exec, s[0:1]
	v_mul_f32_e32 v82, 0x3fb8aa3b, v83
	v_exp_f32_e32 v82, v82
	s_nop 0
	v_sub_f32_e32 v82, 1.0, v82
	s_andn2_saveexec_b64 s[0:1], s[0:1]
	v_fmamk_f32 v82, v83, 0x3d2aaaab, v223
	v_fma_f32 v82, v83, v82, 0.5
	v_fma_f32 v82, v83, v82, 1.0
	v_mul_f32_e64 v82, v82, -v83
	s_or_b64 exec, exec, s[0:1]
	s_waitcnt lgkmcnt(4)
	v_add_f32_e32 v10, v10, v73
	v_mul_f32_e32 v10, 0xbfb8aa3b, v10
	v_exp_f32_e32 v10, v10
	s_nop 0
	v_add_f32_e32 v10, 1.0, v10
	v_div_scale_f32 v83, s[0:1], v10, v10, 1.0
	v_rcp_f32_e32 v85, v83
	v_div_scale_f32 v86, vcc, 1.0, v10, 1.0
	s_mov_b32 s0, 0xbdcccccd
	v_fma_f32 v87, -v83, v85, 1.0
	v_fmac_f32_e32 v85, v87, v85
	v_mul_f32_e32 v87, v86, v85
	v_fma_f32 v88, -v83, v87, v86
	v_fmac_f32_e32 v87, v88, v85
	v_fma_f32 v83, -v83, v87, v86
	v_div_fmas_f32 v83, v83, v85, v87
	v_div_fixup_f32 v10, v83, v10, 1.0
	v_mul_f32_e32 v10, 0xc1000000, v10
	v_mul_f32_e32 v10, v10, v84
	v_add_f32_e32 v85, v10, v10
	v_cmp_nlt_f32_e32 vcc, s0, v85
	s_and_saveexec_b64 s[0:1], vcc
	s_xor_b64 s[0:1], exec, s[0:1]
	v_mul_f32_e32 v83, 0x3fb8aa3b, v85
	v_exp_f32_e32 v83, v83
	s_nop 0
	v_sub_f32_e32 v83, 1.0, v83
	s_andn2_saveexec_b64 s[0:1], s[0:1]
	v_fmamk_f32 v83, v85, 0x3d2aaaab, v223
	v_fma_f32 v83, v85, v83, 0.5
	v_fma_f32 v83, v85, v83, 1.0
	v_mul_f32_e64 v83, v83, -v85
	s_or_b64 exec, exec, s[0:1]
	s_waitcnt lgkmcnt(3)
	v_add_f32_e32 v8, v8, v73
	v_mul_f32_e32 v8, 0xbfb8aa3b, v8
	v_exp_f32_e32 v8, v8
	s_nop 0
	v_add_f32_e32 v8, 1.0, v8
	v_div_scale_f32 v85, s[0:1], v8, v8, 1.0
	v_rcp_f32_e32 v86, v85
	v_div_scale_f32 v87, vcc, 1.0, v8, 1.0
	s_mov_b32 s0, 0xbdcccccd
	v_fma_f32 v88, -v85, v86, 1.0
	v_fmac_f32_e32 v86, v88, v86
	v_mul_f32_e32 v88, v87, v86
	v_fma_f32 v89, -v85, v88, v87
	v_fmac_f32_e32 v88, v89, v86
	v_fma_f32 v85, -v85, v88, v87
	v_div_fmas_f32 v85, v85, v86, v88
	v_div_fixup_f32 v8, v85, v8, 1.0
	v_mul_f32_e32 v8, 0xc1000000, v8
	v_mul_f32_e32 v8, v8, v84
	v_add_f32_e32 v86, v8, v8
	v_cmp_nlt_f32_e32 vcc, s0, v86
	s_and_saveexec_b64 s[0:1], vcc
	s_xor_b64 s[0:1], exec, s[0:1]
	v_mul_f32_e32 v85, 0x3fb8aa3b, v86
	v_exp_f32_e32 v85, v85
	s_nop 0
	v_sub_f32_e32 v85, 1.0, v85
	s_andn2_saveexec_b64 s[0:1], s[0:1]
	v_fmamk_f32 v85, v86, 0x3d2aaaab, v223
	v_fma_f32 v85, v86, v85, 0.5
	v_fma_f32 v85, v86, v85, 1.0
	v_mul_f32_e64 v85, v85, -v86
	s_or_b64 exec, exec, s[0:1]
	s_waitcnt lgkmcnt(2)
; DI float bf2f(u16 v) { return (float)__builtin_bit_cast(_Float16, v); }
; DI float sigmoidf_(float x) { return 1.f / (1.f + __expf(-x)); }
;     ...
;   for (int i = 0; i < 16; ++i) {
;     const float cur = bf2f(zb[(size_t)(t0 + i) * ZS]);
;     xc[i] = cb + w0 * xm3 + w1 * xm2 + w2 * xm1 + w3 * cur;
;     xm3 = xm2; xm2 = xm1; xm1 = cur;
;     ...
;   for (int i = 0; i < 16; ++i) {
;     const float rr = sigmoidf_(aA[i] + ba), ig = sigmoidf_(aX[i] + bx);
;     const float la = -8.f * rr * sp;
;     const float a = __expf(la);
;     const float x2 = 2.f * la;
;     const float em = (x2 > -0.1f) ? -x2 * (1.f + x2 * (0.5f + x2 * (0.16666667f + x2 * 0.041666667f))) : 1.f - __expf(x2);
;     const float bb = sqrtf(fmaxf(em, 0.f)) * ig * xc[i];
;     aA[i] = a; aX[i] = bb;
;     H = a * H + bb;
;     P *= a;
;   }
	v_add_f32_e32 v6, v6, v73
	v_mul_f32_e32 v6, 0xbfb8aa3b, v6
	v_exp_f32_e32 v6, v6
	s_nop 0
	v_add_f32_e32 v6, 1.0, v6
	v_div_scale_f32 v86, s[0:1], v6, v6, 1.0
	v_rcp_f32_e32 v87, v86
	v_div_scale_f32 v88, vcc, 1.0, v6, 1.0
	s_mov_b32 s0, 0xbdcccccd
	v_fma_f32 v89, -v86, v87, 1.0
	v_fmac_f32_e32 v87, v89, v87
	v_mul_f32_e32 v89, v88, v87
	v_fma_f32 v90, -v86, v89, v88
	v_fmac_f32_e32 v89, v90, v87
	v_fma_f32 v86, -v86, v89, v88
	v_div_fmas_f32 v86, v86, v87, v89
	v_div_fixup_f32 v6, v86, v6, 1.0
	v_mul_f32_e32 v6, 0xc1000000, v6
	v_mul_f32_e32 v6, v6, v84
	v_add_f32_e32 v87, v6, v6
	v_cmp_nlt_f32_e32 vcc, s0, v87
	s_and_saveexec_b64 s[0:1], vcc
	s_xor_b64 s[0:1], exec, s[0:1]
	v_mul_f32_e32 v86, 0x3fb8aa3b, v87
	v_exp_f32_e32 v86, v86
	s_nop 0
	v_sub_f32_e32 v86, 1.0, v86
	s_andn2_saveexec_b64 s[0:1], s[0:1]
	v_fmamk_f32 v86, v87, 0x3d2aaaab, v223
	v_fma_f32 v86, v87, v86, 0.5
	v_fma_f32 v86, v87, v86, 1.0
	v_mul_f32_e64 v86, v86, -v87
	s_or_b64 exec, exec, s[0:1]
	s_waitcnt lgkmcnt(1)
	v_add_f32_e32 v4, v4, v73
	v_mul_f32_e32 v4, 0xbfb8aa3b, v4
	v_exp_f32_e32 v4, v4
	s_nop 0
	v_add_f32_e32 v4, 1.0, v4
	v_div_scale_f32 v87, s[0:1], v4, v4, 1.0
	v_rcp_f32_e32 v88, v87
	v_div_scale_f32 v89, vcc, 1.0, v4, 1.0
	s_mov_b32 s0, 0xbdcccccd
	v_fma_f32 v90, -v87, v88, 1.0
	v_fmac_f32_e32 v88, v90, v88
	v_mul_f32_e32 v90, v89, v88
	v_fma_f32 v91, -v87, v90, v89
	v_fmac_f32_e32 v90, v91, v88
	v_fma_f32 v87, -v87, v90, v89
	v_div_fmas_f32 v87, v87, v88, v90
	v_div_fixup_f32 v4, v87, v4, 1.0
	v_mul_f32_e32 v4, 0xc1000000, v4
	v_mul_f32_e32 v4, v4, v84
	v_add_f32_e32 v88, v4, v4
	v_cmp_nlt_f32_e32 vcc, s0, v88
	s_and_saveexec_b64 s[0:1], vcc
	s_xor_b64 s[0:1], exec, s[0:1]
	v_mul_f32_e32 v87, 0x3fb8aa3b, v88
	v_exp_f32_e32 v87, v87
	s_nop 0
	v_sub_f32_e32 v87, 1.0, v87
	s_andn2_saveexec_b64 s[0:1], s[0:1]
	v_fmamk_f32 v87, v88, 0x3d2aaaab, v223
	v_fma_f32 v87, v88, v87, 0.5
	v_fma_f32 v87, v88, v87, 1.0
	v_mul_f32_e64 v87, v87, -v88
	s_or_b64 exec, exec, s[0:1]
	s_waitcnt lgkmcnt(0)
	v_add_f32_e32 v2, v2, v73
	v_mul_f32_e32 v2, 0xbfb8aa3b, v2
	v_exp_f32_e32 v2, v2
	s_nop 0
	v_add_f32_e32 v2, 1.0, v2
	v_div_scale_f32 v73, s[0:1], v2, v2, 1.0
	v_rcp_f32_e32 v88, v73
	v_div_scale_f32 v89, vcc, 1.0, v2, 1.0
	s_mov_b32 s0, 0xbdcccccd
	v_fma_f32 v90, -v73, v88, 1.0
	v_fmac_f32_e32 v88, v90, v88
	v_mul_f32_e32 v90, v89, v88
	v_fma_f32 v91, -v73, v90, v89
	v_fmac_f32_e32 v90, v91, v88
	v_fma_f32 v73, -v73, v90, v89
	v_div_fmas_f32 v73, v73, v88, v90
	v_div_fixup_f32 v2, v73, v2, 1.0
	v_mul_f32_e32 v2, 0xc1000000, v2
	v_mul_f32_e32 v2, v2, v84
	v_add_f32_e32 v84, v2, v2
	v_cmp_nlt_f32_e32 vcc, s0, v84
	s_and_saveexec_b64 s[0:1], vcc
	s_xor_b64 s[0:1], exec, s[0:1]
	v_mul_f32_e32 v73, 0x3fb8aa3b, v84
	v_exp_f32_e32 v73, v73
	s_nop 0
	v_sub_f32_e32 v73, 1.0, v73
	s_andn2_saveexec_b64 s[0:1], s[0:1]
	v_fmamk_f32 v73, v84, 0x3d2aaaab, v223
	v_fma_f32 v73, v84, v73, 0.5
	v_fma_f32 v73, v84, v73, 1.0
	v_mul_f32_e64 v73, v73, -v84
	s_or_b64 exec, exec, s[0:1]
	s_waitcnt vmcnt(0)
	v_add_f32_e32 v33, v33, v34
	v_mul_f32_e32 v33, 0xbfb8aa3b, v33
	v_exp_f32_e32 v33, v33
	v_fma_mix_f32 v56, v38, v43, v56 op_sel_hi:[0,1,0]
	v_fma_mix_f32 v43, v38, v46, v63 op_sel_hi:[0,1,0]
	v_fma_mix_f32 v55, v38, v42, v55 op_sel_hi:[0,1,0]
	v_add_f32_e32 v46, 1.0, v33
	v_fma_mix_f32 v42, v38, v47, v65 op_sel_hi:[0,1,0]
	v_div_scale_f32 v47, s[0:1], v46, v46, 1.0
	v_fma_mix_f32 v54, v38, v41, v54 op_sel_hi:[0,1,0]
	v_fma_mix_f32 v41, v38, v48, v67 op_sel_hi:[0,1,0]
	v_rcp_f32_e32 v48, v47
	v_fma_mix_f32 v84, v38, v39, v44 op_sel_hi:[0,1,0]
	v_fma_mix_f32 v53, v38, v40, v53 op_sel_hi:[0,1,0]
	v_fma_mix_f32 v45, v38, v45, v57 op_sel_hi:[0,1,0]
	v_fma_mix_f32 v49, v38, v49, v61 op_sel_hi:[0,1,0]
	v_fma_mix_f32 v50, v38, v50, v62 op_sel_hi:[0,1,0]
	v_fma_mix_f32 v51, v38, v51, v64 op_sel_hi:[0,1,0]
	v_fma_mix_f32 v44, v38, v52, v66 op_sel_hi:[0,1,0]
	v_fma_mix_f32 v40, v38, v58, v68 op_sel_hi:[0,1,0]
	v_fma_mix_f32 v39, v38, v59, v69 op_sel_hi:[0,1,0]
	v_fma_mix_f32 v33, v38, v60, v70 op_sel_hi:[0,1,0]
	v_fma_f32 v38, -v47, v48, 1.0
	v_fmac_f32_e32 v48, v38, v48
	v_div_scale_f32 v38, vcc, 1.0, v46, 1.0
	v_mul_f32_e32 v52, v38, v48
	v_fma_f32 v57, -v47, v52, v38
	v_fmac_f32_e32 v52, v57, v48
	v_fma_f32 v38, -v47, v52, v38
	v_max_f32_e32 v47, v71, v71
	v_max_f32_e32 v47, 0, v47
	s_mov_b32 s10, 0xf800000
	v_div_fmas_f32 v38, v38, v48, v52
	v_mul_f32_e32 v48, 0x4f800000, v47
	v_cmp_gt_f32_e32 vcc, s10, v47
	v_div_fixup_f32 v38, v38, v46, 1.0
	v_add_f32_e32 v31, v31, v34
	v_cndmask_b32_e32 v47, v47, v48, vcc
	v_sqrt_f32_e32 v48, v47
	v_mul_f32_e32 v31, 0xbfb8aa3b, v31
	v_exp_f32_e32 v31, v31
	v_mov_b32_e32 v58, 0x260
	v_add_u32_e32 v46, -1, v48
	v_fma_f32 v52, -v46, v48, v47
	v_cmp_ge_f32_e64 s[0:1], 0, v52
	v_add_u32_e32 v52, 1, v48
	v_add_f32_e32 v31, 1.0, v31
	v_cndmask_b32_e64 v46, v48, v46, s[0:1]
	v_fma_f32 v48, -v52, v48, v47
	v_cmp_lt_f32_e64 s[0:1], 0, v48
	v_add_f32_e32 v29, v29, v34
	v_mul_f32_e32 v29, 0xbfb8aa3b, v29
	v_cndmask_b32_e64 v46, v46, v52, s[0:1]
	v_mul_f32_e32 v48, 0x37800000, v46
	v_cndmask_b32_e32 v46, v46, v48, vcc
	v_cmp_class_f32_e32 vcc, v47, v58
	v_exp_f32_e32 v29, v29
	v_mul_f32_e32 v32, 0x3fb8aa3b, v32
	v_cndmask_b32_e32 v46, v46, v47, vcc
	v_div_scale_f32 v47, s[0:1], v31, v31, 1.0
	v_rcp_f32_e32 v48, v47
	v_mul_f32_e32 v38, v38, v46
	v_add_f32_e32 v29, 1.0, v29
	v_exp_f32_e32 v32, v32
	v_fma_f32 v46, -v47, v48, 1.0
	v_fmac_f32_e32 v48, v46, v48
	v_div_scale_f32 v46, vcc, 1.0, v31, 1.0
	v_mul_f32_e32 v52, v46, v48
	v_fma_f32 v57, -v47, v52, v46
	v_fmac_f32_e32 v52, v57, v48
	v_fma_f32 v46, -v47, v52, v46
	v_max_f32_e32 v47, v72, v72
	v_max_f32_e32 v47, 0, v47
; DI float sigmoidf_(float x) { return 1.f / (1.f + __expf(-x)); }
;     ...
;   for (int i = 0; i < 16; ++i) {
;     const float rr = sigmoidf_(aA[i] + ba), ig = sigmoidf_(aX[i] + bx);
;     const float la = -8.f * rr * sp;
;     const float a = __expf(la);
;     const float x2 = 2.f * la;
;     const float em = (x2 > -0.1f) ? -x2 * (1.f + x2 * (0.5f + x2 * (0.16666667f + x2 * 0.041666667f))) : 1.f - __expf(x2);
;     const float bb = sqrtf(fmaxf(em, 0.f)) * ig * xc[i];
;     aA[i] = a; aX[i] = bb;
;     H = a * H + bb;
;     P *= a;
;   }
	v_div_fmas_f32 v46, v46, v48, v52
	v_mul_f32_e32 v48, 0x4f800000, v47
	v_cmp_gt_f32_e32 vcc, s10, v47
	v_div_fixup_f32 v31, v46, v31, 1.0
	v_mul_f32_e32 v30, 0x3fb8aa3b, v30
	v_cndmask_b32_e32 v47, v47, v48, vcc
	v_sqrt_f32_e32 v48, v47
	v_exp_f32_e32 v30, v30
	v_mul_f32_e32 v38, v84, v38
	v_fmac_f32_e32 v38, 0, v32
	v_add_u32_e32 v46, -1, v48
	v_fma_f32 v52, -v46, v48, v47
	v_cmp_ge_f32_e64 s[0:1], 0, v52
	v_add_u32_e32 v52, 1, v48
	v_add_f32_e32 v27, v27, v34
	v_cndmask_b32_e64 v46, v48, v46, s[0:1]
	v_fma_f32 v48, -v52, v48, v47
	v_cmp_lt_f32_e64 s[0:1], 0, v48
	v_mul_f32_e32 v27, 0xbfb8aa3b, v27
	v_exp_f32_e32 v27, v27
	v_cndmask_b32_e64 v46, v46, v52, s[0:1]
	v_mul_f32_e32 v48, 0x37800000, v46
	v_cndmask_b32_e32 v46, v46, v48, vcc
	v_cmp_class_f32_e32 vcc, v47, v58
	v_add_f32_e32 v27, 1.0, v27
	v_mul_f32_e32 v28, 0x3fb8aa3b, v28
	v_cndmask_b32_e32 v46, v46, v47, vcc
	v_mul_f32_e32 v31, v31, v46
	v_div_scale_f32 v46, s[0:1], v29, v29, 1.0
	v_rcp_f32_e32 v47, v46
	v_mul_f32_e32 v31, v53, v31
	v_fmac_f32_e32 v31, v30, v38
	v_mul_f32_e32 v30, v32, v30
	v_fma_f32 v32, -v46, v47, 1.0
	v_fmac_f32_e32 v47, v32, v47
	v_div_scale_f32 v32, vcc, 1.0, v29, 1.0
	v_mul_f32_e32 v38, v32, v47
	v_fma_f32 v48, -v46, v38, v32
	v_fmac_f32_e32 v38, v48, v47
	v_fma_f32 v32, -v46, v38, v32
	v_div_fmas_f32 v32, v32, v47, v38
	v_max_f32_e32 v38, v74, v74
	v_max_f32_e32 v38, 0, v38
	v_mul_f32_e32 v46, 0x4f800000, v38
	v_cmp_gt_f32_e32 vcc, s10, v38
	v_div_fixup_f32 v29, v32, v29, 1.0
	v_exp_f32_e32 v28, v28
	v_cndmask_b32_e32 v38, v38, v46, vcc
	v_sqrt_f32_e32 v46, v38
	v_add_f32_e32 v25, v25, v34
	v_mul_f32_e32 v25, 0xbfb8aa3b, v25
	v_exp_f32_e32 v25, v25
	v_add_u32_e32 v32, -1, v46
	v_fma_f32 v47, -v32, v46, v38
	v_cmp_ge_f32_e64 s[0:1], 0, v47
	v_add_u32_e32 v47, 1, v46
	v_add_f32_e32 v25, 1.0, v25
	v_cndmask_b32_e64 v32, v46, v32, s[0:1]
	v_fma_f32 v46, -v47, v46, v38
	v_cmp_lt_f32_e64 s[0:1], 0, v46
	v_mul_f32_e32 v26, 0x3fb8aa3b, v26
	v_exp_f32_e32 v26, v26
	v_cndmask_b32_e64 v32, v32, v47, s[0:1]
	v_mul_f32_e32 v46, 0x37800000, v32
	v_cndmask_b32_e32 v32, v32, v46, vcc
	v_cmp_class_f32_e32 vcc, v38, v58
	v_add_f32_e32 v23, v23, v34
	v_mul_f32_e32 v23, 0xbfb8aa3b, v23
	v_cndmask_b32_e32 v32, v32, v38, vcc
	v_mul_f32_e32 v29, v29, v32
	v_div_scale_f32 v32, s[0:1], v27, v27, 1.0
	v_rcp_f32_e32 v38, v32
	v_mul_f32_e32 v29, v54, v29
	v_fmac_f32_e32 v29, v28, v31
	v_mul_f32_e32 v28, v28, v30
	v_fma_f32 v30, -v32, v38, 1.0
	v_fmac_f32_e32 v38, v30, v38
	v_div_scale_f32 v30, vcc, 1.0, v27, 1.0
	v_mul_f32_e32 v31, v30, v38
	v_fma_f32 v46, -v32, v31, v30
	v_fmac_f32_e32 v31, v46, v38
	v_fma_f32 v30, -v32, v31, v30
	v_div_fmas_f32 v30, v30, v38, v31
	v_max_f32_e32 v31, v75, v75
	v_max_f32_e32 v31, 0, v31
	v_mul_f32_e32 v32, 0x4f800000, v31
	v_cmp_gt_f32_e32 vcc, s10, v31
	v_div_fixup_f32 v27, v30, v27, 1.0
	v_exp_f32_e32 v23, v23
	v_cndmask_b32_e32 v31, v31, v32, vcc
	v_sqrt_f32_e32 v32, v31
	v_mul_f32_e32 v24, 0x3fb8aa3b, v24
	v_add_f32_e32 v23, 1.0, v23
	v_exp_f32_e32 v24, v24
	v_add_u32_e32 v30, -1, v32
	v_fma_f32 v38, -v30, v32, v31
	v_cmp_ge_f32_e64 s[0:1], 0, v38
	v_add_u32_e32 v38, 1, v32
	v_add_f32_e32 v21, v21, v34
	v_cndmask_b32_e64 v30, v32, v30, s[0:1]
	v_fma_f32 v32, -v38, v32, v31
	v_cmp_lt_f32_e64 s[0:1], 0, v32
	v_mul_f32_e32 v21, 0xbfb8aa3b, v21
	v_exp_f32_e32 v21, v21
	v_cndmask_b32_e64 v30, v30, v38, s[0:1]
	v_mul_f32_e32 v32, 0x37800000, v30
	v_cndmask_b32_e32 v30, v30, v32, vcc
	v_cmp_class_f32_e32 vcc, v31, v58
	v_add_f32_e32 v21, 1.0, v21
	v_mul_f32_e32 v22, 0x3fb8aa3b, v22
	v_cndmask_b32_e32 v30, v30, v31, vcc
	v_mul_f32_e32 v27, v27, v30
	v_div_scale_f32 v30, s[0:1], v25, v25, 1.0
	v_rcp_f32_e32 v31, v30
	v_mul_f32_e32 v27, v55, v27
	v_fmac_f32_e32 v27, v26, v29
	v_mul_f32_e32 v26, v26, v28
	v_fma_f32 v28, -v30, v31, 1.0
	v_fmac_f32_e32 v31, v28, v31
	v_div_scale_f32 v28, vcc, 1.0, v25, 1.0
	v_mul_f32_e32 v29, v28, v31
	v_fma_f32 v32, -v30, v29, v28
	v_fmac_f32_e32 v29, v32, v31
	v_fma_f32 v28, -v30, v29, v28
	v_div_fmas_f32 v28, v28, v31, v29
	v_max_f32_e32 v29, v76, v76
	v_max_f32_e32 v29, 0, v29
	v_mul_f32_e32 v30, 0x4f800000, v29
	v_cmp_gt_f32_e32 vcc, s10, v29
	v_div_fixup_f32 v25, v28, v25, 1.0
	v_exp_f32_e32 v22, v22
	v_cndmask_b32_e32 v29, v29, v30, vcc
	v_sqrt_f32_e32 v30, v29
	v_add_f32_e32 v19, v19, v34
	v_mul_f32_e32 v19, 0xbfb8aa3b, v19
	v_exp_f32_e32 v19, v19
	v_add_u32_e32 v28, -1, v30
	v_fma_f32 v31, -v28, v30, v29
	v_cmp_ge_f32_e64 s[0:1], 0, v31
	v_add_u32_e32 v31, 1, v30
	v_add_f32_e32 v19, 1.0, v19
	v_cndmask_b32_e64 v28, v30, v28, s[0:1]
	v_fma_f32 v30, -v31, v30, v29
	v_cmp_lt_f32_e64 s[0:1], 0, v30
	v_mul_f32_e32 v20, 0x3fb8aa3b, v20
	v_exp_f32_e32 v20, v20
	v_cndmask_b32_e64 v28, v28, v31, s[0:1]
	v_mul_f32_e32 v30, 0x37800000, v28
	v_cndmask_b32_e32 v28, v28, v30, vcc
	v_cmp_class_f32_e32 vcc, v29, v58
	v_add_f32_e32 v17, v17, v34
	v_mul_f32_e32 v17, 0xbfb8aa3b, v17
	v_cndmask_b32_e32 v28, v28, v29, vcc
	v_mul_f32_e32 v25, v25, v28
	v_div_scale_f32 v28, s[0:1], v23, v23, 1.0
	v_rcp_f32_e32 v29, v28
	v_mul_f32_e32 v25, v56, v25
	v_fmac_f32_e32 v25, v24, v27
	v_mul_f32_e32 v24, v24, v26
	v_fma_f32 v26, -v28, v29, 1.0
	v_fmac_f32_e32 v29, v26, v29
	v_div_scale_f32 v26, vcc, 1.0, v23, 1.0
	v_mul_f32_e32 v27, v26, v29
	v_fma_f32 v30, -v28, v27, v26
	v_fmac_f32_e32 v27, v30, v29
	v_fma_f32 v26, -v28, v27, v26
	v_div_fmas_f32 v26, v26, v29, v27
	v_max_f32_e32 v27, v77, v77
	v_max_f32_e32 v27, 0, v27
	v_mul_f32_e32 v28, 0x4f800000, v27
	v_cmp_gt_f32_e32 vcc, s10, v27
	v_div_fixup_f32 v23, v26, v23, 1.0
	v_exp_f32_e32 v17, v17
	v_cndmask_b32_e32 v27, v27, v28, vcc
	v_sqrt_f32_e32 v28, v27
	v_mul_f32_e32 v18, 0x3fb8aa3b, v18
; DI float sigmoidf_(float x) { return 1.f / (1.f + __expf(-x)); }
;     ...
;   for (int i = 0; i < 16; ++i) {
;     const float rr = sigmoidf_(aA[i] + ba), ig = sigmoidf_(aX[i] + bx);
;     const float la = -8.f * rr * sp;
;     const float a = __expf(la);
;     const float x2 = 2.f * la;
;     const float em = (x2 > -0.1f) ? -x2 * (1.f + x2 * (0.5f + x2 * (0.16666667f + x2 * 0.041666667f))) : 1.f - __expf(x2);
;     const float bb = sqrtf(fmaxf(em, 0.f)) * ig * xc[i];
;     aA[i] = a; aX[i] = bb;
;     H = a * H + bb;
;     P *= a;
;   }
	v_add_f32_e32 v17, 1.0, v17
	v_exp_f32_e32 v18, v18
	v_add_u32_e32 v26, -1, v28
	v_fma_f32 v29, -v26, v28, v27
	v_cmp_ge_f32_e64 s[0:1], 0, v29
	v_add_u32_e32 v29, 1, v28
	v_add_f32_e32 v15, v15, v34
	v_cndmask_b32_e64 v26, v28, v26, s[0:1]
	v_fma_f32 v28, -v29, v28, v27
	v_cmp_lt_f32_e64 s[0:1], 0, v28
	v_mul_f32_e32 v15, 0xbfb8aa3b, v15
	v_exp_f32_e32 v15, v15
	v_cndmask_b32_e64 v26, v26, v29, s[0:1]
	v_mul_f32_e32 v28, 0x37800000, v26
	v_cndmask_b32_e32 v26, v26, v28, vcc
	v_cmp_class_f32_e32 vcc, v27, v58
	v_add_f32_e32 v15, 1.0, v15
	v_mul_f32_e32 v16, 0x3fb8aa3b, v16
	v_cndmask_b32_e32 v26, v26, v27, vcc
	v_mul_f32_e32 v23, v23, v26
	v_div_scale_f32 v26, s[0:1], v21, v21, 1.0
	v_rcp_f32_e32 v27, v26
	v_mul_f32_e32 v23, v45, v23
	v_fmac_f32_e32 v23, v22, v25
	v_mul_f32_e32 v22, v22, v24
	v_fma_f32 v24, -v26, v27, 1.0
	v_fmac_f32_e32 v27, v24, v27
	v_div_scale_f32 v24, vcc, 1.0, v21, 1.0
	v_mul_f32_e32 v25, v24, v27
	v_fma_f32 v28, -v26, v25, v24
	v_fmac_f32_e32 v25, v28, v27
	v_fma_f32 v24, -v26, v25, v24
	v_div_fmas_f32 v24, v24, v27, v25
	v_max_f32_e32 v25, v78, v78
	v_max_f32_e32 v25, 0, v25
	v_mul_f32_e32 v26, 0x4f800000, v25
	v_cmp_gt_f32_e32 vcc, s10, v25
	v_div_fixup_f32 v21, v24, v21, 1.0
	v_exp_f32_e32 v16, v16
	v_cndmask_b32_e32 v25, v25, v26, vcc
	v_sqrt_f32_e32 v26, v25
	v_add_f32_e32 v13, v13, v34
	v_mul_f32_e32 v13, 0xbfb8aa3b, v13
	v_exp_f32_e32 v13, v13
	v_add_u32_e32 v24, -1, v26
	v_fma_f32 v27, -v24, v26, v25
	v_cmp_ge_f32_e64 s[0:1], 0, v27
	v_add_u32_e32 v27, 1, v26
	v_add_f32_e32 v13, 1.0, v13
	v_cndmask_b32_e64 v24, v26, v24, s[0:1]
	v_fma_f32 v26, -v27, v26, v25
	v_cmp_lt_f32_e64 s[0:1], 0, v26
	v_mul_f32_e32 v14, 0x3fb8aa3b, v14
	v_exp_f32_e32 v14, v14
	v_cndmask_b32_e64 v24, v24, v27, s[0:1]
	v_mul_f32_e32 v26, 0x37800000, v24
	v_cndmask_b32_e32 v24, v24, v26, vcc
	v_cmp_class_f32_e32 vcc, v25, v58
	v_add_f32_e32 v11, v11, v34
	v_mul_f32_e32 v11, 0xbfb8aa3b, v11
	v_cndmask_b32_e32 v24, v24, v25, vcc
	v_mul_f32_e32 v21, v21, v24
	v_div_scale_f32 v24, s[0:1], v19, v19, 1.0
	v_rcp_f32_e32 v25, v24
	v_mul_f32_e32 v21, v49, v21
	v_fmac_f32_e32 v21, v20, v23
	v_mul_f32_e32 v20, v20, v22
	v_fma_f32 v22, -v24, v25, 1.0
	v_fmac_f32_e32 v25, v22, v25
	v_div_scale_f32 v22, vcc, 1.0, v19, 1.0
	v_mul_f32_e32 v23, v22, v25
	v_fma_f32 v26, -v24, v23, v22
	v_fmac_f32_e32 v23, v26, v25
	v_fma_f32 v22, -v24, v23, v22
	v_div_fmas_f32 v22, v22, v25, v23
	v_max_f32_e32 v23, v79, v79
	v_max_f32_e32 v23, 0, v23
	v_mul_f32_e32 v24, 0x4f800000, v23
	v_cmp_gt_f32_e32 vcc, s10, v23
	v_div_fixup_f32 v19, v22, v19, 1.0
	v_exp_f32_e32 v11, v11
	v_cndmask_b32_e32 v23, v23, v24, vcc
	v_sqrt_f32_e32 v24, v23
	v_mul_f32_e32 v12, 0x3fb8aa3b, v12
	v_add_f32_e32 v11, 1.0, v11
	v_exp_f32_e32 v12, v12
	v_add_u32_e32 v22, -1, v24
	v_fma_f32 v25, -v22, v24, v23
	v_cmp_ge_f32_e64 s[0:1], 0, v25
	v_add_u32_e32 v25, 1, v24
	v_add_f32_e32 v9, v9, v34
	v_cndmask_b32_e64 v22, v24, v22, s[0:1]
	v_fma_f32 v24, -v25, v24, v23
	v_cmp_lt_f32_e64 s[0:1], 0, v24
	v_mul_f32_e32 v9, 0xbfb8aa3b, v9
	v_exp_f32_e32 v9, v9
	v_cndmask_b32_e64 v22, v22, v25, s[0:1]
	v_mul_f32_e32 v24, 0x37800000, v22
	v_cndmask_b32_e32 v22, v22, v24, vcc
	v_cmp_class_f32_e32 vcc, v23, v58
	v_add_f32_e32 v9, 1.0, v9
	v_mul_f32_e32 v10, 0x3fb8aa3b, v10
	v_cndmask_b32_e32 v22, v22, v23, vcc
	v_mul_f32_e32 v19, v19, v22
	v_div_scale_f32 v22, s[0:1], v17, v17, 1.0
	v_rcp_f32_e32 v23, v22
	v_mul_f32_e32 v19, v50, v19
	v_fmac_f32_e32 v19, v18, v21
	v_mul_f32_e32 v18, v18, v20
	v_fma_f32 v20, -v22, v23, 1.0
	v_fmac_f32_e32 v23, v20, v23
	v_div_scale_f32 v20, vcc, 1.0, v17, 1.0
	v_mul_f32_e32 v21, v20, v23
	v_fma_f32 v24, -v22, v21, v20
	v_fmac_f32_e32 v21, v24, v23
	v_fma_f32 v20, -v22, v21, v20
	v_div_fmas_f32 v20, v20, v23, v21
	v_max_f32_e32 v21, v80, v80
	v_max_f32_e32 v21, 0, v21
	v_mul_f32_e32 v22, 0x4f800000, v21
	v_cmp_gt_f32_e32 vcc, s10, v21
	v_div_fixup_f32 v17, v20, v17, 1.0
	v_exp_f32_e32 v10, v10
	v_cndmask_b32_e32 v21, v21, v22, vcc
	v_sqrt_f32_e32 v22, v21
	v_add_f32_e32 v7, v7, v34
	v_mul_f32_e32 v7, 0xbfb8aa3b, v7
	v_exp_f32_e32 v7, v7
	v_add_u32_e32 v20, -1, v22
	v_fma_f32 v23, -v20, v22, v21
	v_cmp_ge_f32_e64 s[0:1], 0, v23
	v_add_u32_e32 v23, 1, v22
	v_add_f32_e32 v7, 1.0, v7
	v_cndmask_b32_e64 v20, v22, v20, s[0:1]
	v_fma_f32 v22, -v23, v22, v21
	v_cmp_lt_f32_e64 s[0:1], 0, v22
	v_mul_f32_e32 v8, 0x3fb8aa3b, v8
	v_exp_f32_e32 v8, v8
	v_cndmask_b32_e64 v20, v20, v23, s[0:1]
	v_mul_f32_e32 v22, 0x37800000, v20
	v_cndmask_b32_e32 v20, v20, v22, vcc
	v_cmp_class_f32_e32 vcc, v21, v58
	v_add_f32_e32 v5, v5, v34
	v_mul_f32_e32 v5, 0xbfb8aa3b, v5
	v_cndmask_b32_e32 v20, v20, v21, vcc
	v_mul_f32_e32 v17, v17, v20
	v_div_scale_f32 v20, s[0:1], v15, v15, 1.0
	v_rcp_f32_e32 v21, v20
	v_mul_f32_e32 v17, v51, v17
	v_fmac_f32_e32 v17, v16, v19
	v_mul_f32_e32 v16, v16, v18
	v_fma_f32 v18, -v20, v21, 1.0
	v_fmac_f32_e32 v21, v18, v21
	v_div_scale_f32 v18, vcc, 1.0, v15, 1.0
	v_mul_f32_e32 v19, v18, v21
	v_fma_f32 v22, -v20, v19, v18
	v_fmac_f32_e32 v19, v22, v21
	v_fma_f32 v18, -v20, v19, v18
	v_div_fmas_f32 v18, v18, v21, v19
	v_max_f32_e32 v19, v81, v81
	v_max_f32_e32 v19, 0, v19
	v_mul_f32_e32 v20, 0x4f800000, v19
	v_cmp_gt_f32_e32 vcc, s10, v19
	v_div_fixup_f32 v15, v18, v15, 1.0
	v_exp_f32_e32 v5, v5
	v_cndmask_b32_e32 v19, v19, v20, vcc
	v_sqrt_f32_e32 v20, v19
	v_mul_f32_e32 v6, 0x3fb8aa3b, v6
	v_add_f32_e32 v5, 1.0, v5
	v_exp_f32_e32 v6, v6
	v_add_u32_e32 v18, -1, v20
	v_fma_f32 v21, -v18, v20, v19
	v_cmp_ge_f32_e64 s[0:1], 0, v21
	v_add_u32_e32 v21, 1, v20
	v_add_f32_e32 v3, v3, v34
	v_cndmask_b32_e64 v18, v20, v18, s[0:1]
	v_fma_f32 v20, -v21, v20, v19
	v_cmp_lt_f32_e64 s[0:1], 0, v20
; DI float sigmoidf_(float x) { return 1.f / (1.f + __expf(-x)); }
;     ...
;   for (int i = 0; i < 16; ++i) {
;     const float rr = sigmoidf_(aA[i] + ba), ig = sigmoidf_(aX[i] + bx);
;     const float la = -8.f * rr * sp;
;     const float a = __expf(la);
;     const float x2 = 2.f * la;
;     const float em = (x2 > -0.1f) ? -x2 * (1.f + x2 * (0.5f + x2 * (0.16666667f + x2 * 0.041666667f))) : 1.f - __expf(x2);
;     const float bb = sqrtf(fmaxf(em, 0.f)) * ig * xc[i];
;     aA[i] = a; aX[i] = bb;
;     H = a * H + bb;
;     P *= a;
;   }
	v_mul_f32_e32 v3, 0xbfb8aa3b, v3
	v_exp_f32_e32 v3, v3
	v_cndmask_b32_e64 v18, v18, v21, s[0:1]
	v_mul_f32_e32 v20, 0x37800000, v18
	v_cndmask_b32_e32 v18, v18, v20, vcc
	v_cmp_class_f32_e32 vcc, v19, v58
	v_add_f32_e32 v3, 1.0, v3
	v_mul_f32_e32 v4, 0x3fb8aa3b, v4
	v_cndmask_b32_e32 v18, v18, v19, vcc
	v_mul_f32_e32 v15, v15, v18
	v_div_scale_f32 v18, s[0:1], v13, v13, 1.0
	v_rcp_f32_e32 v19, v18
	v_mul_f32_e32 v15, v44, v15
	v_fmac_f32_e32 v15, v14, v17
	v_mul_f32_e32 v14, v14, v16
	v_fma_f32 v16, -v18, v19, 1.0
	v_fmac_f32_e32 v19, v16, v19
	v_div_scale_f32 v16, vcc, 1.0, v13, 1.0
	v_mul_f32_e32 v17, v16, v19
	v_fma_f32 v20, -v18, v17, v16
	v_fmac_f32_e32 v17, v20, v19
	v_fma_f32 v16, -v18, v17, v16
	v_div_fmas_f32 v16, v16, v19, v17
	v_max_f32_e32 v17, v82, v82
	v_max_f32_e32 v17, 0, v17
	v_mul_f32_e32 v18, 0x4f800000, v17
	v_cmp_gt_f32_e32 vcc, s10, v17
	v_div_fixup_f32 v13, v16, v13, 1.0
	v_exp_f32_e32 v4, v4
	v_cndmask_b32_e32 v17, v17, v18, vcc
	v_sqrt_f32_e32 v18, v17
	v_mul_f32_e32 v2, 0x3fb8aa3b, v2
	v_exp_f32_e32 v2, v2
	v_add_u32_e32 v16, -1, v18
	v_fma_f32 v19, -v16, v18, v17
	v_cmp_ge_f32_e64 s[0:1], 0, v19
	v_add_u32_e32 v19, 1, v18
	s_nop 0
	v_cndmask_b32_e64 v16, v18, v16, s[0:1]
	v_fma_f32 v18, -v19, v18, v17
	v_cmp_lt_f32_e64 s[0:1], 0, v18
	s_nop 1
	v_cndmask_b32_e64 v16, v16, v19, s[0:1]
	v_mul_f32_e32 v18, 0x37800000, v16
	v_cndmask_b32_e32 v16, v16, v18, vcc
	v_cmp_class_f32_e32 vcc, v17, v58
	s_nop 1
	v_cndmask_b32_e32 v16, v16, v17, vcc
	v_mul_f32_e32 v13, v13, v16
	v_div_scale_f32 v16, s[0:1], v11, v11, 1.0
	v_rcp_f32_e32 v17, v16
	v_mul_f32_e32 v13, v43, v13
	v_fmac_f32_e32 v13, v12, v15
	v_mul_f32_e32 v12, v12, v14
	v_fma_f32 v14, -v16, v17, 1.0
	v_fmac_f32_e32 v17, v14, v17
	v_div_scale_f32 v14, vcc, 1.0, v11, 1.0
	v_mul_f32_e32 v15, v14, v17
	v_fma_f32 v18, -v16, v15, v14
	v_fmac_f32_e32 v15, v18, v17
	v_fma_f32 v14, -v16, v15, v14
	v_div_fmas_f32 v14, v14, v17, v15
	v_max_f32_e32 v15, v83, v83
	v_max_f32_e32 v15, 0, v15
	v_mul_f32_e32 v16, 0x4f800000, v15
	v_cmp_gt_f32_e32 vcc, s10, v15
	v_div_fixup_f32 v11, v14, v11, 1.0
	s_nop 0
	v_cndmask_b32_e32 v15, v15, v16, vcc
	v_sqrt_f32_e32 v16, v15
	s_nop 0
	v_add_u32_e32 v14, -1, v16
	v_fma_f32 v17, -v14, v16, v15
	v_cmp_ge_f32_e64 s[0:1], 0, v17
	v_add_u32_e32 v17, 1, v16
	s_nop 0
	v_cndmask_b32_e64 v14, v16, v14, s[0:1]
	v_fma_f32 v16, -v17, v16, v15
	v_cmp_lt_f32_e64 s[0:1], 0, v16
	s_nop 1
	v_cndmask_b32_e64 v14, v14, v17, s[0:1]
	v_mul_f32_e32 v16, 0x37800000, v14
	v_cndmask_b32_e32 v14, v14, v16, vcc
	v_cmp_class_f32_e32 vcc, v15, v58
	s_nop 1
	v_cndmask_b32_e32 v14, v14, v15, vcc
	v_mul_f32_e32 v11, v11, v14
	v_div_scale_f32 v14, s[0:1], v9, v9, 1.0
	v_rcp_f32_e32 v15, v14
	v_mul_f32_e32 v11, v42, v11
	v_fmac_f32_e32 v11, v10, v13
	v_mul_f32_e32 v10, v10, v12
	v_fma_f32 v12, -v14, v15, 1.0
	v_fmac_f32_e32 v15, v12, v15
	v_div_scale_f32 v12, vcc, 1.0, v9, 1.0
	v_mul_f32_e32 v13, v12, v15
	v_fma_f32 v16, -v14, v13, v12
	v_fmac_f32_e32 v13, v16, v15
	v_fma_f32 v12, -v14, v13, v12
	v_div_fmas_f32 v12, v12, v15, v13
	v_max_f32_e32 v13, v85, v85
	v_max_f32_e32 v13, 0, v13
	v_mul_f32_e32 v14, 0x4f800000, v13
	v_cmp_gt_f32_e32 vcc, s10, v13
	v_div_fixup_f32 v9, v12, v9, 1.0
	s_nop 0
	v_cndmask_b32_e32 v13, v13, v14, vcc
	v_sqrt_f32_e32 v14, v13
	s_nop 0
	v_add_u32_e32 v12, -1, v14
	v_fma_f32 v15, -v12, v14, v13
	v_cmp_ge_f32_e64 s[0:1], 0, v15
	v_add_u32_e32 v15, 1, v14
	s_nop 0
	v_cndmask_b32_e64 v12, v14, v12, s[0:1]
	v_fma_f32 v14, -v15, v14, v13
	v_cmp_lt_f32_e64 s[0:1], 0, v14
	s_nop 1
	v_cndmask_b32_e64 v12, v12, v15, s[0:1]
	v_mul_f32_e32 v14, 0x37800000, v12
	v_cndmask_b32_e32 v12, v12, v14, vcc
	v_cmp_class_f32_e32 vcc, v13, v58
	s_nop 1
	v_cndmask_b32_e32 v12, v12, v13, vcc
	v_mul_f32_e32 v9, v9, v12
	v_div_scale_f32 v12, s[0:1], v7, v7, 1.0
	v_rcp_f32_e32 v13, v12
	v_mul_f32_e32 v9, v41, v9
	v_fmac_f32_e32 v9, v8, v11
	v_mul_f32_e32 v8, v8, v10
	v_fma_f32 v10, -v12, v13, 1.0
	v_fmac_f32_e32 v13, v10, v13
	v_div_scale_f32 v10, vcc, 1.0, v7, 1.0
	v_mul_f32_e32 v11, v10, v13
	v_fma_f32 v14, -v12, v11, v10
	v_fmac_f32_e32 v11, v14, v13
	v_fma_f32 v10, -v12, v11, v10
	v_div_fmas_f32 v10, v10, v13, v11
	v_max_f32_e32 v11, v86, v86
	v_max_f32_e32 v11, 0, v11
	v_mul_f32_e32 v12, 0x4f800000, v11
;     ...
;     const float bb = sqrtf(fmaxf(em, 0.f)) * ig * xc[i];
;     aA[i] = a; aX[i] = bb;
;     H = a * H + bb;
;     P *= a;
;   }
;   segP[tq * 64 + ch] = P;
;   segH[tq * 64 + ch] = H;
;   __syncthreads();
;   if (pass == 1) {
;     if (tq == 3) {
;       float Pt = 1.f, Ht = 0.f;
; #pragma unroll
;       for (int s = 0; s < 4; ++s) { Ht = segP[s * 64 + ch] * Ht + segH[s * 64 + ch]; Pt *= segP[s * 64 + ch]; }
;       float2 o; o.x = Pt; o.y = Ht;
;       *(float2*)(p.lrusum + ((size_t)(b * 64 + chunk) * 512 + chg) * 2) = o;
;     }
	v_cmp_gt_f32_e32 vcc, s10, v11
	v_div_fixup_f32 v7, v10, v7, 1.0
	s_nop 0
	v_cndmask_b32_e32 v11, v11, v12, vcc
	v_sqrt_f32_e32 v12, v11
	s_nop 0
	v_add_u32_e32 v10, -1, v12
	v_fma_f32 v13, -v10, v12, v11
	v_cmp_ge_f32_e64 s[0:1], 0, v13
	v_add_u32_e32 v13, 1, v12
	s_nop 0
	v_cndmask_b32_e64 v10, v12, v10, s[0:1]
	v_fma_f32 v12, -v13, v12, v11
	v_cmp_lt_f32_e64 s[0:1], 0, v12
	s_nop 1
	v_cndmask_b32_e64 v10, v10, v13, s[0:1]
	v_mul_f32_e32 v12, 0x37800000, v10
	v_cndmask_b32_e32 v10, v10, v12, vcc
	v_cmp_class_f32_e32 vcc, v11, v58
	s_nop 1
	v_cndmask_b32_e32 v10, v10, v11, vcc
	v_mul_f32_e32 v7, v7, v10
	v_div_scale_f32 v10, s[0:1], v5, v5, 1.0
	v_rcp_f32_e32 v11, v10
	v_mul_f32_e32 v7, v40, v7
	v_fmac_f32_e32 v7, v6, v9
	v_mul_f32_e32 v6, v6, v8
	v_fma_f32 v8, -v10, v11, 1.0
	v_fmac_f32_e32 v11, v8, v11
	v_div_scale_f32 v8, vcc, 1.0, v5, 1.0
	v_mul_f32_e32 v9, v8, v11
	v_fma_f32 v12, -v10, v9, v8
	v_fmac_f32_e32 v9, v12, v11
	v_fma_f32 v8, -v10, v9, v8
	v_div_fmas_f32 v8, v8, v11, v9
	v_max_f32_e32 v9, v87, v87
	v_max_f32_e32 v9, 0, v9
	v_mul_f32_e32 v10, 0x4f800000, v9
	v_cmp_gt_f32_e32 vcc, s10, v9
	v_div_fixup_f32 v5, v8, v5, 1.0
	s_nop 0
	v_cndmask_b32_e32 v9, v9, v10, vcc
	v_sqrt_f32_e32 v10, v9
	s_nop 0
	v_add_u32_e32 v8, -1, v10
	v_fma_f32 v11, -v8, v10, v9
	v_cmp_ge_f32_e64 s[0:1], 0, v11
	v_add_u32_e32 v11, 1, v10
	s_nop 0
	v_cndmask_b32_e64 v8, v10, v8, s[0:1]
	v_fma_f32 v10, -v11, v10, v9
	v_cmp_lt_f32_e64 s[0:1], 0, v10
	s_nop 1
	v_cndmask_b32_e64 v8, v8, v11, s[0:1]
	v_mul_f32_e32 v10, 0x37800000, v8
	v_cndmask_b32_e32 v8, v8, v10, vcc
	v_cmp_class_f32_e32 vcc, v9, v58
	s_nop 1
	v_cndmask_b32_e32 v8, v8, v9, vcc
	v_mul_f32_e32 v5, v5, v8
	v_div_scale_f32 v8, s[0:1], v3, v3, 1.0
	v_rcp_f32_e32 v9, v8
	v_mul_f32_e32 v5, v39, v5
	v_fmac_f32_e32 v5, v4, v7
	v_mul_f32_e32 v4, v4, v6
	v_fma_f32 v6, -v8, v9, 1.0
	v_fmac_f32_e32 v9, v6, v9
	v_div_scale_f32 v6, vcc, 1.0, v3, 1.0
	v_mul_f32_e32 v7, v6, v9
	v_fma_f32 v10, -v8, v7, v6
	v_fmac_f32_e32 v7, v10, v9
	v_fma_f32 v6, -v8, v7, v6
	v_div_fmas_f32 v6, v6, v9, v7
	v_max_f32_e32 v7, v73, v73
	v_max_f32_e32 v7, 0, v7
	v_mul_f32_e32 v8, 0x4f800000, v7
	v_cmp_gt_f32_e32 vcc, s10, v7
	v_div_fixup_f32 v3, v6, v3, 1.0
	s_nop 0
	v_cndmask_b32_e32 v7, v7, v8, vcc
	v_sqrt_f32_e32 v8, v7
	s_nop 0
	v_add_u32_e32 v6, -1, v8
	v_fma_f32 v9, -v6, v8, v7
	v_cmp_ge_f32_e64 s[0:1], 0, v9
	v_add_u32_e32 v9, 1, v8
	s_nop 0
	v_cndmask_b32_e64 v6, v8, v6, s[0:1]
	v_fma_f32 v8, -v9, v8, v7
	v_cmp_lt_f32_e64 s[0:1], 0, v8
	s_nop 1
	v_cndmask_b32_e64 v6, v6, v9, s[0:1]
	v_mul_f32_e32 v8, 0x37800000, v6
	v_cndmask_b32_e32 v6, v6, v8, vcc
	v_cmp_class_f32_e32 vcc, v7, v58
	s_nop 1
	v_cndmask_b32_e32 v6, v6, v7, vcc
	v_mul_f32_e32 v3, v3, v6
	v_mul_f32_e32 v3, v33, v3
	v_fmac_f32_e32 v3, v2, v5
	v_mul_f32_e32 v2, v2, v4
	v_cmp_eq_u32_e32 vcc, 3, v37
	ds_write2st64_b32 v35, v2, v3 offset0:236 offset1:240
	s_waitcnt lgkmcnt(0)
	s_barrier
	s_and_saveexec_b64 s[0:1], vcc
	s_xor_b64 s[0:1], exec, s[0:1]
	s_cbranch_execz .LBB0_412
	ds_read2st64_b32 v[2:3], v0 offset0:238 offset1:240
	ds_read2st64_b32 v[4:5], v0 offset0:236 offset1:237
	ds_read2st64_b32 v[6:7], v0 offset0:241 offset1:242
	ds_read2st64_b32 v[8:9], v35 offset0:236 offset1:240
	s_lshl_b32 s9, s9, 6
	s_mov_b32 s11, s25
	s_waitcnt lgkmcnt(2)
	v_fma_f32 v0, 0, v4, v3
	s_waitcnt lgkmcnt(1)
	v_fma_f32 v0, v0, v5, v6
	s_or_b32 s10, s9, s8
	v_readlane_b32 s36, v251, 34
	v_mul_f32_e32 v6, v4, v5
	v_fmac_f32_e32 v7, v0, v2
	s_lshl_b64 s[8:9], s[10:11], 12
	v_readlane_b32 s40, v251, 38
	s_waitcnt lgkmcnt(0)
	v_mov_b32_e32 v3, v8
	v_readlane_b32 s41, v251, 39
	s_add_u32 s8, s40, s8
	v_mul_f32_e32 v4, v6, v2
	v_pk_fma_f32 v[2:3], v[6:7], v[2:3], v[8:9]
	s_addc_u32 s9, s41, s9
	v_lshlrev_b32_e32 v0, 3, v36
	v_mul_f32_e32 v4, v4, v8
	v_mov_b32_e32 v5, v3
	v_readlane_b32 s37, v251, 35
	v_readlane_b32 s38, v251, 36
	v_readlane_b32 s39, v251, 37
	v_readlane_b32 s42, v251, 40
	v_readlane_b32 s43, v251, 41
	v_readlane_b32 s44, v251, 42
	v_readlane_b32 s45, v251, 43
	v_readlane_b32 s46, v251, 44
	v_readlane_b32 s47, v251, 45
	v_readlane_b32 s48, v251, 46
	v_readlane_b32 s49, v251, 47
	v_readlane_b32 s50, v251, 48
	v_readlane_b32 s51, v251, 49
	global_store_dwordx2 v0, v[4:5], s[8:9]

; DI float bf2f(u16 v) { return (float)__builtin_bit_cast(_Float16, v); }
; DI u16 f2bf(float x) { return (u16)(pk2(x, 0.f) & 0xffffu); }
; DI int TID() { int t = threadIdx.x; asm volatile("" : "+v"(t)); return t; }
;     ...
;   const int tid = TID(), ch = tid & 63, tq = tid >> 6;
;   const int chg = n * 64 + ch;
;   const int t0 = chunk * 64 + tq * 16;
;   const u16* zb = p.z + (size_t)b * S_ * ZS + XB + chg;
;   const float* cw = p.conv_w + l * 4 * 512;
;   const float w0 = cw[chg], w1 = cw[512 + chg], w2 = cw[1024 + chg], w3 = cw[1536 + chg];
;   const float cb = p.conv_b[l * 512 + chg];
;   float xm3 = (t0 >= 3) ? bf2f(zb[(size_t)(t0 - 3) * ZS]) : 0.f;
;   float xm2 = (t0 >= 2) ? bf2f(zb[(size_t)(t0 - 2) * ZS]) : 0.f;
;   float xm1 = (t0 >= 1) ? bf2f(zb[(size_t)(t0 - 1) * ZS]) : 0.f;
;   float xc[16];
; #pragma unroll
;   for (int i = 0; i < 16; ++i) {
;     const float cur = bf2f(zb[(size_t)(t0 + i) * ZS]);
;     xc[i] = cb + w0 * xm3 + w1 * xm2 + w2 * xm1 + w3 * cur;
;     xm3 = xm2; xm2 = xm1; xm1 = cur;
;     X[(tq * 16 + i) * 72 + ch] = f2bf(xc[i]);
;   }
.LBB0_913:
	s_and_b64 vcc, exec, s[0:1]
	s_cbranch_vccz .LBB0_772
	v_mov_b32_e32 v38, v209
	v_readlane_b32 s0, v254, 11
	v_and_b32_e32 v40, 63, v38
	v_or_b32_e32 v37, s6, v40
	v_lshlrev_b32_e32 v0, 2, v37
	v_readlane_b32 s1, v254, 12
	v_readlane_b32 s36, v251, 2
	v_readlane_b32 s50, v251, 16
	v_lshl_add_u64 v[2:3], s[0:1], 0, v[0:1]
	v_add_co_u32_e32 v2, vcc, 0x1000, v2
	v_readlane_b32 s51, v251, 17
	s_nop 0
	v_addc_co_u32_e32 v3, vcc, 0, v3, vcc
	global_load_dword v6, v0, s[0:1]
	global_load_dword v7, v0, s[0:1] offset:2048
	global_load_dword v8, v[2:3], off
	global_load_dword v42, v[2:3], off offset:2048
	v_readlane_b32 s0, v254, 9
	s_ashr_i32 s2, s5, 9
	v_readlane_b32 s80, v253, 12
	v_or_b32_e32 v0, s0, v37
	v_lshl_add_u64 v[2:3], v[0:1], 2, s[50:51]
	global_load_dword v9, v[2:3], off
	v_readlane_b32 s1, v254, 10
	s_bfe_u32 s3, s5, 0x60003
	s_mul_i32 s0, s2, 0x3300000
	v_readlane_b32 s86, v253, 18
	v_ashrrev_i32_e32 v41, 6, v38
	s_mul_hi_i32 s1, s2, 0x3300000
	v_readlane_b32 s87, v253, 19
	s_add_u32 s0, s86, s0
	v_lshlrev_b32_e32 v74, 4, v41
	s_addc_u32 s1, s87, s1
	v_lshlrev_b32_e32 v34, 1, v37
	v_mov_b32_e32 v35, v1
	s_waitcnt vmcnt(36)
	v_lshl_add_u32 v36, s3, 6, v74
	v_lshl_add_u64 v[2:3], s[0:1], 0, v[34:35]
	v_lshl_add_u64 v[2:3], v[2:3], 0, s[34:35]
	v_cmp_lt_i32_e32 vcc, 2, v36
	v_mov_b32_e32 v4, 0
	v_mov_b32_e32 v5, 0
	v_readlane_b32 s37, v251, 3
	v_readlane_b32 s38, v251, 4
	v_readlane_b32 s39, v251, 5
	v_readlane_b32 s40, v251, 6
	v_readlane_b32 s41, v251, 7
	v_readlane_b32 s42, v251, 8
	v_readlane_b32 s43, v251, 9
	v_readlane_b32 s44, v251, 10
	v_readlane_b32 s45, v251, 11
	v_readlane_b32 s46, v251, 12
	v_readlane_b32 s47, v251, 13
	v_readlane_b32 s48, v251, 14
	v_readlane_b32 s49, v251, 15
	v_readlane_b32 s81, v253, 13
	v_readlane_b32 s82, v253, 14
	v_readlane_b32 s83, v253, 15
	v_readlane_b32 s84, v253, 16
	v_readlane_b32 s85, v253, 17
	v_readlane_b32 s88, v253, 20
	v_readlane_b32 s89, v253, 21
	v_readlane_b32 s90, v253, 22
	v_readlane_b32 s91, v253, 23
	v_readlane_b32 s92, v253, 24
	v_readlane_b32 s93, v253, 25
	v_readlane_b32 s94, v253, 26
	v_readlane_b32 s95, v253, 27
	s_and_saveexec_b64 s[0:1], vcc
	s_cbranch_execz .LBB0_916
	v_add_u32_e32 v5, -3, v36
	v_mad_u64_u32 v[10:11], s[6:7], v5, s75, v[2:3]
	global_load_ushort v5, v[10:11], off
.LBB0_916:
	s_or_b64 exec, exec, s[0:1]
	v_cmp_lt_i32_e32 vcc, 1, v36
	s_and_saveexec_b64 s[0:1], vcc
	s_cbranch_execz .LBB0_918
	v_add_u32_e32 v4, -2, v36
	v_mad_u64_u32 v[10:11], s[6:7], v4, s75, v[2:3]
	global_load_ushort v4, v[10:11], off
.LBB0_918:
	s_or_b64 exec, exec, s[0:1]
	v_cmp_lt_i32_e32 vcc, 0, v36
	v_mov_b32_e32 v10, 0
	s_and_saveexec_b64 s[0:1], vcc
	s_cbranch_execz .LBB0_920
	v_add_u32_e32 v10, -1, v36
	v_mad_u64_u32 v[10:11], s[6:7], v10, s75, v[2:3]
	global_load_ushort v10, v[10:11], off
.LBB0_920:
	s_or_b64 exec, exec, s[0:1]
	v_mad_i64_i32 v[12:13], s[0:1], v36, s75, v[2:3]
	v_or_b32_e32 v11, 1, v36
	global_load_ushort v43, v[12:13], off
	v_mad_i64_i32 v[12:13], s[0:1], v11, s75, v[2:3]
	v_or_b32_e32 v11, 2, v36
	global_load_ushort v44, v[12:13], off
	v_mad_i64_i32 v[12:13], s[0:1], v11, s75, v[2:3]
	v_or_b32_e32 v11, 3, v36
	global_load_ushort v45, v[12:13], off
	v_mad_i64_i32 v[12:13], s[0:1], v11, s75, v[2:3]
	v_or_b32_e32 v11, 4, v36
	global_load_ushort v46, v[12:13], off
	v_mad_i64_i32 v[12:13], s[0:1], v11, s75, v[2:3]
	global_load_ushort v47, v[12:13], off
	s_movk_i32 s0, 0x900
	v_lshlrev_b32_e32 v12, 1, v40
	s_waitcnt vmcnt(5)
	v_cvt_f32_f16_e32 v5, v5
	v_cvt_f32_f16_e32 v4, v4
	v_cvt_f32_f16_e32 v10, v10
	v_fma_f32 v48, v6, v5, v9
	v_mul_lo_u32 v5, v41, s0
	v_or_b32_e32 v13, 5, v36
	v_fma_f32 v11, v6, v4, v9
	v_fmac_f32_e32 v48, v7, v4
	v_or_b32_e32 v26, v12, v5
	v_mad_i64_i32 v[4:5], s[0:1], v13, s75, v[2:3]
	global_load_ushort v49, v[4:5], off
	v_or_b32_e32 v76, 1, v74
	v_or_b32_e32 v14, 6, v36
	v_mad_u64_u32 v[4:5], s[0:1], v76, s76, v[12:13]
	v_mad_i64_i32 v[12:13], s[0:1], v14, s75, v[2:3]
	global_load_ushort v53, v[12:13], off
	v_or_b32_e32 v15, 7, v36
	v_or_b32_e32 v16, 8, v36
	v_or_b32_e32 v17, 9, v36
	v_or_b32_e32 v18, 10, v36
	v_or_b32_e32 v20, 11, v36
	v_or_b32_e32 v22, 12, v36
	v_mad_i64_i32 v[12:13], s[0:1], v15, s75, v[2:3]
	v_mad_i64_i32 v[14:15], s[0:1], v16, s75, v[2:3]
	v_mad_i64_i32 v[16:17], s[0:1], v17, s75, v[2:3]
	v_mad_i64_i32 v[18:19], s[0:1], v18, s75, v[2:3]
	v_mad_i64_i32 v[20:21], s[0:1], v20, s75, v[2:3]
	v_mad_i64_i32 v[22:23], s[0:1], v22, s75, v[2:3]
	global_load_ushort v54, v[12:13], off
	global_load_ushort v55, v[14:15], off
	global_load_ushort v56, v[16:17], off
	global_load_ushort v50, v[18:19], off
	global_load_ushort v51, v[20:21], off
	global_load_ushort v52, v[22:23], off
	v_fma_f32 v24, v6, v10, v9
	v_fmac_f32_e32 v11, v7, v10
	v_fmac_f32_e32 v48, v8, v10
	v_or_b32_e32 v25, 13, v36
	v_ashrrev_i32_e32 v39, 31, v38
	v_ashrrev_i32_e32 v77, 2, v38
	v_lshrrev_b32_e32 v75, 5, v40
	v_lshlrev_b32_e32 v35, 2, v38
	s_movk_i32 s96, 0x2000
	s_movk_i32 s97, 0x3000
	s_waitcnt vmcnt(12)
	v_fma_mixlo_f16 v5, v42, v43, v48 op_sel_hi:[0,1,0]
	v_fma_mix_f32 v57, v8, v43, v11 op_sel_hi:[0,1,0]
	v_fma_mix_f32 v10, v7, v43, v24 op_sel_hi:[0,1,0]
	v_fma_mix_f32 v11, v6, v43, v9 op_sel_hi:[0,1,0]
	ds_write_b16 v26, v5
	s_waitcnt vmcnt(11)
	v_fma_mixlo_f16 v5, v42, v44, v57 op_sel_hi:[0,1,0]
	v_fma_mix_f32 v58, v8, v44, v10 op_sel_hi:[0,1,0]
	v_fma_mix_f32 v10, v7, v44, v11 op_sel_hi:[0,1,0]
	v_fma_mix_f32 v11, v6, v44, v9 op_sel_hi:[0,1,0]
	ds_write_b16 v4, v5
	s_waitcnt vmcnt(10)
	v_fma_mixlo_f16 v5, v42, v45, v58 op_sel_hi:[0,1,0]
	v_fma_mix_f32 v59, v8, v45, v10 op_sel_hi:[0,1,0]
	v_fma_mix_f32 v10, v7, v45, v11 op_sel_hi:[0,1,0]
	v_fma_mix_f32 v12, v6, v45, v9 op_sel_hi:[0,1,0]
	ds_write_b16 v4, v5 offset:144
	s_waitcnt vmcnt(9)
; DI unsigned pk2(float a, float b) { f2_t v = {a, b}; bf2_t r = __builtin_convertvector(v, bf2_t); return __builtin_bit_cast(unsigned, r); }
; DI float bf2f(u16 v) { return (float)__builtin_bit_cast(_Float16, v); }
; DI u16 f2bf(float x) { return (u16)(pk2(x, 0.f) & 0xffffu); }
;     ...
; #pragma unroll
;   for (int i = 0; i < 16; ++i) {
;     const float cur = bf2f(zb[(size_t)(t0 + i) * ZS]);
;     xc[i] = cb + w0 * xm3 + w1 * xm2 + w2 * xm1 + w3 * cur;
;     xm3 = xm2; xm2 = xm1; xm1 = cur;
;     X[(tq * 16 + i) * 72 + ch] = f2bf(xc[i]);
;   }
;   {
;     const float4* ga = (const float4*)(p.w_rg_a + ((size_t)(l * 8 + n) * 64) * 64);
;     const float4* gx = (const float4*)(p.w_rg_x + ((size_t)(l * 8 + n) * 64) * 64);
; #pragma unroll
;     for (int i = 0; i < 4; ++i) {
;       const int idx = tid + 256 * i, d = idx >> 4, e = (idx & 15) * 4;
;       const float4 va = ga[idx], vx = gx[idx];
;       uint2 oa, ox;
;       oa.x = pk2(va.x, va.y); oa.y = pk2(va.z, va.w);
;       ox.x = pk2(vx.x, vx.y); ox.y = pk2(vx.z, vx.w);
;       *(uint2*)(Wa + d * 72 + e) = oa;
;       *(uint2*)(Wx + d * 72 + e) = ox;
;     }
;   }
;   __syncthreads();
	v_fma_mixlo_f16 v5, v42, v46, v59 op_sel_hi:[0,1,0]
	v_fma_mix_f32 v60, v8, v46, v10 op_sel_hi:[0,1,0]
	v_fma_mix_f32 v11, v7, v46, v12 op_sel_hi:[0,1,0]
	ds_write_b16 v4, v5 offset:288
	s_waitcnt vmcnt(8)
	v_fma_mixlo_f16 v5, v42, v47, v60 op_sel_hi:[0,1,0]
	v_fma_mix_f32 v61, v8, v47, v11 op_sel_hi:[0,1,0]
	ds_write_b16 v4, v5 offset:432
	v_mad_i64_i32 v[10:11], s[0:1], v25, s75, v[2:3]
	v_or_b32_e32 v5, 14, v36
	global_load_ushort v62, v[10:11], off
	v_mad_i64_i32 v[10:11], s[0:1], v5, s75, v[2:3]
	v_or_b32_e32 v5, 15, v36
	v_mad_i64_i32 v[2:3], s[0:1], v5, s75, v[2:3]
	s_lshl_b32 s0, s4, 12
	v_readlane_b32 s1, v254, 13
	s_or_b32 s18, s0, s1
	global_load_ushort v63, v[10:11], off
	global_load_ushort v64, v[2:3], off
	s_lshl_b64 s[0:1], s[18:19], 2
	s_add_u32 s4, s60, s0
	s_addc_u32 s5, s61, s1
	s_add_u32 s0, s64, s0
	s_addc_u32 s1, s65, s1
	v_lshlrev_b64 v[2:3], 4, v[38:39]
	v_lshl_add_u64 v[66:67], s[4:5], 0, v[2:3]
	v_lshl_add_u64 v[2:3], s[0:1], 0, v[2:3]
	s_movk_i32 s0, 0x2000
	v_add_co_u32_e32 v26, vcc, s0, v66
	global_load_dwordx4 v[10:13], v[66:67], off
	s_nop 0
	v_addc_co_u32_e32 v27, vcc, 0, v67, vcc
	global_load_dwordx4 v[14:17], v[2:3], off
	v_add_co_u32_e32 v30, vcc, s0, v2
	s_movk_i32 s0, 0x3000
	s_nop 0
	v_addc_co_u32_e32 v31, vcc, 0, v3, vcc
	global_load_dwordx4 v[18:21], v[26:27], off offset:-4096
	global_load_dwordx4 v[22:25], v[30:31], off offset:-4096
	v_add_co_u32_e32 v66, vcc, s0, v66
	s_waitcnt vmcnt(14)
	v_fma_mixlo_f16 v5, v42, v49, v61 op_sel_hi:[0,1,0]
	v_addc_co_u32_e32 v67, vcc, 0, v67, vcc
	ds_write_b16 v4, v5 offset:576
	v_add_co_u32_e32 v2, vcc, s0, v2
	global_load_dwordx4 v[26:29], v[26:27], off
	s_nop 0
	global_load_dwordx4 v[30:33], v[30:31], off
	v_addc_co_u32_e32 v3, vcc, 0, v3, vcc
	global_load_dwordx4 v[78:81], v[66:67], off
	global_load_dwordx4 v[82:85], v[2:3], off
	v_fma_mix_f32 v2, v6, v47, v9 op_sel_hi:[0,1,0]
	v_fma_mix_f32 v2, v7, v49, v2 op_sel_hi:[0,1,0]
	s_waitcnt vmcnt(17)
	v_fma_mix_f32 v65, v8, v53, v2 op_sel_hi:[0,1,0]
	s_waitcnt vmcnt(16)
	v_fma_mixlo_f16 v2, v42, v54, v65 op_sel_hi:[0,1,0]
	ds_write_b16 v4, v2 offset:864
	v_fma_mix_f32 v2, v6, v49, v9 op_sel_hi:[0,1,0]
	v_fma_mix_f32 v2, v7, v53, v2 op_sel_hi:[0,1,0]
	v_fma_mix_f32 v67, v8, v54, v2 op_sel_hi:[0,1,0]
	s_waitcnt vmcnt(15)
	v_fma_mixlo_f16 v2, v42, v55, v67 op_sel_hi:[0,1,0]
	ds_write_b16 v4, v2 offset:1008
	v_fma_mix_f32 v2, v6, v53, v9 op_sel_hi:[0,1,0]
	v_fma_mix_f32 v2, v7, v54, v2 op_sel_hi:[0,1,0]
	v_fma_mix_f32 v69, v8, v55, v2 op_sel_hi:[0,1,0]
	s_waitcnt vmcnt(14)
	v_fma_mixlo_f16 v2, v42, v56, v69 op_sel_hi:[0,1,0]
	ds_write_b16 v4, v2 offset:1152
	v_fma_mix_f32 v2, v6, v54, v9 op_sel_hi:[0,1,0]
	v_fma_mix_f32 v2, v7, v55, v2 op_sel_hi:[0,1,0]
	v_fma_mix_f32 v66, v8, v56, v2 op_sel_hi:[0,1,0]
	s_waitcnt vmcnt(13)
	v_fma_mixlo_f16 v2, v42, v50, v66 op_sel_hi:[0,1,0]
	ds_write_b16 v4, v2 offset:1296
	v_fma_mix_f32 v2, v6, v55, v9 op_sel_hi:[0,1,0]
	v_fma_mix_f32 v2, v7, v56, v2 op_sel_hi:[0,1,0]
	v_fma_mix_f32 v68, v8, v50, v2 op_sel_hi:[0,1,0]
	s_waitcnt vmcnt(12)
	v_fma_mixlo_f16 v2, v42, v51, v68 op_sel_hi:[0,1,0]
	ds_write_b16 v4, v2 offset:1440
	v_fma_mix_f32 v2, v6, v56, v9 op_sel_hi:[0,1,0]
	v_fma_mix_f32 v2, v7, v50, v2 op_sel_hi:[0,1,0]
	v_fma_mix_f32 v70, v8, v51, v2 op_sel_hi:[0,1,0]
	s_waitcnt vmcnt(11)
	v_fma_mixlo_f16 v2, v42, v52, v70 op_sel_hi:[0,1,0]
	ds_write_b16 v4, v2 offset:1584
	v_fma_mix_f32 v2, v6, v50, v9 op_sel_hi:[0,1,0]
	v_fma_mix_f32 v2, v7, v51, v2 op_sel_hi:[0,1,0]
	v_fma_mix_f32 v71, v8, v52, v2 op_sel_hi:[0,1,0]
	v_fma_mix_f32 v5, v6, v46, v9 op_sel_hi:[0,1,0]
	s_waitcnt vmcnt(10)
	v_fma_mixlo_f16 v2, v42, v62, v71 op_sel_hi:[0,1,0]
	ds_write_b16 v4, v2 offset:1728
	v_fma_mix_f32 v2, v6, v51, v9 op_sel_hi:[0,1,0]
	v_fma_mix_f32 v2, v7, v52, v2 op_sel_hi:[0,1,0]
	v_fma_mix_f32 v72, v8, v62, v2 op_sel_hi:[0,1,0]
	v_fma_mix_f32 v5, v7, v47, v5 op_sel_hi:[0,1,0]
	v_fma_mix_f32 v39, v8, v49, v5 op_sel_hi:[0,1,0]
	v_lshrrev_b32_e32 v3, 4, v38
	v_fma_mixlo_f16 v5, v42, v53, v39 op_sel_hi:[0,1,0]
	s_waitcnt vmcnt(9)
	v_fma_mixlo_f16 v2, v42, v63, v72 op_sel_hi:[0,1,0]
	ds_write_b16 v4, v2 offset:1872
	v_fma_mix_f32 v2, v6, v52, v9 op_sel_hi:[0,1,0]
	v_fma_mix_f32 v2, v7, v62, v2 op_sel_hi:[0,1,0]
	v_fma_mix_f32 v73, v8, v63, v2 op_sel_hi:[0,1,0]
	s_waitcnt vmcnt(8)
	v_fma_mixlo_f16 v2, v42, v64, v73 op_sel_hi:[0,1,0]
	ds_write_b16 v4, v2 offset:2016
	v_lshlrev_b32_e32 v2, 3, v38
	v_and_b32_e32 v2, 0x78, v2
	v_mad_u64_u32 v[8:9], s[0:1], v3, s76, v[2:3]
	v_add_u32_e32 v3, 0x100, v38
	ds_write_b16 v4, v5 offset:720
	s_waitcnt vmcnt(7)
	v_cvt_pk_f16_f32 v4, v10, v11
	v_cvt_pk_f16_f32 v5, v12, v13
	v_lshrrev_b32_e32 v3, 4, v3
	s_waitcnt vmcnt(6)
	v_cvt_pk_f16_f32 v6, v14, v15
	v_cvt_pk_f16_f32 v7, v16, v17
	ds_write2st64_b64 v8, v[4:5], v[6:7] offset0:18 offset1:36
	v_mad_u64_u32 v[8:9], s[0:1], v3, s76, v[2:3]
	v_add_u32_e32 v3, 0x200, v38
	s_waitcnt vmcnt(5)
	v_cvt_pk_f16_f32 v4, v18, v19
	v_cvt_pk_f16_f32 v5, v20, v21
	s_waitcnt vmcnt(4)
	v_cvt_pk_f16_f32 v6, v22, v23
	v_cvt_pk_f16_f32 v7, v24, v25
	v_lshrrev_b32_e32 v3, 4, v3
	ds_write2st64_b64 v8, v[4:5], v[6:7] offset0:18 offset1:36
	v_mad_u64_u32 v[8:9], s[0:1], v3, s76, v[2:3]
	v_add_u32_e32 v3, 0x300, v38
	v_lshrrev_b32_e32 v3, 4, v3
	s_waitcnt vmcnt(3)
	v_cvt_pk_f16_f32 v4, v26, v27
	v_cvt_pk_f16_f32 v5, v28, v29
	s_waitcnt vmcnt(2)
	v_cvt_pk_f16_f32 v6, v30, v31
	v_cvt_pk_f16_f32 v7, v32, v33
	v_mad_u64_u32 v[2:3], s[0:1], v3, s76, v[2:3]
	ds_write2st64_b64 v8, v[4:5], v[6:7] offset0:18 offset1:36
	s_waitcnt vmcnt(1)
	v_cvt_pk_f16_f32 v4, v78, v79
	v_cvt_pk_f16_f32 v5, v80, v81
	s_waitcnt vmcnt(0)
	v_cvt_pk_f16_f32 v6, v82, v83
	v_cvt_pk_f16_f32 v7, v84, v85
	s_movk_i32 s0, 0xffe0
	ds_write2st64_b64 v2, v[4:5], v[6:7] offset0:18 offset1:36
	v_bfi_b32 v4, s0, v77, v38
	v_mul_lo_u32 v4, v4, s76
	v_lshl_add_u32 v86, v75, 4, v4
	s_waitcnt lgkmcnt(0)
	s_barrier
; #define MFMA(a, b, c) __builtin_amdgcn_mfma_f32_32x32x16_f16(__builtin_bit_cast(h16x8, (a)), __builtin_bit_cast(h16x8, (b)), (c), 0, 0, 0)
;     ...
;   {
;     const int lane = tid & 63, r = lane & 31, h = lane >> 5, mt = tq >> 1, nt = tq & 1;
;     const int q4 = (lane & 15) >> 2, p4 = lane & 3, blk = (lane >> 4) & 1;
;     f32x16 accA, accX;
; #pragma unroll
;     for (int i = 0; i < 16; ++i) { accA[i] = 0.f; accX[i] = 0.f; }
; #pragma unroll
;     for (int ks = 0; ks < 4; ++ks) {
;       const bf16x8 af = *(const bf16x8*)(X + (mt * 32 + r) * 72 + ks * 16 + 8 * h);
;       const int woff = (ks * 16 + 8 * h + q4) * 72 + nt * 32 + 16 * blk + 4 * p4;
;       const s16x4 alo = __builtin_amdgcn_ds_read_tr16_b64_v4i16((__attribute__((address_space(3))) s16x4*)(Wa + woff));
;       const s16x4 ahi = __builtin_amdgcn_ds_read_tr16_b64_v4i16((__attribute__((address_space(3))) s16x4*)(Wa + woff + 4 * 72));
;       const s16x4 xlo = __builtin_amdgcn_ds_read_tr16_b64_v4i16((__attribute__((address_space(3))) s16x4*)(Wx + woff));
;       const s16x4 xhi = __builtin_amdgcn_ds_read_tr16_b64_v4i16((__attribute__((address_space(3))) s16x4*)(Wx + woff + 4 * 72));
;       const bf16x8 ba_ = __builtin_shufflevector(alo, ahi, 0, 1, 2, 3, 4, 5, 6, 7);
;       const bf16x8 bx_ = __builtin_shufflevector(xlo, xhi, 0, 1, 2, 3, 4, 5, 6, 7);
;       accA = MFMA(af, ba_, accA);
;       accX = MFMA(af, bx_, accX);
;     }
; #pragma unroll
;     for (int i = 0; i < 16; ++i) {
;       const int t = mt * 32 + (i & 3) + 8 * (i >> 2) + 4 * h;
;       preA[t * 64 + nt * 32 + r] = accA[i];
;       preX[t * 64 + nt * 32 + r] = accX[i];
;     }
;   }
;   __syncthreads();
;   float aA[16], aX[16];
; #pragma unroll
;   for (int i = 0; i < 16; ++i) { aA[i] = preA[(tq * 16 + i) * 64 + ch]; aX[i] = preX[(tq * 16 + i) * 64 + ch]; }
;   const float ba = p.b_rg_a[l * 512 + chg], bx = p.b_rg_x[l * 512 + chg], lam = p.lru_lambda[l * 512 + chg];
;   const float sp = fmaxf(-lam, 0.f) + __logf(1.f + __expf(-fabsf(lam)));
;   float P = 1.f, H = 0.f;
; #pragma unroll
;   for (int i = 0; i < 16; ++i) {
;     const float rr = sigmoidf_(aA[i] + ba), ig = sigmoidf_(aX[i] + bx);
;     const float la = -8.f * rr * sp;
;     const float a = __expf(la);
;     const float x2 = 2.f * la;
;     const float em = (x2 > -0.1f) ? -x2 * (1.f + x2 * (0.5f + x2 * (0.16666667f + x2 * 0.041666667f))) : 1.f - __expf(x2);
	v_bfe_u32 v2, v38, 2, 2
	v_lshlrev_b32_e32 v4, 5, v41
	ds_read_b128 v[18:21], v86
	v_and_b32_e32 v3, 16, v38
	v_lshl_or_b32 v2, v75, 3, v2
	v_and_b32_e32 v87, 32, v4
	v_and_b32_e32 v4, 12, v35
	v_or3_b32 v3, v4, v3, v87
	v_mul_u32_u24_e32 v2, 0x48, v2
	v_add_lshl_u32 v88, v2, v3, 1
	ds_read_b64_tr_b16 v[2:3], v88 offset:9216
	ds_read_b64_tr_b16 v[4:5], v88 offset:9792
	s_waitcnt lgkmcnt(0)
	v_mfma_f32_32x32x16_f16 v[2:17], v[18:21], v[2:5], 0
	ds_read_b64_tr_b16 v[22:23], v88 offset:18432
	ds_read_b64_tr_b16 v[24:25], v88 offset:19008
	ds_read_b128 v[78:81], v86 offset:32
	ds_read_b64_tr_b16 v[82:83], v88 offset:11520
	ds_read_b64_tr_b16 v[84:85], v88 offset:12096
	v_and_b32_e32 v77, 0xffffffe0, v77
	v_lshlrev_b32_e32 v77, 6, v77
	v_and_b32_e32 v38, 31, v38
	v_lshl_or_b32 v75, v75, 8, v77
	v_or3_b32 v38, v75, v87, v38
	s_waitcnt lgkmcnt(3)
	v_mfma_f32_32x32x16_f16 v[18:33], v[18:21], v[22:25], 0
	v_lshlrev_b32_e32 v38, 2, v38
	s_mov_b32 s0, 0xbfb8aa3b
	s_waitcnt lgkmcnt(0)
	v_mfma_f32_32x32x16_f16 v[2:17], v[78:81], v[82:85], v[2:17]
	ds_read_b64_tr_b16 v[82:83], v88 offset:20736
	ds_read_b64_tr_b16 v[84:85], v88 offset:21312
	s_waitcnt lgkmcnt(0)
	v_mfma_f32_32x32x16_f16 v[18:33], v[78:81], v[82:85], v[18:33]
	ds_read_b128 v[78:81], v86 offset:64
	ds_read_b64_tr_b16 v[82:83], v88 offset:13824
	ds_read_b64_tr_b16 v[84:85], v88 offset:14400
	s_waitcnt lgkmcnt(0)
	v_mfma_f32_32x32x16_f16 v[2:17], v[78:81], v[82:85], v[2:17]
	ds_read_b64_tr_b16 v[82:83], v88 offset:23040
	ds_read_b64_tr_b16 v[84:85], v88 offset:23616
	s_waitcnt lgkmcnt(0)
	v_mfma_f32_32x32x16_f16 v[18:33], v[78:81], v[82:85], v[18:33]
	ds_read_b128 v[78:81], v86 offset:96
	ds_read_b64_tr_b16 v[82:83], v88 offset:16128
	ds_read_b64_tr_b16 v[84:85], v88 offset:16704
	s_waitcnt lgkmcnt(0)
	v_mfma_f32_32x32x16_f16 v[2:17], v[78:81], v[82:85], v[2:17]
	ds_read_b64_tr_b16 v[82:83], v88 offset:25344
	ds_read_b64_tr_b16 v[84:85], v88 offset:25920
	s_waitcnt lgkmcnt(0)
	v_mfma_f32_32x32x16_f16 v[18:33], v[78:81], v[82:85], v[18:33]
	s_nop 7
	ds_write2st64_b32 v38, v2, v3 offset0:108 offset1:109
	s_nop 2
	ds_write2st64_b32 v38, v18, v19 offset0:172 offset1:173
	ds_write2st64_b32 v38, v4, v5 offset0:110 offset1:111
	ds_write2st64_b32 v38, v20, v21 offset0:174 offset1:175
	ds_write2st64_b32 v38, v6, v7 offset0:116 offset1:117
	ds_write2st64_b32 v38, v22, v23 offset0:180 offset1:181
	ds_write2st64_b32 v38, v8, v9 offset0:118 offset1:119
	ds_write2st64_b32 v38, v24, v25 offset0:182 offset1:183
	ds_write2st64_b32 v38, v10, v11 offset0:124 offset1:125
	ds_write2st64_b32 v38, v26, v27 offset0:188 offset1:189
	ds_write2st64_b32 v38, v12, v13 offset0:126 offset1:127
	ds_write2st64_b32 v38, v28, v29 offset0:190 offset1:191
	ds_write2st64_b32 v38, v14, v15 offset0:132 offset1:133
	ds_write2st64_b32 v38, v30, v31 offset0:196 offset1:197
	ds_write2st64_b32 v38, v16, v17 offset0:134 offset1:135
	ds_write2st64_b32 v38, v32, v33 offset0:198 offset1:199
	v_lshlrev_b64 v[2:3], 2, v[0:1]
	v_lshl_add_u64 v[4:5], s[68:69], 0, v[2:3]
	s_waitcnt lgkmcnt(0)
	s_barrier
	global_load_dword v77, v[4:5], off
	v_lshl_add_u64 v[4:5], s[62:63], 0, v[2:3]
	global_load_dword v75, v[4:5], off
	v_lshl_add_u64 v[2:3], s[66:67], 0, v[2:3]
	global_load_dword v0, v[2:3], off
	v_lshlrev_b32_e32 v38, 2, v40
	v_lshl_or_b32 v2, v41, 12, v38
	ds_read2st64_b32 v[32:33], v2 offset0:108 offset1:172
	v_lshl_or_b32 v2, v76, 8, v38
	ds_read2st64_b32 v[30:31], v2 offset0:108 offset1:172
	v_lshl_or_b32 v2, v74, 8, v38
	v_or_b32_e32 v3, 0x200, v2
	ds_read2st64_b32 v[28:29], v3 offset0:108 offset1:172
	v_or_b32_e32 v3, 0x300, v2
	ds_read2st64_b32 v[26:27], v3 offset0:108 offset1:172
	v_or_b32_e32 v3, 0x400, v2
	ds_read2st64_b32 v[24:25], v3 offset0:108 offset1:172
	v_or_b32_e32 v3, 0x500, v2
	ds_read2st64_b32 v[22:23], v3 offset0:108 offset1:172
	v_or_b32_e32 v3, 0x600, v2
	ds_read2st64_b32 v[20:21], v3 offset0:108 offset1:172
	v_or_b32_e32 v3, 0x700, v2
	ds_read2st64_b32 v[18:19], v3 offset0:108 offset1:172
	v_or_b32_e32 v3, 0x800, v2
	ds_read2st64_b32 v[16:17], v3 offset0:108 offset1:172
	v_or_b32_e32 v3, 0x900, v2
	ds_read2st64_b32 v[14:15], v3 offset0:108 offset1:172
	v_or_b32_e32 v3, 0xa00, v2
	ds_read2st64_b32 v[12:13], v3 offset0:108 offset1:172
	v_or_b32_e32 v3, 0xb00, v2
	ds_read2st64_b32 v[10:11], v3 offset0:108 offset1:172
	v_or_b32_e32 v3, 0xc00, v2
	ds_read2st64_b32 v[8:9], v3 offset0:108 offset1:172
	v_or_b32_e32 v3, 0xd00, v2
	ds_read2st64_b32 v[6:7], v3 offset0:108 offset1:172
	v_mov_b32_e32 v79, 0x41b17218
	v_or_b32_e32 v4, 0xe00, v2
	v_or_b32_e32 v2, 0xf00, v2
	ds_read2st64_b32 v[4:5], v4 offset0:108 offset1:172
	s_waitcnt vmcnt(2)
	v_mul_f32_e64 v3, |v77|, s0
	v_exp_f32_e32 v3, v3
	s_waitcnt vmcnt(1) lgkmcnt(14)
	v_add_f32_e32 v32, v32, v75
	v_mul_f32_e32 v32, 0xbfb8aa3b, v32
	v_exp_f32_e32 v32, v32
	v_add_f32_e32 v3, 1.0, v3
	v_cmp_gt_f32_e32 vcc, s56, v3
	v_max_f32_e64 v76, -v77, -v77
	s_mov_b32 s0, 0x3f317217
	v_cndmask_b32_e64 v74, 0, 32, vcc
	v_ldexp_f32 v3, v3, v74
	v_log_f32_e32 v74, v3
	v_add_f32_e32 v32, 1.0, v32
	v_cndmask_b32_e32 v79, 0, v79, vcc
	v_max_f32_e32 v76, 0, v76
	v_mul_f32_e32 v77, 0x3f317217, v74
	v_fma_f32 v77, v74, s0, -v77
	v_fmac_f32_e32 v77, 0x3377d1cf, v74
	s_mov_b32 s0, 0x7f800000
	v_fmac_f32_e32 v77, 0x3f317217, v74
	v_cmp_lt_f32_e64 s[0:1], |v74|, s0
	ds_read2st64_b32 v[2:3], v2 offset0:108 offset1:172
	s_nop 0
	v_cndmask_b32_e64 v74, v74, v77, s[0:1]
	v_div_scale_f32 v77, s[0:1], v32, v32, 1.0
	v_rcp_f32_e32 v78, v77
	v_sub_f32_e32 v74, v74, v79
	v_add_f32_e32 v85, v76, v74
	s_mov_b32 s0, 0xbdcccccd
	v_fma_f32 v74, -v77, v78, 1.0
	v_fmac_f32_e32 v78, v74, v78
	v_div_scale_f32 v74, vcc, 1.0, v32, 1.0
	v_mul_f32_e32 v76, v74, v78
	v_fma_f32 v79, -v77, v76, v74
	v_fmac_f32_e32 v76, v79, v78
	v_fma_f32 v74, -v77, v76, v74
	v_div_fmas_f32 v74, v74, v78, v76
	v_div_fixup_f32 v32, v74, v32, 1.0
	v_mul_f32_e32 v32, 0xc1000000, v32
	v_mul_f32_e32 v32, v32, v85
	v_add_f32_e32 v76, v32, v32
	v_cmp_nlt_f32_e32 vcc, s0, v76
	s_and_saveexec_b64 s[0:1], vcc
	s_xor_b64 s[0:1], exec, s[0:1]
	v_mul_f32_e32 v74, 0x3fb8aa3b, v76
	v_exp_f32_e32 v74, v74
	s_nop 0
	v_sub_f32_e32 v74, 1.0, v74
	s_andn2_saveexec_b64 s[0:1], s[0:1]
	v_fmamk_f32 v74, v76, 0x3d2aaaab, v223
	v_fma_f32 v74, v76, v74, 0.5
	v_fma_f32 v74, v76, v74, 1.0
	v_mul_f32_e64 v74, v74, -v76
	s_or_b64 exec, exec, s[0:1]
	s_waitcnt lgkmcnt(14)
; DI float sigmoidf_(float x) { return 1.f / (1.f + __expf(-x)); }
;     ...
;   for (int i = 0; i < 16; ++i) {
;     const float rr = sigmoidf_(aA[i] + ba), ig = sigmoidf_(aX[i] + bx);
;     const float la = -8.f * rr * sp;
;     const float a = __expf(la);
;     const float x2 = 2.f * la;
;     const float em = (x2 > -0.1f) ? -x2 * (1.f + x2 * (0.5f + x2 * (0.16666667f + x2 * 0.041666667f))) : 1.f - __expf(x2);
	v_add_f32_e32 v30, v30, v75
	v_mul_f32_e32 v30, 0xbfb8aa3b, v30
	v_exp_f32_e32 v30, v30
	s_nop 0
	v_add_f32_e32 v30, 1.0, v30
	v_div_scale_f32 v76, s[0:1], v30, v30, 1.0
	v_rcp_f32_e32 v77, v76
	v_div_scale_f32 v78, vcc, 1.0, v30, 1.0
	s_mov_b32 s0, 0xbdcccccd
	v_fma_f32 v79, -v76, v77, 1.0
	v_fmac_f32_e32 v77, v79, v77
	v_mul_f32_e32 v79, v78, v77
	v_fma_f32 v80, -v76, v79, v78
	v_fmac_f32_e32 v79, v80, v77
	v_fma_f32 v76, -v76, v79, v78
	v_div_fmas_f32 v76, v76, v77, v79
	v_div_fixup_f32 v30, v76, v30, 1.0
	v_mul_f32_e32 v30, 0xc1000000, v30
	v_mul_f32_e32 v30, v30, v85
	v_add_f32_e32 v77, v30, v30
	v_cmp_nlt_f32_e32 vcc, s0, v77
	s_and_saveexec_b64 s[0:1], vcc
	s_xor_b64 s[0:1], exec, s[0:1]
	v_mul_f32_e32 v76, 0x3fb8aa3b, v77
	v_exp_f32_e32 v76, v76
	s_nop 0
	v_sub_f32_e32 v76, 1.0, v76
	s_andn2_saveexec_b64 s[0:1], s[0:1]
	v_fmamk_f32 v76, v77, 0x3d2aaaab, v223
	v_fma_f32 v76, v77, v76, 0.5
	v_fma_f32 v76, v77, v76, 1.0
	v_mul_f32_e64 v76, v76, -v77
	s_or_b64 exec, exec, s[0:1]
	s_waitcnt lgkmcnt(13)
	v_add_f32_e32 v28, v28, v75
	v_mul_f32_e32 v28, 0xbfb8aa3b, v28
	v_exp_f32_e32 v28, v28
	s_nop 0
	v_add_f32_e32 v28, 1.0, v28
	v_div_scale_f32 v77, s[0:1], v28, v28, 1.0
	v_rcp_f32_e32 v78, v77
	v_div_scale_f32 v79, vcc, 1.0, v28, 1.0
	s_mov_b32 s0, 0xbdcccccd
	v_fma_f32 v80, -v77, v78, 1.0
	v_fmac_f32_e32 v78, v80, v78
	v_mul_f32_e32 v80, v79, v78
	v_fma_f32 v81, -v77, v80, v79
	v_fmac_f32_e32 v80, v81, v78
	v_fma_f32 v77, -v77, v80, v79
	v_div_fmas_f32 v77, v77, v78, v80
	v_div_fixup_f32 v28, v77, v28, 1.0
	v_mul_f32_e32 v28, 0xc1000000, v28
	v_mul_f32_e32 v28, v28, v85
	v_add_f32_e32 v78, v28, v28
	v_cmp_nlt_f32_e32 vcc, s0, v78
	s_and_saveexec_b64 s[0:1], vcc
	s_xor_b64 s[0:1], exec, s[0:1]
	v_mul_f32_e32 v77, 0x3fb8aa3b, v78
	v_exp_f32_e32 v77, v77
	s_nop 0
	v_sub_f32_e32 v77, 1.0, v77
	s_andn2_saveexec_b64 s[0:1], s[0:1]
	v_fmamk_f32 v77, v78, 0x3d2aaaab, v223
	v_fma_f32 v77, v78, v77, 0.5
	v_fma_f32 v77, v78, v77, 1.0
	v_mul_f32_e64 v77, v77, -v78
	s_or_b64 exec, exec, s[0:1]
	s_waitcnt lgkmcnt(12)
	v_add_f32_e32 v26, v26, v75
	v_mul_f32_e32 v26, 0xbfb8aa3b, v26
	v_exp_f32_e32 v26, v26
	s_nop 0
	v_add_f32_e32 v26, 1.0, v26
	v_div_scale_f32 v78, s[0:1], v26, v26, 1.0
	v_rcp_f32_e32 v79, v78
	v_div_scale_f32 v80, vcc, 1.0, v26, 1.0
	s_mov_b32 s0, 0xbdcccccd
	v_fma_f32 v81, -v78, v79, 1.0
	v_fmac_f32_e32 v79, v81, v79
	v_mul_f32_e32 v81, v80, v79
	v_fma_f32 v82, -v78, v81, v80
	v_fmac_f32_e32 v81, v82, v79
	v_fma_f32 v78, -v78, v81, v80
	v_div_fmas_f32 v78, v78, v79, v81
	v_div_fixup_f32 v26, v78, v26, 1.0
	v_mul_f32_e32 v26, 0xc1000000, v26
	v_mul_f32_e32 v26, v26, v85
	v_add_f32_e32 v79, v26, v26
	v_cmp_nlt_f32_e32 vcc, s0, v79
	s_and_saveexec_b64 s[0:1], vcc
	s_xor_b64 s[0:1], exec, s[0:1]
	v_mul_f32_e32 v78, 0x3fb8aa3b, v79
	v_exp_f32_e32 v78, v78
	s_nop 0
	v_sub_f32_e32 v78, 1.0, v78
	s_andn2_saveexec_b64 s[0:1], s[0:1]
	v_fmamk_f32 v78, v79, 0x3d2aaaab, v223
	v_fma_f32 v78, v79, v78, 0.5
	v_fma_f32 v78, v79, v78, 1.0
	v_mul_f32_e64 v78, v78, -v79
	s_or_b64 exec, exec, s[0:1]
	s_waitcnt lgkmcnt(11)
	v_add_f32_e32 v24, v24, v75
	v_mul_f32_e32 v24, 0xbfb8aa3b, v24
	v_exp_f32_e32 v24, v24
	s_nop 0
	v_add_f32_e32 v24, 1.0, v24
	v_div_scale_f32 v79, s[0:1], v24, v24, 1.0
	v_rcp_f32_e32 v80, v79
	v_div_scale_f32 v81, vcc, 1.0, v24, 1.0
	s_mov_b32 s0, 0xbdcccccd
	v_fma_f32 v82, -v79, v80, 1.0
	v_fmac_f32_e32 v80, v82, v80
	v_mul_f32_e32 v82, v81, v80
	v_fma_f32 v83, -v79, v82, v81
	v_fmac_f32_e32 v82, v83, v80
	v_fma_f32 v79, -v79, v82, v81
	v_div_fmas_f32 v79, v79, v80, v82
	v_div_fixup_f32 v24, v79, v24, 1.0
	v_mul_f32_e32 v24, 0xc1000000, v24
	v_mul_f32_e32 v24, v24, v85
	v_add_f32_e32 v80, v24, v24
	v_cmp_nlt_f32_e32 vcc, s0, v80
	s_and_saveexec_b64 s[0:1], vcc
	s_xor_b64 s[0:1], exec, s[0:1]
	v_mul_f32_e32 v79, 0x3fb8aa3b, v80
	v_exp_f32_e32 v79, v79
	s_nop 0
	v_sub_f32_e32 v79, 1.0, v79
	s_andn2_saveexec_b64 s[0:1], s[0:1]
	v_fmamk_f32 v79, v80, 0x3d2aaaab, v223
	v_fma_f32 v79, v80, v79, 0.5
	v_fma_f32 v79, v80, v79, 1.0
	v_mul_f32_e64 v79, v79, -v80
	s_or_b64 exec, exec, s[0:1]
	s_waitcnt lgkmcnt(10)
	v_add_f32_e32 v22, v22, v75
	v_mul_f32_e32 v22, 0xbfb8aa3b, v22
	v_exp_f32_e32 v22, v22
	s_nop 0
	v_add_f32_e32 v22, 1.0, v22
	v_div_scale_f32 v80, s[0:1], v22, v22, 1.0
	v_rcp_f32_e32 v81, v80
	v_div_scale_f32 v82, vcc, 1.0, v22, 1.0
	s_mov_b32 s0, 0xbdcccccd
	v_fma_f32 v83, -v80, v81, 1.0
	v_fmac_f32_e32 v81, v83, v81
	v_mul_f32_e32 v83, v82, v81
	v_fma_f32 v84, -v80, v83, v82
	v_fmac_f32_e32 v83, v84, v81
	v_fma_f32 v80, -v80, v83, v82
	v_div_fmas_f32 v80, v80, v81, v83
	v_div_fixup_f32 v22, v80, v22, 1.0
	v_mul_f32_e32 v22, 0xc1000000, v22
	v_mul_f32_e32 v22, v22, v85
	v_add_f32_e32 v81, v22, v22
	v_cmp_nlt_f32_e32 vcc, s0, v81
	s_and_saveexec_b64 s[0:1], vcc
	s_xor_b64 s[0:1], exec, s[0:1]
	v_mul_f32_e32 v80, 0x3fb8aa3b, v81
	v_exp_f32_e32 v80, v80
	s_nop 0
	v_sub_f32_e32 v80, 1.0, v80
	s_andn2_saveexec_b64 s[0:1], s[0:1]
	v_fmamk_f32 v80, v81, 0x3d2aaaab, v223
	v_fma_f32 v80, v81, v80, 0.5
	v_fma_f32 v80, v81, v80, 1.0
	v_mul_f32_e64 v80, v80, -v81
	s_or_b64 exec, exec, s[0:1]
	s_waitcnt lgkmcnt(9)
	v_add_f32_e32 v20, v20, v75
	v_mul_f32_e32 v20, 0xbfb8aa3b, v20
	v_exp_f32_e32 v20, v20
	s_nop 0
	v_add_f32_e32 v20, 1.0, v20
	v_div_scale_f32 v81, s[0:1], v20, v20, 1.0
	v_rcp_f32_e32 v82, v81
	v_div_scale_f32 v83, vcc, 1.0, v20, 1.0
	s_mov_b32 s0, 0xbdcccccd
	v_fma_f32 v84, -v81, v82, 1.0
	v_fmac_f32_e32 v82, v84, v82
	v_mul_f32_e32 v84, v83, v82
	v_fma_f32 v86, -v81, v84, v83
	v_fmac_f32_e32 v84, v86, v82
	v_fma_f32 v81, -v81, v84, v83
	v_div_fmas_f32 v81, v81, v82, v84
	v_div_fixup_f32 v20, v81, v20, 1.0
	v_mul_f32_e32 v20, 0xc1000000, v20
	v_mul_f32_e32 v20, v20, v85
	v_add_f32_e32 v82, v20, v20
	v_cmp_nlt_f32_e32 vcc, s0, v82
	s_and_saveexec_b64 s[0:1], vcc
	s_xor_b64 s[0:1], exec, s[0:1]
	v_mul_f32_e32 v81, 0x3fb8aa3b, v82
	v_exp_f32_e32 v81, v81
	s_nop 0
	v_sub_f32_e32 v81, 1.0, v81
	s_andn2_saveexec_b64 s[0:1], s[0:1]
	v_fmamk_f32 v81, v82, 0x3d2aaaab, v223
	v_fma_f32 v81, v82, v81, 0.5
	v_fma_f32 v81, v82, v81, 1.0
	v_mul_f32_e64 v81, v81, -v82
	s_or_b64 exec, exec, s[0:1]
	s_waitcnt lgkmcnt(8)
; DI float sigmoidf_(float x) { return 1.f / (1.f + __expf(-x)); }
;     ...
;   for (int i = 0; i < 16; ++i) {
;     const float rr = sigmoidf_(aA[i] + ba), ig = sigmoidf_(aX[i] + bx);
;     const float la = -8.f * rr * sp;
;     const float a = __expf(la);
;     const float x2 = 2.f * la;
;     const float em = (x2 > -0.1f) ? -x2 * (1.f + x2 * (0.5f + x2 * (0.16666667f + x2 * 0.041666667f))) : 1.f - __expf(x2);
	v_add_f32_e32 v18, v18, v75
	v_mul_f32_e32 v18, 0xbfb8aa3b, v18
	v_exp_f32_e32 v18, v18
	s_nop 0
	v_add_f32_e32 v18, 1.0, v18
	v_div_scale_f32 v82, s[0:1], v18, v18, 1.0
	v_rcp_f32_e32 v83, v82
	v_div_scale_f32 v84, vcc, 1.0, v18, 1.0
	s_mov_b32 s0, 0xbdcccccd
	v_fma_f32 v86, -v82, v83, 1.0
	v_fmac_f32_e32 v83, v86, v83
	v_mul_f32_e32 v86, v84, v83
	v_fma_f32 v87, -v82, v86, v84
	v_fmac_f32_e32 v86, v87, v83
	v_fma_f32 v82, -v82, v86, v84
	v_div_fmas_f32 v82, v82, v83, v86
	v_div_fixup_f32 v18, v82, v18, 1.0
	v_mul_f32_e32 v18, 0xc1000000, v18
	v_mul_f32_e32 v18, v18, v85
	v_add_f32_e32 v83, v18, v18
	v_cmp_nlt_f32_e32 vcc, s0, v83
	s_and_saveexec_b64 s[0:1], vcc
	s_xor_b64 s[0:1], exec, s[0:1]
	v_mul_f32_e32 v82, 0x3fb8aa3b, v83
	v_exp_f32_e32 v82, v82
	s_nop 0
	v_sub_f32_e32 v82, 1.0, v82
	s_andn2_saveexec_b64 s[0:1], s[0:1]
	v_fmamk_f32 v82, v83, 0x3d2aaaab, v223
	v_fma_f32 v82, v83, v82, 0.5
	v_fma_f32 v82, v83, v82, 1.0
	v_mul_f32_e64 v82, v82, -v83
	s_or_b64 exec, exec, s[0:1]
	s_waitcnt lgkmcnt(7)
	v_add_f32_e32 v16, v16, v75
	v_mul_f32_e32 v16, 0xbfb8aa3b, v16
	v_exp_f32_e32 v16, v16
	s_nop 0
	v_add_f32_e32 v16, 1.0, v16
	v_div_scale_f32 v83, s[0:1], v16, v16, 1.0
	v_rcp_f32_e32 v84, v83
	v_div_scale_f32 v86, vcc, 1.0, v16, 1.0
	s_mov_b32 s0, 0xbdcccccd
	v_fma_f32 v87, -v83, v84, 1.0
	v_fmac_f32_e32 v84, v87, v84
	v_mul_f32_e32 v87, v86, v84
	v_fma_f32 v88, -v83, v87, v86
	v_fmac_f32_e32 v87, v88, v84
	v_fma_f32 v83, -v83, v87, v86
	v_div_fmas_f32 v83, v83, v84, v87
	v_div_fixup_f32 v16, v83, v16, 1.0
	v_mul_f32_e32 v16, 0xc1000000, v16
	v_mul_f32_e32 v16, v16, v85
	v_add_f32_e32 v84, v16, v16
	v_cmp_nlt_f32_e32 vcc, s0, v84
	s_and_saveexec_b64 s[0:1], vcc
	s_xor_b64 s[0:1], exec, s[0:1]
	v_mul_f32_e32 v83, 0x3fb8aa3b, v84
	v_exp_f32_e32 v83, v83
	s_nop 0
	v_sub_f32_e32 v83, 1.0, v83
	s_andn2_saveexec_b64 s[0:1], s[0:1]
	v_fmamk_f32 v83, v84, 0x3d2aaaab, v223
	v_fma_f32 v83, v84, v83, 0.5
	v_fma_f32 v83, v84, v83, 1.0
	v_mul_f32_e64 v83, v83, -v84
	s_or_b64 exec, exec, s[0:1]
	s_waitcnt lgkmcnt(6)
	v_add_f32_e32 v14, v14, v75
	v_mul_f32_e32 v14, 0xbfb8aa3b, v14
	v_exp_f32_e32 v14, v14
	s_nop 0
	v_add_f32_e32 v14, 1.0, v14
	v_div_scale_f32 v84, s[0:1], v14, v14, 1.0
	v_rcp_f32_e32 v86, v84
	v_div_scale_f32 v87, vcc, 1.0, v14, 1.0
	s_mov_b32 s0, 0xbdcccccd
	v_fma_f32 v88, -v84, v86, 1.0
	v_fmac_f32_e32 v86, v88, v86
	v_mul_f32_e32 v88, v87, v86
	v_fma_f32 v89, -v84, v88, v87
	v_fmac_f32_e32 v88, v89, v86
	v_fma_f32 v84, -v84, v88, v87
	v_div_fmas_f32 v84, v84, v86, v88
	v_div_fixup_f32 v14, v84, v14, 1.0
	v_mul_f32_e32 v14, 0xc1000000, v14
	v_mul_f32_e32 v14, v14, v85
	v_add_f32_e32 v86, v14, v14
	v_cmp_nlt_f32_e32 vcc, s0, v86
	s_and_saveexec_b64 s[0:1], vcc
	s_xor_b64 s[0:1], exec, s[0:1]
	v_mul_f32_e32 v84, 0x3fb8aa3b, v86
	v_exp_f32_e32 v84, v84
	s_nop 0
	v_sub_f32_e32 v84, 1.0, v84
	s_andn2_saveexec_b64 s[0:1], s[0:1]
	v_fmamk_f32 v84, v86, 0x3d2aaaab, v223
	v_fma_f32 v84, v86, v84, 0.5
	v_fma_f32 v84, v86, v84, 1.0
	v_mul_f32_e64 v84, v84, -v86
	s_or_b64 exec, exec, s[0:1]
	s_waitcnt lgkmcnt(5)
	v_add_f32_e32 v12, v12, v75
	v_mul_f32_e32 v12, 0xbfb8aa3b, v12
	v_exp_f32_e32 v12, v12
	s_nop 0
	v_add_f32_e32 v12, 1.0, v12
	v_div_scale_f32 v86, s[0:1], v12, v12, 1.0
	v_rcp_f32_e32 v87, v86
	v_div_scale_f32 v88, vcc, 1.0, v12, 1.0
	s_mov_b32 s0, 0xbdcccccd
	v_fma_f32 v89, -v86, v87, 1.0
	v_fmac_f32_e32 v87, v89, v87
	v_mul_f32_e32 v89, v88, v87
	v_fma_f32 v90, -v86, v89, v88
	v_fmac_f32_e32 v89, v90, v87
	v_fma_f32 v86, -v86, v89, v88
	v_div_fmas_f32 v86, v86, v87, v89
	v_div_fixup_f32 v12, v86, v12, 1.0
	v_mul_f32_e32 v12, 0xc1000000, v12
	v_mul_f32_e32 v12, v12, v85
	v_add_f32_e32 v87, v12, v12
	v_cmp_nlt_f32_e32 vcc, s0, v87
	s_and_saveexec_b64 s[0:1], vcc
	s_xor_b64 s[0:1], exec, s[0:1]
	v_mul_f32_e32 v86, 0x3fb8aa3b, v87
	v_exp_f32_e32 v86, v86
	s_nop 0
	v_sub_f32_e32 v86, 1.0, v86
	s_andn2_saveexec_b64 s[0:1], s[0:1]
	v_fmamk_f32 v86, v87, 0x3d2aaaab, v223
	v_fma_f32 v86, v87, v86, 0.5
	v_fma_f32 v86, v87, v86, 1.0
	v_mul_f32_e64 v86, v86, -v87
	s_or_b64 exec, exec, s[0:1]
	s_waitcnt lgkmcnt(4)
	v_add_f32_e32 v10, v10, v75
	v_mul_f32_e32 v10, 0xbfb8aa3b, v10
	v_exp_f32_e32 v10, v10
	s_nop 0
	v_add_f32_e32 v10, 1.0, v10
	v_div_scale_f32 v87, s[0:1], v10, v10, 1.0
	v_rcp_f32_e32 v88, v87
	v_div_scale_f32 v89, vcc, 1.0, v10, 1.0
	s_mov_b32 s0, 0xbdcccccd
	v_fma_f32 v90, -v87, v88, 1.0
	v_fmac_f32_e32 v88, v90, v88
	v_mul_f32_e32 v90, v89, v88
	v_fma_f32 v91, -v87, v90, v89
	v_fmac_f32_e32 v90, v91, v88
	v_fma_f32 v87, -v87, v90, v89
	v_div_fmas_f32 v87, v87, v88, v90
	v_div_fixup_f32 v10, v87, v10, 1.0
	v_mul_f32_e32 v10, 0xc1000000, v10
	v_mul_f32_e32 v10, v10, v85
	v_add_f32_e32 v88, v10, v10
	v_cmp_nlt_f32_e32 vcc, s0, v88
	s_and_saveexec_b64 s[0:1], vcc
	s_xor_b64 s[0:1], exec, s[0:1]
	v_mul_f32_e32 v87, 0x3fb8aa3b, v88
	v_exp_f32_e32 v87, v87
	s_nop 0
	v_sub_f32_e32 v87, 1.0, v87
	s_andn2_saveexec_b64 s[0:1], s[0:1]
	v_fmamk_f32 v87, v88, 0x3d2aaaab, v223
	v_fma_f32 v87, v88, v87, 0.5
	v_fma_f32 v87, v88, v87, 1.0
	v_mul_f32_e64 v87, v87, -v88
	s_or_b64 exec, exec, s[0:1]
	s_waitcnt lgkmcnt(3)
	v_add_f32_e32 v8, v8, v75
	v_mul_f32_e32 v8, 0xbfb8aa3b, v8
	v_exp_f32_e32 v8, v8
	s_nop 0
	v_add_f32_e32 v8, 1.0, v8
	v_div_scale_f32 v88, s[0:1], v8, v8, 1.0
	v_rcp_f32_e32 v89, v88
	v_div_scale_f32 v90, vcc, 1.0, v8, 1.0
	s_mov_b32 s0, 0xbdcccccd
	v_fma_f32 v91, -v88, v89, 1.0
	v_fmac_f32_e32 v89, v91, v89
	v_mul_f32_e32 v91, v90, v89
	v_fma_f32 v92, -v88, v91, v90
	v_fmac_f32_e32 v91, v92, v89
	v_fma_f32 v88, -v88, v91, v90
	v_div_fmas_f32 v88, v88, v89, v91
	v_div_fixup_f32 v8, v88, v8, 1.0
	v_mul_f32_e32 v8, 0xc1000000, v8
	v_mul_f32_e32 v8, v8, v85
	v_add_f32_e32 v89, v8, v8
	v_cmp_nlt_f32_e32 vcc, s0, v89
	s_and_saveexec_b64 s[0:1], vcc
	s_xor_b64 s[0:1], exec, s[0:1]
	v_mul_f32_e32 v88, 0x3fb8aa3b, v89
	v_exp_f32_e32 v88, v88
	s_nop 0
	v_sub_f32_e32 v88, 1.0, v88
	s_andn2_saveexec_b64 s[0:1], s[0:1]
	v_fmamk_f32 v88, v89, 0x3d2aaaab, v223
	v_fma_f32 v88, v89, v88, 0.5
	v_fma_f32 v88, v89, v88, 1.0
	v_mul_f32_e64 v88, v88, -v89
	s_or_b64 exec, exec, s[0:1]
	s_waitcnt lgkmcnt(2)
; DI float bf2f(u16 v) { return (float)__builtin_bit_cast(_Float16, v); }
; DI float sigmoidf_(float x) { return 1.f / (1.f + __expf(-x)); }
;     ...
;   for (int i = 0; i < 16; ++i) {
;     const float cur = bf2f(zb[(size_t)(t0 + i) * ZS]);
;     xc[i] = cb + w0 * xm3 + w1 * xm2 + w2 * xm1 + w3 * cur;
;     xm3 = xm2; xm2 = xm1; xm1 = cur;
;     ...
;   for (int i = 0; i < 16; ++i) {
;     const float rr = sigmoidf_(aA[i] + ba), ig = sigmoidf_(aX[i] + bx);
;     const float la = -8.f * rr * sp;
;     const float a = __expf(la);
;     const float x2 = 2.f * la;
;     const float em = (x2 > -0.1f) ? -x2 * (1.f + x2 * (0.5f + x2 * (0.16666667f + x2 * 0.041666667f))) : 1.f - __expf(x2);
;     const float bb = sqrtf(fmaxf(em, 0.f)) * ig * xc[i];
;     aA[i] = a; aX[i] = bb;
;     H = a * H + bb;
;     P *= a;
;   }
	v_add_f32_e32 v6, v6, v75
	v_mul_f32_e32 v6, 0xbfb8aa3b, v6
	v_exp_f32_e32 v6, v6
	s_nop 0
	v_add_f32_e32 v6, 1.0, v6
	v_div_scale_f32 v89, s[0:1], v6, v6, 1.0
	v_rcp_f32_e32 v90, v89
	v_div_scale_f32 v91, vcc, 1.0, v6, 1.0
	s_mov_b32 s0, 0xbdcccccd
	v_fma_f32 v92, -v89, v90, 1.0
	v_fmac_f32_e32 v90, v92, v90
	v_mul_f32_e32 v92, v91, v90
	v_fma_f32 v93, -v89, v92, v91
	v_fmac_f32_e32 v92, v93, v90
	v_fma_f32 v89, -v89, v92, v91
	v_div_fmas_f32 v89, v89, v90, v92
	v_div_fixup_f32 v6, v89, v6, 1.0
	v_mul_f32_e32 v6, 0xc1000000, v6
	v_mul_f32_e32 v6, v6, v85
	v_add_f32_e32 v90, v6, v6
	v_cmp_nlt_f32_e32 vcc, s0, v90
	s_and_saveexec_b64 s[0:1], vcc
	s_xor_b64 s[0:1], exec, s[0:1]
	v_mul_f32_e32 v89, 0x3fb8aa3b, v90
	v_exp_f32_e32 v89, v89
	s_nop 0
	v_sub_f32_e32 v89, 1.0, v89
	s_andn2_saveexec_b64 s[0:1], s[0:1]
	v_fmamk_f32 v89, v90, 0x3d2aaaab, v223
	v_fma_f32 v89, v90, v89, 0.5
	v_fma_f32 v89, v90, v89, 1.0
	v_mul_f32_e64 v89, v89, -v90
	s_or_b64 exec, exec, s[0:1]
	s_waitcnt lgkmcnt(1)
	v_add_f32_e32 v4, v4, v75
	v_mul_f32_e32 v4, 0xbfb8aa3b, v4
	v_exp_f32_e32 v4, v4
	s_nop 0
	v_add_f32_e32 v4, 1.0, v4
	v_div_scale_f32 v90, s[0:1], v4, v4, 1.0
	v_rcp_f32_e32 v91, v90
	v_div_scale_f32 v92, vcc, 1.0, v4, 1.0
	s_mov_b32 s0, 0xbdcccccd
	v_fma_f32 v93, -v90, v91, 1.0
	v_fmac_f32_e32 v91, v93, v91
	v_mul_f32_e32 v93, v92, v91
	v_fma_f32 v94, -v90, v93, v92
	v_fmac_f32_e32 v93, v94, v91
	v_fma_f32 v90, -v90, v93, v92
	v_div_fmas_f32 v90, v90, v91, v93
	v_div_fixup_f32 v4, v90, v4, 1.0
	v_mul_f32_e32 v4, 0xc1000000, v4
	v_mul_f32_e32 v4, v4, v85
	v_add_f32_e32 v91, v4, v4
	v_cmp_nlt_f32_e32 vcc, s0, v91
	s_and_saveexec_b64 s[0:1], vcc
	s_xor_b64 s[0:1], exec, s[0:1]
	v_mul_f32_e32 v90, 0x3fb8aa3b, v91
	v_exp_f32_e32 v90, v90
	s_nop 0
	v_sub_f32_e32 v90, 1.0, v90
	s_andn2_saveexec_b64 s[0:1], s[0:1]
	v_fmamk_f32 v90, v91, 0x3d2aaaab, v223
	v_fma_f32 v90, v91, v90, 0.5
	v_fma_f32 v90, v91, v90, 1.0
	v_mul_f32_e64 v90, v90, -v91
	s_or_b64 exec, exec, s[0:1]
	s_waitcnt lgkmcnt(0)
	v_add_f32_e32 v2, v2, v75
	v_mul_f32_e32 v2, 0xbfb8aa3b, v2
	v_exp_f32_e32 v2, v2
	s_nop 0
	v_add_f32_e32 v2, 1.0, v2
	v_div_scale_f32 v75, s[0:1], v2, v2, 1.0
	v_rcp_f32_e32 v91, v75
	v_div_scale_f32 v92, vcc, 1.0, v2, 1.0
	s_mov_b32 s0, 0xbdcccccd
	v_fma_f32 v93, -v75, v91, 1.0
	v_fmac_f32_e32 v91, v93, v91
	v_mul_f32_e32 v93, v92, v91
	v_fma_f32 v94, -v75, v93, v92
	v_fmac_f32_e32 v93, v94, v91
	v_fma_f32 v75, -v75, v93, v92
	v_div_fmas_f32 v75, v75, v91, v93
	v_div_fixup_f32 v2, v75, v2, 1.0
	v_mul_f32_e32 v2, 0xc1000000, v2
	v_mul_f32_e32 v2, v2, v85
	v_add_f32_e32 v85, v2, v2
	v_cmp_nlt_f32_e32 vcc, s0, v85
	s_and_saveexec_b64 s[0:1], vcc
	s_xor_b64 s[0:1], exec, s[0:1]
	v_mul_f32_e32 v75, 0x3fb8aa3b, v85
	v_exp_f32_e32 v75, v75
	s_nop 0
	v_sub_f32_e32 v75, 1.0, v75
	s_andn2_saveexec_b64 s[0:1], s[0:1]
	v_fmamk_f32 v75, v85, 0x3d2aaaab, v223
	v_fma_f32 v75, v85, v75, 0.5
	v_fma_f32 v75, v85, v75, 1.0
	v_mul_f32_e64 v75, v75, -v85
	s_or_b64 exec, exec, s[0:1]
	s_waitcnt vmcnt(0)
	v_add_f32_e32 v33, v33, v0
	v_mul_f32_e32 v33, 0xbfb8aa3b, v33
	v_exp_f32_e32 v33, v33
	v_fma_mix_f32 v44, v42, v44, v57 op_sel_hi:[0,1,0]
	v_fma_mix_f32 v57, v42, v45, v58 op_sel_hi:[0,1,0]
	v_fma_mix_f32 v58, v42, v46, v59 op_sel_hi:[0,1,0]
	v_add_f32_e32 v33, 1.0, v33
	v_fma_mix_f32 v59, v42, v47, v60 op_sel_hi:[0,1,0]
	v_fma_mix_f32 v60, v42, v49, v61 op_sel_hi:[0,1,0]
	v_fma_mix_f32 v61, v42, v53, v39 op_sel_hi:[0,1,0]
	v_div_scale_f32 v39, s[0:1], v33, v33, 1.0
	v_rcp_f32_e32 v45, v39
	v_fma_mix_f32 v43, v42, v43, v48 op_sel_hi:[0,1,0]
	v_fma_mix_f32 v65, v42, v54, v65 op_sel_hi:[0,1,0]
	v_fma_mix_f32 v67, v42, v55, v67 op_sel_hi:[0,1,0]
	v_fma_mix_f32 v56, v42, v56, v69 op_sel_hi:[0,1,0]
	v_fma_mix_f32 v55, v42, v50, v66 op_sel_hi:[0,1,0]
	v_fma_mix_f32 v54, v42, v51, v68 op_sel_hi:[0,1,0]
	v_fma_mix_f32 v53, v42, v52, v70 op_sel_hi:[0,1,0]
	v_fma_mix_f32 v52, v42, v62, v71 op_sel_hi:[0,1,0]
	v_fma_mix_f32 v51, v42, v63, v72 op_sel_hi:[0,1,0]
	v_fma_mix_f32 v50, v42, v64, v73 op_sel_hi:[0,1,0]
	v_fma_f32 v42, -v39, v45, 1.0
	v_fmac_f32_e32 v45, v42, v45
	v_div_scale_f32 v42, vcc, 1.0, v33, 1.0
	v_mul_f32_e32 v46, v42, v45
	v_fma_f32 v47, -v39, v46, v42
	v_fmac_f32_e32 v46, v47, v45
	v_fma_f32 v39, -v39, v46, v42
	v_max_f32_e32 v42, v74, v74
	v_max_f32_e32 v42, 0, v42
	s_mov_b32 s4, 0xf800000
	v_div_fmas_f32 v39, v39, v45, v46
	v_mul_f32_e32 v45, 0x4f800000, v42
	v_cmp_gt_f32_e32 vcc, s4, v42
	v_mul_f32_e32 v32, 0x3fb8aa3b, v32
	v_exp_f32_e32 v48, v32
	v_cndmask_b32_e32 v42, v42, v45, vcc
	v_sqrt_f32_e32 v45, v42
	v_add_f32_e32 v31, v31, v0
	v_div_fixup_f32 v33, v39, v33, 1.0
	v_mul_f32_e32 v31, 0xbfb8aa3b, v31
	v_add_u32_e32 v32, -1, v45
	v_fma_f32 v39, -v32, v45, v42
	v_cmp_ge_f32_e64 s[0:1], 0, v39
	v_add_u32_e32 v39, 1, v45
	v_exp_f32_e32 v31, v31
	v_cndmask_b32_e64 v32, v45, v32, s[0:1]
	v_fma_f32 v45, -v39, v45, v42
	v_cmp_lt_f32_e64 s[0:1], 0, v45
	v_mov_b32_e32 v62, 0x260
	v_add_f32_e32 v31, 1.0, v31
	v_cndmask_b32_e64 v32, v32, v39, s[0:1]
	v_mul_f32_e32 v39, 0x37800000, v32
	v_cndmask_b32_e32 v32, v32, v39, vcc
	v_cmp_class_f32_e32 vcc, v42, v62
	v_div_scale_f32 v39, s[0:1], v31, v31, 1.0
	s_nop 0
	v_cndmask_b32_e32 v32, v32, v42, vcc
	v_rcp_f32_e32 v42, v39
	v_mul_f32_e32 v32, v33, v32
	v_mul_f32_e32 v47, v43, v32
	v_mul_f32_e32 v30, 0x3fb8aa3b, v30
	v_fma_f32 v33, -v39, v42, 1.0
	v_fmac_f32_e32 v42, v33, v42
	v_div_scale_f32 v33, vcc, 1.0, v31, 1.0
	v_mul_f32_e32 v43, v33, v42
	v_fma_f32 v45, -v39, v43, v33
	v_fmac_f32_e32 v43, v45, v42
	v_fma_f32 v33, -v39, v43, v33
	v_max_f32_e32 v39, v76, v76
	v_max_f32_e32 v39, 0, v39
	v_div_fmas_f32 v33, v33, v42, v43
; DI float sigmoidf_(float x) { return 1.f / (1.f + __expf(-x)); }
;     ...
;   for (int i = 0; i < 16; ++i) {
;     const float rr = sigmoidf_(aA[i] + ba), ig = sigmoidf_(aX[i] + bx);
;     const float la = -8.f * rr * sp;
;     const float a = __expf(la);
;     const float x2 = 2.f * la;
;     const float em = (x2 > -0.1f) ? -x2 * (1.f + x2 * (0.5f + x2 * (0.16666667f + x2 * 0.041666667f))) : 1.f - __expf(x2);
;     const float bb = sqrtf(fmaxf(em, 0.f)) * ig * xc[i];
;     aA[i] = a; aX[i] = bb;
;     H = a * H + bb;
;     P *= a;
;   }
	v_mul_f32_e32 v42, 0x4f800000, v39
	v_cmp_gt_f32_e32 vcc, s4, v39
	v_exp_f32_e32 v49, v30
	v_div_fixup_f32 v31, v33, v31, 1.0
	v_cndmask_b32_e32 v39, v39, v42, vcc
	v_sqrt_f32_e32 v42, v39
	v_add_f32_e32 v29, v29, v0
	v_mul_f32_e32 v29, 0xbfb8aa3b, v29
	v_exp_f32_e32 v29, v29
	v_add_u32_e32 v30, -1, v42
	v_fma_f32 v33, -v30, v42, v39
	v_cmp_ge_f32_e64 s[0:1], 0, v33
	v_add_u32_e32 v33, 1, v42
	v_add_f32_e32 v29, 1.0, v29
	v_cndmask_b32_e64 v30, v42, v30, s[0:1]
	v_fma_f32 v42, -v33, v42, v39
	v_cmp_lt_f32_e64 s[0:1], 0, v42
	v_mul_f32_e32 v28, 0x3fb8aa3b, v28
	v_exp_f32_e32 v46, v28
	v_cndmask_b32_e64 v30, v30, v33, s[0:1]
	v_mul_f32_e32 v33, 0x37800000, v30
	v_cndmask_b32_e32 v30, v30, v33, vcc
	v_cmp_class_f32_e32 vcc, v39, v62
	v_add_f32_e32 v27, v27, v0
	v_mul_f32_e32 v27, 0xbfb8aa3b, v27
	v_cndmask_b32_e32 v30, v30, v39, vcc
	v_mul_f32_e32 v30, v31, v30
	v_div_scale_f32 v31, s[0:1], v29, v29, 1.0
	v_rcp_f32_e32 v33, v31
	v_exp_f32_e32 v27, v27
	v_fma_f32 v32, 0, v48, v47
	v_mul_f32_e32 v45, v44, v30
	v_fma_f32 v39, -v31, v33, 1.0
	v_fmac_f32_e32 v33, v39, v33
	v_div_scale_f32 v39, vcc, 1.0, v29, 1.0
	v_mul_f32_e32 v42, v39, v33
	v_fma_f32 v43, -v31, v42, v39
	v_fmac_f32_e32 v42, v43, v33
	v_fma_f32 v31, -v31, v42, v39
	v_div_fmas_f32 v31, v31, v33, v42
	v_max_f32_e32 v33, v77, v77
	v_max_f32_e32 v33, 0, v33
	v_mul_f32_e32 v39, 0x4f800000, v33
	v_cmp_gt_f32_e32 vcc, s4, v33
	v_div_fixup_f32 v29, v31, v29, 1.0
	v_add_f32_e32 v27, 1.0, v27
	v_cndmask_b32_e32 v33, v33, v39, vcc
	v_sqrt_f32_e32 v39, v33
	v_fma_f32 v30, v49, v32, v45
	v_mul_f32_e32 v32, v48, v49
	v_mul_f32_e32 v26, 0x3fb8aa3b, v26
	v_add_u32_e32 v28, -1, v39
	v_fma_f32 v31, -v28, v39, v33
	v_cmp_ge_f32_e64 s[0:1], 0, v31
	v_add_u32_e32 v31, 1, v39
	v_exp_f32_e32 v44, v26
	v_cndmask_b32_e64 v28, v39, v28, s[0:1]
	v_fma_f32 v39, -v31, v39, v33
	v_cmp_lt_f32_e64 s[0:1], 0, v39
	v_add_f32_e32 v25, v25, v0
	v_mul_f32_e32 v25, 0xbfb8aa3b, v25
	v_cndmask_b32_e64 v28, v28, v31, s[0:1]
	v_mul_f32_e32 v31, 0x37800000, v28
	v_cndmask_b32_e32 v28, v28, v31, vcc
	v_cmp_class_f32_e32 vcc, v33, v62
	v_exp_f32_e32 v25, v25
	v_mul_f32_e32 v24, 0x3fb8aa3b, v24
	v_cndmask_b32_e32 v28, v28, v33, vcc
	v_mul_f32_e32 v28, v29, v28
	v_div_scale_f32 v29, s[0:1], v27, v27, 1.0
	v_rcp_f32_e32 v31, v29
	v_mul_f32_e32 v43, v57, v28
	v_fma_f32 v28, v46, v30, v43
	v_mul_f32_e32 v30, v46, v32
	v_fma_f32 v32, -v29, v31, 1.0
	v_fmac_f32_e32 v31, v32, v31
	v_div_scale_f32 v32, vcc, 1.0, v27, 1.0
	v_mul_f32_e32 v33, v32, v31
	v_fma_f32 v39, -v29, v33, v32
	v_fmac_f32_e32 v33, v39, v31
	v_fma_f32 v29, -v29, v33, v32
	v_div_fmas_f32 v29, v29, v31, v33
	v_max_f32_e32 v31, v78, v78
	v_max_f32_e32 v31, 0, v31
	v_mul_f32_e32 v32, 0x4f800000, v31
	v_cmp_gt_f32_e32 vcc, s4, v31
	v_div_fixup_f32 v27, v29, v27, 1.0
	v_add_f32_e32 v25, 1.0, v25
	v_cndmask_b32_e32 v31, v31, v32, vcc
	v_sqrt_f32_e32 v32, v31
	v_exp_f32_e32 v39, v24
	v_add_f32_e32 v23, v23, v0
	v_mul_f32_e32 v23, 0xbfb8aa3b, v23
	v_add_u32_e32 v26, -1, v32
	v_fma_f32 v29, -v26, v32, v31
	v_cmp_ge_f32_e64 s[0:1], 0, v29
	v_add_u32_e32 v29, 1, v32
	v_exp_f32_e32 v23, v23
	v_cndmask_b32_e64 v26, v32, v26, s[0:1]
	v_fma_f32 v32, -v29, v32, v31
	v_cmp_lt_f32_e64 s[0:1], 0, v32
	v_add_f32_e32 v23, 1.0, v23
	v_mul_f32_e32 v22, 0x3fb8aa3b, v22
	v_cndmask_b32_e64 v26, v26, v29, s[0:1]
	v_mul_f32_e32 v29, 0x37800000, v26
	v_cndmask_b32_e32 v26, v26, v29, vcc
	v_cmp_class_f32_e32 vcc, v31, v62
	v_exp_f32_e32 v42, v22
	v_add_f32_e32 v21, v21, v0
	v_cndmask_b32_e32 v26, v26, v31, vcc
	v_mul_f32_e32 v26, v27, v26
	v_div_scale_f32 v27, s[0:1], v25, v25, 1.0
	v_rcp_f32_e32 v29, v27
	v_mul_f32_e32 v32, v58, v26
	v_fma_f32 v26, v44, v28, v32
	v_mul_f32_e32 v28, v44, v30
	v_fma_f32 v30, -v27, v29, 1.0
	v_fmac_f32_e32 v29, v30, v29
	v_div_scale_f32 v30, vcc, 1.0, v25, 1.0
	v_mul_f32_e32 v31, v30, v29
	v_fma_f32 v33, -v27, v31, v30
	v_fmac_f32_e32 v31, v33, v29
	v_fma_f32 v27, -v27, v31, v30
	v_div_fmas_f32 v27, v27, v29, v31
	v_max_f32_e32 v29, v79, v79
	v_max_f32_e32 v29, 0, v29
	v_mul_f32_e32 v30, 0x4f800000, v29
	v_cmp_gt_f32_e32 vcc, s4, v29
	v_div_fixup_f32 v25, v27, v25, 1.0
	v_mul_f32_e32 v21, 0xbfb8aa3b, v21
	v_cndmask_b32_e32 v29, v29, v30, vcc
	v_sqrt_f32_e32 v30, v29
	v_exp_f32_e32 v21, v21
	v_mul_f32_e32 v20, 0x3fb8aa3b, v20
	v_exp_f32_e32 v31, v20
	v_add_u32_e32 v24, -1, v30
	v_fma_f32 v27, -v24, v30, v29
	v_cmp_ge_f32_e64 s[0:1], 0, v27
	v_add_u32_e32 v27, 1, v30
	v_add_f32_e32 v21, 1.0, v21
	v_cndmask_b32_e64 v24, v30, v24, s[0:1]
	v_fma_f32 v30, -v27, v30, v29
	v_cmp_lt_f32_e64 s[0:1], 0, v30
	v_add_f32_e32 v19, v19, v0
	v_mul_f32_e32 v19, 0xbfb8aa3b, v19
	v_cndmask_b32_e64 v24, v24, v27, s[0:1]
	v_mul_f32_e32 v27, 0x37800000, v24
	v_cndmask_b32_e32 v24, v24, v27, vcc
	v_cmp_class_f32_e32 vcc, v29, v62
	v_exp_f32_e32 v19, v19
	v_mul_f32_e32 v18, 0x3fb8aa3b, v18
	v_cndmask_b32_e32 v24, v24, v29, vcc
	v_mul_f32_e32 v24, v25, v24
	v_div_scale_f32 v25, s[0:1], v23, v23, 1.0
	v_rcp_f32_e32 v27, v25
	v_mul_f32_e32 v33, v59, v24
	v_fma_f32 v24, v39, v26, v33
	v_mul_f32_e32 v26, v39, v28
	v_fma_f32 v28, -v25, v27, 1.0
	v_fmac_f32_e32 v27, v28, v27
	v_div_scale_f32 v28, vcc, 1.0, v23, 1.0
	v_mul_f32_e32 v29, v28, v27
	v_fma_f32 v30, -v25, v29, v28
	v_fmac_f32_e32 v29, v30, v27
	v_fma_f32 v25, -v25, v29, v28
	v_div_fmas_f32 v25, v25, v27, v29
	v_max_f32_e32 v27, v80, v80
	v_max_f32_e32 v27, 0, v27
	v_mul_f32_e32 v28, 0x4f800000, v27
	v_cmp_gt_f32_e32 vcc, s4, v27
	v_div_fixup_f32 v23, v25, v23, 1.0
	v_add_f32_e32 v19, 1.0, v19
	v_cndmask_b32_e32 v27, v27, v28, vcc
	v_sqrt_f32_e32 v28, v27
	v_exp_f32_e32 v29, v18
	v_add_f32_e32 v17, v17, v0
	v_mul_f32_e32 v17, 0xbfb8aa3b, v17
; DI float sigmoidf_(float x) { return 1.f / (1.f + __expf(-x)); }
;     ...
;   for (int i = 0; i < 16; ++i) {
;     const float rr = sigmoidf_(aA[i] + ba), ig = sigmoidf_(aX[i] + bx);
;     const float la = -8.f * rr * sp;
;     const float a = __expf(la);
;     const float x2 = 2.f * la;
;     const float em = (x2 > -0.1f) ? -x2 * (1.f + x2 * (0.5f + x2 * (0.16666667f + x2 * 0.041666667f))) : 1.f - __expf(x2);
;     const float bb = sqrtf(fmaxf(em, 0.f)) * ig * xc[i];
;     aA[i] = a; aX[i] = bb;
;     H = a * H + bb;
;     P *= a;
;   }
	v_add_u32_e32 v22, -1, v28
	v_fma_f32 v25, -v22, v28, v27
	v_cmp_ge_f32_e64 s[0:1], 0, v25
	v_add_u32_e32 v25, 1, v28
	v_exp_f32_e32 v17, v17
	v_cndmask_b32_e64 v22, v28, v22, s[0:1]
	v_fma_f32 v28, -v25, v28, v27
	v_cmp_lt_f32_e64 s[0:1], 0, v28
	v_add_f32_e32 v17, 1.0, v17
	v_mul_f32_e32 v16, 0x3fb8aa3b, v16
	v_cndmask_b32_e64 v22, v22, v25, s[0:1]
	v_mul_f32_e32 v25, 0x37800000, v22
	v_cndmask_b32_e32 v22, v22, v25, vcc
	v_cmp_class_f32_e32 vcc, v27, v62
	v_add_f32_e32 v15, v15, v0
	v_mul_f32_e32 v15, 0xbfb8aa3b, v15
	v_cndmask_b32_e32 v22, v22, v27, vcc
	v_mul_f32_e32 v22, v23, v22
	v_div_scale_f32 v23, s[0:1], v21, v21, 1.0
	v_rcp_f32_e32 v25, v23
	v_mul_f32_e32 v30, v60, v22
	v_fma_f32 v22, v42, v24, v30
	v_mul_f32_e32 v24, v42, v26
	v_fma_f32 v26, -v23, v25, 1.0
	v_fmac_f32_e32 v25, v26, v25
	v_div_scale_f32 v26, vcc, 1.0, v21, 1.0
	v_mul_f32_e32 v27, v26, v25
	v_fma_f32 v28, -v23, v27, v26
	v_fmac_f32_e32 v27, v28, v25
	v_fma_f32 v23, -v23, v27, v26
	v_div_fmas_f32 v23, v23, v25, v27
	v_max_f32_e32 v25, v81, v81
	v_max_f32_e32 v25, 0, v25
	v_mul_f32_e32 v26, 0x4f800000, v25
	v_cmp_gt_f32_e32 vcc, s4, v25
	v_div_fixup_f32 v21, v23, v21, 1.0
	v_exp_f32_e32 v27, v16
	v_cndmask_b32_e32 v25, v25, v26, vcc
	v_sqrt_f32_e32 v26, v25
	v_exp_f32_e32 v15, v15
	v_mul_f32_e32 v14, 0x3fb8aa3b, v14
	v_add_f32_e32 v13, v13, v0
	v_add_u32_e32 v20, -1, v26
	v_fma_f32 v23, -v20, v26, v25
	v_cmp_ge_f32_e64 s[0:1], 0, v23
	v_add_u32_e32 v23, 1, v26
	v_add_f32_e32 v15, 1.0, v15
	v_cndmask_b32_e64 v20, v26, v20, s[0:1]
	v_fma_f32 v26, -v23, v26, v25
	v_cmp_lt_f32_e64 s[0:1], 0, v26
	v_mul_f32_e32 v13, 0xbfb8aa3b, v13
	v_exp_f32_e32 v13, v13
	v_cndmask_b32_e64 v20, v20, v23, s[0:1]
	v_mul_f32_e32 v23, 0x37800000, v20
	v_cndmask_b32_e32 v20, v20, v23, vcc
	v_cmp_class_f32_e32 vcc, v25, v62
	v_add_f32_e32 v13, 1.0, v13
	v_mul_f32_e32 v12, 0x3fb8aa3b, v12
	v_cndmask_b32_e32 v20, v20, v25, vcc
	v_mul_f32_e32 v20, v21, v20
	v_div_scale_f32 v21, s[0:1], v19, v19, 1.0
	v_rcp_f32_e32 v23, v21
	v_mul_f32_e32 v28, v61, v20
	v_fma_f32 v20, v31, v22, v28
	v_mul_f32_e32 v22, v31, v24
	v_fma_f32 v24, -v21, v23, 1.0
	v_fmac_f32_e32 v23, v24, v23
	v_div_scale_f32 v24, vcc, 1.0, v19, 1.0
	v_mul_f32_e32 v25, v24, v23
	v_fma_f32 v26, -v21, v25, v24
	v_fmac_f32_e32 v25, v26, v23
	v_fma_f32 v21, -v21, v25, v24
	v_div_fmas_f32 v21, v21, v23, v25
	v_max_f32_e32 v23, v82, v82
	v_max_f32_e32 v23, 0, v23
	v_mul_f32_e32 v24, 0x4f800000, v23
	v_cmp_gt_f32_e32 vcc, s4, v23
	v_div_fixup_f32 v19, v21, v19, 1.0
	v_exp_f32_e32 v25, v14
	v_cndmask_b32_e32 v23, v23, v24, vcc
	v_sqrt_f32_e32 v24, v23
	v_add_f32_e32 v11, v11, v0
	v_mul_f32_e32 v11, 0xbfb8aa3b, v11
	v_exp_f32_e32 v11, v11
	v_add_u32_e32 v18, -1, v24
	v_fma_f32 v21, -v18, v24, v23
	v_cmp_ge_f32_e64 s[0:1], 0, v21
	v_add_u32_e32 v21, 1, v24
	v_add_f32_e32 v11, 1.0, v11
	v_cndmask_b32_e64 v18, v24, v18, s[0:1]
	v_fma_f32 v24, -v21, v24, v23
	v_cmp_lt_f32_e64 s[0:1], 0, v24
	v_mul_f32_e32 v10, 0x3fb8aa3b, v10
	v_add_f32_e32 v9, v9, v0
	v_cndmask_b32_e64 v18, v18, v21, s[0:1]
	v_mul_f32_e32 v21, 0x37800000, v18
	v_cndmask_b32_e32 v18, v18, v21, vcc
	v_cmp_class_f32_e32 vcc, v23, v62
	v_mul_f32_e32 v9, 0xbfb8aa3b, v9
	v_exp_f32_e32 v9, v9
	v_cndmask_b32_e32 v18, v18, v23, vcc
	v_mul_f32_e32 v18, v19, v18
	v_div_scale_f32 v19, s[0:1], v17, v17, 1.0
	v_rcp_f32_e32 v21, v19
	v_mul_f32_e32 v26, v65, v18
	v_fma_f32 v18, v29, v20, v26
	v_mul_f32_e32 v20, v29, v22
	v_fma_f32 v22, -v19, v21, 1.0
	v_fmac_f32_e32 v21, v22, v21
	v_div_scale_f32 v22, vcc, 1.0, v17, 1.0
	v_mul_f32_e32 v23, v22, v21
	v_fma_f32 v24, -v19, v23, v22
	v_fmac_f32_e32 v23, v24, v21
	v_fma_f32 v19, -v19, v23, v22
	v_div_fmas_f32 v19, v19, v21, v23
	v_max_f32_e32 v21, v83, v83
	v_max_f32_e32 v21, 0, v21
	v_mul_f32_e32 v22, 0x4f800000, v21
	v_cmp_gt_f32_e32 vcc, s4, v21
	v_div_fixup_f32 v17, v19, v17, 1.0
	v_exp_f32_e32 v23, v12
	v_cndmask_b32_e32 v21, v21, v22, vcc
	v_sqrt_f32_e32 v22, v21
	v_add_f32_e32 v9, 1.0, v9
	v_mul_f32_e32 v8, 0x3fb8aa3b, v8
	v_add_f32_e32 v7, v7, v0
	v_add_u32_e32 v16, -1, v22
	v_fma_f32 v19, -v16, v22, v21
	v_cmp_ge_f32_e64 s[0:1], 0, v19
	v_add_u32_e32 v19, 1, v22
	v_mul_f32_e32 v7, 0xbfb8aa3b, v7
	v_cndmask_b32_e64 v16, v22, v16, s[0:1]
	v_fma_f32 v22, -v19, v22, v21
	v_cmp_lt_f32_e64 s[0:1], 0, v22
	v_exp_f32_e32 v7, v7
	v_mul_f32_e32 v6, 0x3fb8aa3b, v6
	v_cndmask_b32_e64 v16, v16, v19, s[0:1]
	v_mul_f32_e32 v19, 0x37800000, v16
	v_cndmask_b32_e32 v16, v16, v19, vcc
	v_cmp_class_f32_e32 vcc, v21, v62
	v_add_f32_e32 v7, 1.0, v7
	v_add_f32_e32 v5, v5, v0
	v_cndmask_b32_e32 v16, v16, v21, vcc
	v_mul_f32_e32 v16, v17, v16
	v_div_scale_f32 v17, s[0:1], v15, v15, 1.0
	v_rcp_f32_e32 v19, v17
	v_mul_f32_e32 v24, v67, v16
	v_fma_f32 v16, v27, v18, v24
	v_mul_f32_e32 v18, v27, v20
	v_fma_f32 v20, -v17, v19, 1.0
	v_fmac_f32_e32 v19, v20, v19
	v_div_scale_f32 v20, vcc, 1.0, v15, 1.0
	v_mul_f32_e32 v21, v20, v19
	v_fma_f32 v22, -v17, v21, v20
	v_fmac_f32_e32 v21, v22, v19
	v_fma_f32 v17, -v17, v21, v20
	v_div_fmas_f32 v17, v17, v19, v21
	v_max_f32_e32 v19, v84, v84
	v_max_f32_e32 v19, 0, v19
	v_mul_f32_e32 v20, 0x4f800000, v19
	v_cmp_gt_f32_e32 vcc, s4, v19
	v_div_fixup_f32 v15, v17, v15, 1.0
	v_exp_f32_e32 v21, v10
	v_cndmask_b32_e32 v19, v19, v20, vcc
	v_sqrt_f32_e32 v20, v19
	v_mul_f32_e32 v5, 0xbfb8aa3b, v5
	v_exp_f32_e32 v5, v5
	v_mul_f32_e32 v4, 0x3fb8aa3b, v4
	v_add_u32_e32 v14, -1, v20
	v_fma_f32 v17, -v14, v20, v19
	v_cmp_ge_f32_e64 s[0:1], 0, v17
	v_add_u32_e32 v17, 1, v20
	v_add_f32_e32 v5, 1.0, v5
	v_cndmask_b32_e64 v14, v20, v14, s[0:1]
	v_fma_f32 v20, -v17, v20, v19
	v_cmp_lt_f32_e64 s[0:1], 0, v20
	v_add_f32_e32 v0, v3, v0
; DI float sigmoidf_(float x) { return 1.f / (1.f + __expf(-x)); }
;     ...
;   for (int i = 0; i < 16; ++i) {
;     const float rr = sigmoidf_(aA[i] + ba), ig = sigmoidf_(aX[i] + bx);
;     const float la = -8.f * rr * sp;
;     const float a = __expf(la);
;     const float x2 = 2.f * la;
;     const float em = (x2 > -0.1f) ? -x2 * (1.f + x2 * (0.5f + x2 * (0.16666667f + x2 * 0.041666667f))) : 1.f - __expf(x2);
;     const float bb = sqrtf(fmaxf(em, 0.f)) * ig * xc[i];
;     aA[i] = a; aX[i] = bb;
;     H = a * H + bb;
;     P *= a;
;   }
	v_mul_f32_e32 v0, 0xbfb8aa3b, v0
	v_cndmask_b32_e64 v14, v14, v17, s[0:1]
	v_mul_f32_e32 v17, 0x37800000, v14
	v_cndmask_b32_e32 v14, v14, v17, vcc
	v_cmp_class_f32_e32 vcc, v19, v62
	v_exp_f32_e32 v0, v0
	v_mul_f32_e32 v2, 0x3fb8aa3b, v2
	v_cndmask_b32_e32 v14, v14, v19, vcc
	v_mul_f32_e32 v14, v15, v14
	v_div_scale_f32 v15, s[0:1], v13, v13, 1.0
	v_rcp_f32_e32 v17, v15
	v_mul_f32_e32 v22, v56, v14
	v_fma_f32 v14, v25, v16, v22
	v_mul_f32_e32 v16, v25, v18
	v_fma_f32 v18, -v15, v17, 1.0
	v_fmac_f32_e32 v17, v18, v17
	v_div_scale_f32 v18, vcc, 1.0, v13, 1.0
	v_mul_f32_e32 v19, v18, v17
	v_fma_f32 v20, -v15, v19, v18
	v_fmac_f32_e32 v19, v20, v17
	v_fma_f32 v15, -v15, v19, v18
	v_div_fmas_f32 v15, v15, v17, v19
	v_max_f32_e32 v17, v86, v86
	v_max_f32_e32 v17, 0, v17
	v_mul_f32_e32 v18, 0x4f800000, v17
	v_cmp_gt_f32_e32 vcc, s4, v17
	v_div_fixup_f32 v13, v15, v13, 1.0
	v_exp_f32_e32 v19, v8
	v_cndmask_b32_e32 v17, v17, v18, vcc
	v_sqrt_f32_e32 v18, v17
	v_add_f32_e32 v0, 1.0, v0
	v_add_u32_e32 v12, -1, v18
	v_fma_f32 v15, -v12, v18, v17
	v_cmp_ge_f32_e64 s[0:1], 0, v15
	v_add_u32_e32 v15, 1, v18
	s_nop 0
	v_cndmask_b32_e64 v12, v18, v12, s[0:1]
	v_fma_f32 v18, -v15, v18, v17
	v_cmp_lt_f32_e64 s[0:1], 0, v18
	s_nop 1
	v_cndmask_b32_e64 v12, v12, v15, s[0:1]
	v_mul_f32_e32 v15, 0x37800000, v12
	v_cndmask_b32_e32 v12, v12, v15, vcc
	v_cmp_class_f32_e32 vcc, v17, v62
	s_nop 1
	v_cndmask_b32_e32 v12, v12, v17, vcc
	v_mul_f32_e32 v12, v13, v12
	v_div_scale_f32 v13, s[0:1], v11, v11, 1.0
	v_rcp_f32_e32 v15, v13
	v_mul_f32_e32 v20, v55, v12
	v_fma_f32 v12, v23, v14, v20
	v_mul_f32_e32 v14, v23, v16
	v_fma_f32 v16, -v13, v15, 1.0
	v_fmac_f32_e32 v15, v16, v15
	v_div_scale_f32 v16, vcc, 1.0, v11, 1.0
	v_mul_f32_e32 v17, v16, v15
	v_fma_f32 v18, -v13, v17, v16
	v_fmac_f32_e32 v17, v18, v15
	v_fma_f32 v13, -v13, v17, v16
	v_div_fmas_f32 v13, v13, v15, v17
	v_max_f32_e32 v15, v87, v87
	v_max_f32_e32 v15, 0, v15
	v_mul_f32_e32 v16, 0x4f800000, v15
	v_cmp_gt_f32_e32 vcc, s4, v15
	v_div_fixup_f32 v11, v13, v11, 1.0
	v_exp_f32_e32 v17, v6
	v_cndmask_b32_e32 v15, v15, v16, vcc
	v_sqrt_f32_e32 v16, v15
	s_nop 0
	v_add_u32_e32 v10, -1, v16
	v_fma_f32 v13, -v10, v16, v15
	v_cmp_ge_f32_e64 s[0:1], 0, v13
	v_add_u32_e32 v13, 1, v16
	s_nop 0
	v_cndmask_b32_e64 v10, v16, v10, s[0:1]
	v_fma_f32 v16, -v13, v16, v15
	v_cmp_lt_f32_e64 s[0:1], 0, v16
	s_nop 1
	v_cndmask_b32_e64 v10, v10, v13, s[0:1]
	v_mul_f32_e32 v13, 0x37800000, v10
	v_cndmask_b32_e32 v10, v10, v13, vcc
	v_cmp_class_f32_e32 vcc, v15, v62
	s_nop 1
	v_cndmask_b32_e32 v10, v10, v15, vcc
	v_mul_f32_e32 v10, v11, v10
	v_div_scale_f32 v11, s[0:1], v9, v9, 1.0
	v_rcp_f32_e32 v13, v11
	v_mul_f32_e32 v18, v54, v10
	v_fma_f32 v10, v21, v12, v18
	v_mul_f32_e32 v12, v21, v14
	v_fma_f32 v14, -v11, v13, 1.0
	v_fmac_f32_e32 v13, v14, v13
	v_div_scale_f32 v14, vcc, 1.0, v9, 1.0
	v_mul_f32_e32 v15, v14, v13
	v_fma_f32 v16, -v11, v15, v14
	v_fmac_f32_e32 v15, v16, v13
	v_fma_f32 v11, -v11, v15, v14
	v_div_fmas_f32 v11, v11, v13, v15
	v_max_f32_e32 v13, v88, v88
	v_max_f32_e32 v13, 0, v13
	v_mul_f32_e32 v14, 0x4f800000, v13
	v_cmp_gt_f32_e32 vcc, s4, v13
	v_div_fixup_f32 v9, v11, v9, 1.0
	v_exp_f32_e32 v15, v4
	v_cndmask_b32_e32 v13, v13, v14, vcc
	v_sqrt_f32_e32 v14, v13
	s_nop 0
	v_add_u32_e32 v8, -1, v14
	v_fma_f32 v11, -v8, v14, v13
	v_cmp_ge_f32_e64 s[0:1], 0, v11
	v_add_u32_e32 v11, 1, v14
	s_nop 0
	v_cndmask_b32_e64 v8, v14, v8, s[0:1]
	v_fma_f32 v14, -v11, v14, v13
	v_cmp_lt_f32_e64 s[0:1], 0, v14
	s_nop 1
	v_cndmask_b32_e64 v8, v8, v11, s[0:1]
	v_mul_f32_e32 v11, 0x37800000, v8
	v_cndmask_b32_e32 v8, v8, v11, vcc
	v_cmp_class_f32_e32 vcc, v13, v62
	s_nop 1
	v_cndmask_b32_e32 v8, v8, v13, vcc
	v_mul_f32_e32 v8, v9, v8
	v_div_scale_f32 v9, s[0:1], v7, v7, 1.0
	v_rcp_f32_e32 v11, v9
	v_mul_f32_e32 v16, v53, v8
	v_fma_f32 v8, v19, v10, v16
	v_mul_f32_e32 v10, v19, v12
	v_fma_f32 v12, -v9, v11, 1.0
	v_fmac_f32_e32 v11, v12, v11
	v_div_scale_f32 v12, vcc, 1.0, v7, 1.0
;     ...
;     const float bb = sqrtf(fmaxf(em, 0.f)) * ig * xc[i];
;     aA[i] = a; aX[i] = bb;
;     H = a * H + bb;
;     P *= a;
;   }
;   segP[tq * 64 + ch] = P;
;   segH[tq * 64 + ch] = H;
;   __syncthreads();
;   if (pass == 1) {
;     if (tq == 3) {
;       float Pt = 1.f, Ht = 0.f;
; #pragma unroll
;       for (int s = 0; s < 4; ++s) { Ht = segP[s * 64 + ch] * Ht + segH[s * 64 + ch]; Pt *= segP[s * 64 + ch]; }
;       float2 o; o.x = Pt; o.y = Ht;
;       *(float2*)(p.lrusum + ((size_t)(b * 64 + chunk) * 512 + chg) * 2) = o;
;     }
;   } else {
;     {
;       const int lo = (chunk * tq) >> 2, hi = (chunk * (tq + 1)) >> 2;
;       float cA = 1.f, cB = 0.f;
; #pragma unroll 4
;       for (int c = lo; c < hi; ++c) {
;         const float2 sm = *(const float2*)(p.lrusum + ((size_t)(b * 64 + c) * 512 + chg) * 2);
;         cB = sm.x * cB + sm.y;
;         cA *= sm.x;
;       }
;       carA[tq * 64 + ch] = cA;
	v_mul_f32_e32 v13, v12, v11
	v_fma_f32 v14, -v9, v13, v12
	v_fmac_f32_e32 v13, v14, v11
	v_fma_f32 v9, -v9, v13, v12
	v_div_fmas_f32 v9, v9, v11, v13
	v_max_f32_e32 v11, v89, v89
	v_max_f32_e32 v11, 0, v11
	v_mul_f32_e32 v12, 0x4f800000, v11
	v_cmp_gt_f32_e32 vcc, s4, v11
	v_div_fixup_f32 v7, v9, v7, 1.0
	v_exp_f32_e32 v13, v2
	v_cndmask_b32_e32 v11, v11, v12, vcc
	v_sqrt_f32_e32 v12, v11
	s_nop 0
	v_add_u32_e32 v6, -1, v12
	v_fma_f32 v9, -v6, v12, v11
	v_cmp_ge_f32_e64 s[0:1], 0, v9
	v_add_u32_e32 v9, 1, v12
	s_nop 0
	v_cndmask_b32_e64 v6, v12, v6, s[0:1]
	v_fma_f32 v12, -v9, v12, v11
	v_cmp_lt_f32_e64 s[0:1], 0, v12
	s_nop 1
	v_cndmask_b32_e64 v6, v6, v9, s[0:1]
	v_mul_f32_e32 v9, 0x37800000, v6
	v_cndmask_b32_e32 v6, v6, v9, vcc
	v_cmp_class_f32_e32 vcc, v11, v62
	s_nop 1
	v_cndmask_b32_e32 v6, v6, v11, vcc
	v_mul_f32_e32 v6, v7, v6
	v_div_scale_f32 v7, s[0:1], v5, v5, 1.0
	v_rcp_f32_e32 v9, v7
	v_mul_f32_e32 v14, v52, v6
	v_fma_f32 v6, v17, v8, v14
	v_mul_f32_e32 v8, v17, v10
	v_fma_f32 v10, -v7, v9, 1.0
	v_fmac_f32_e32 v9, v10, v9
	v_div_scale_f32 v10, vcc, 1.0, v5, 1.0
	v_mul_f32_e32 v11, v10, v9
	v_fma_f32 v12, -v7, v11, v10
	v_fmac_f32_e32 v11, v12, v9
	v_fma_f32 v7, -v7, v11, v10
	v_div_fmas_f32 v7, v7, v9, v11
	v_max_f32_e32 v9, v90, v90
	v_max_f32_e32 v9, 0, v9
	v_mul_f32_e32 v10, 0x4f800000, v9
	v_cmp_gt_f32_e32 vcc, s4, v9
	v_div_fixup_f32 v5, v7, v5, 1.0
	s_nop 0
	v_cndmask_b32_e32 v9, v9, v10, vcc
	v_sqrt_f32_e32 v10, v9
	s_nop 0
	v_add_u32_e32 v4, -1, v10
	v_fma_f32 v7, -v4, v10, v9
	v_cmp_ge_f32_e64 s[0:1], 0, v7
	v_add_u32_e32 v7, 1, v10
	s_nop 0
	v_cndmask_b32_e64 v4, v10, v4, s[0:1]
	v_fma_f32 v10, -v7, v10, v9
	v_cmp_lt_f32_e64 s[0:1], 0, v10
	s_nop 1
	v_cndmask_b32_e64 v4, v4, v7, s[0:1]
	v_mul_f32_e32 v7, 0x37800000, v4
	v_cndmask_b32_e32 v4, v4, v7, vcc
	v_cmp_class_f32_e32 vcc, v9, v62
	s_nop 1
	v_cndmask_b32_e32 v3, v4, v9, vcc
	v_div_scale_f32 v4, s[0:1], v0, v0, 1.0
	v_mul_f32_e32 v3, v5, v3
	v_rcp_f32_e32 v5, v4
	v_mul_f32_e32 v12, v51, v3
	v_fma_f32 v3, v15, v6, v12
	v_mul_f32_e32 v6, v15, v8
	v_fma_f32 v7, -v4, v5, 1.0
	v_fmac_f32_e32 v5, v7, v5
	v_div_scale_f32 v7, vcc, 1.0, v0, 1.0
	v_mul_f32_e32 v8, v7, v5
	v_fma_f32 v9, -v4, v8, v7
	v_fmac_f32_e32 v8, v9, v5
	v_fma_f32 v4, -v4, v8, v7
	v_div_fmas_f32 v4, v4, v5, v8
	v_max_f32_e32 v5, v75, v75
	v_max_f32_e32 v5, 0, v5
	v_mul_f32_e32 v7, 0x4f800000, v5
	v_cmp_gt_f32_e32 vcc, s4, v5
	v_div_fixup_f32 v0, v4, v0, 1.0
	v_mov_b32_e32 v51, 1.0
	v_cndmask_b32_e32 v5, v5, v7, vcc
	v_sqrt_f32_e32 v7, v5
	s_nop 0
	v_add_u32_e32 v2, -1, v7
	v_fma_f32 v4, -v2, v7, v5
	v_cmp_ge_f32_e64 s[0:1], 0, v4
	v_add_u32_e32 v4, 1, v7
	s_nop 0
	v_cndmask_b32_e64 v2, v7, v2, s[0:1]
	v_fma_f32 v7, -v4, v7, v5
	v_cmp_lt_f32_e64 s[0:1], 0, v7
	s_nop 1
	v_cndmask_b32_e64 v2, v2, v4, s[0:1]
	v_mul_f32_e32 v4, 0x37800000, v2
	v_cndmask_b32_e32 v2, v2, v4, vcc
	v_cmp_class_f32_e32 vcc, v5, v62
	s_nop 1
	v_cndmask_b32_e32 v2, v2, v5, vcc
	v_mul_f32_e32 v0, v0, v2
	v_mul_f32_e32 v0, v50, v0
	v_fma_f32 v2, v13, v3, v0
	v_mul_f32_e32 v3, v13, v6
	ds_write2st64_b32 v35, v3, v2 offset0:236 offset1:240
	v_mul_lo_u32 v2, v41, s3
	v_ashrrev_i32_e32 v6, 2, v2
	v_add_u32_e32 v2, s3, v2
	v_ashrrev_i32_e32 v50, 2, v2
	v_cmp_lt_i32_e32 vcc, v6, v50
	v_mov_b32_e32 v3, 0
	s_waitcnt lgkmcnt(0)
	s_barrier
	s_and_saveexec_b64 s[0:1], vcc
	s_cbranch_execz .LBB0_994
	v_sub_u32_e32 v2, v50, v6
	v_and_b32_e32 v7, 3, v2
	s_lshl_b32 s3, s2, 6
	v_lshlrev_b32_e32 v10, 3, v37
	v_cmp_ne_u32_e32 vcc, 0, v7
	v_mov_b32_e32 v3, 0
	v_mov_b32_e32 v51, 1.0
	v_mov_b32_e32 v37, v6
	s_and_saveexec_b64 s[4:5], vcc
	s_cbranch_execz .LBB0_989
	v_add_u32_e32 v2, s3, v6
	v_ashrrev_i32_e32 v3, 31, v2
	v_lshlrev_b64 v[2:3], 12, v[2:3]
	v_readlane_b32 s6, v253, 34
	v_or_b32_e32 v2, v2, v10
	v_readlane_b32 s7, v253, 35
	v_add_u32_e32 v37, v6, v7
	v_mov_b32_e32 v51, 1.0
	v_lshl_add_u64 v[4:5], s[6:7], 0, v[2:3]
	v_mov_b32_e32 v3, 0
	s_mov_b64 s[6:7], 0
	v_mov_b32_e32 v8, v7
